# v96 + GEMM main loops: loop-counter / pointer-advance SALU moved in front of the loop-back s_barrier
# baseline (speedup 1.0000x reference)
; #define PG8_STAGE(bufoff, gbase, voff) do { _Pragma("unroll") for (int _i = 0; _i < 2; ++_i) \
;         __builtin_amdgcn_global_load_lds((const unsigned*)((const char*)(gbase) + (voff)[_i]), (LAS unsigned*)(lds + (bufoff) + ldsw + _i * 8192), 16, 0, 0); } while (0)
; #define PG8_LDA(dst, b, h) do { _Pragma("unroll") for (int m = 0; m < 4; ++m) _Pragma("unroll") for (int k = 0; k < 2; ++k) dst[m][k] = *(const LAS bf16x8*)(lds + PG8_SA(b, h) + aoff + m * 2048 + k * 1024); } while (0)
; #define PG8_LDB(dst, b, h) do { _Pragma("unroll") for (int n = 0; n < 2; ++n) _Pragma("unroll") for (int k = 0; k < 2; ++k) dst[n][k] = *(const LAS bf16x8*)(lds + PG8_SB(b, h) + boff + n * 2048 + k * 1024); } while (0)
; #define PG8_MMA(ai, bj, At, Bt) do { __builtin_amdgcn_s_setprio(1); _Pragma("unroll") for (int m = 0; m < 4; ++m) _Pragma("unroll") for (int n = 0; n < 2; ++n) _Pragma("unroll") for (int k = 0; k < 2; ++k) \
;         acc[ai][bj][m][n] = __builtin_amdgcn_mfma_f32_16x16x32_bf16(Bt[n][k], At[m][k], acc[ai][bj][m][n], 0, 0, 0); __builtin_amdgcn_s_setprio(0); } while (0)
; #define PG8_WAIT_V(n) asm volatile("s_waitcnt vmcnt(" #n ")" ::: "memory")
; #define PG8_WAIT_L(n) asm volatile("s_waitcnt lgkmcnt(" #n ")" ::: "memory")
; #define PG8_BAR __builtin_amdgcn_s_barrier()
; #define PG8_SCHED __builtin_amdgcn_sched_barrier(0)
; template <class Epi, class Sched, bool ALIGN_EPI = true, bool SP2 = true>
; DI void gemm_phase(LAS unsigned char* lds, const Gemm g, const Sched& S, const Epi& E) {
;     ...
;         for (int t = 0; t < nt; t += 2) {
;             const bool last = (t == nt - 2);
;             const char* a1 = cA + (size_t)(t + 1) * kstep;
;             const char* a2 = last ? nA : cA + (size_t)(t + 2) * kstep; const char* b2 = last ? nB : cB + (size_t)(t + 2) * kstep;
;             const char* a3 = a2 + kstep; const char* b3 = b2 + kstep;
;             PG8_LDB(B0, 0, 0); PG8_LDB(B1, 0, 1); PG8_SCHED; PG8_LDA(At, 0, 0); PG8_STAGE(PG8_SA(1, 1), a1 + hstepA, voffA);
;             PG8_WAIT_V(8); PG8_WAIT_L(0); PG8_BAR; PG8_MMA(0, 0, At, B0); PG8_MMA(0, 1, At, B1); PG8_BAR; PG8_SCHED;
;             PG8_LDA(At, 0, 1); PG8_STAGE(PG8_SB(0, 0), b2, voffB); PG8_STAGE(PG8_SB(0, 1), b2 + hstepB, voffB); PG8_STAGE(PG8_SA(0, 0), a2, voffA);
.LBB0_179:
	ds_read_b128 v[146:149], v156
	ds_read_b128 v[160:163], v156 offset:1024
	ds_read_b128 v[164:167], v156 offset:2048
	ds_read_b128 v[168:171], v156 offset:3072
	ds_read_b128 v[172:175], v157
	ds_read_b128 v[176:179], v157 offset:1024
	ds_read_b128 v[180:183], v157 offset:2048
	ds_read_b128 v[184:187], v157 offset:3072
	s_add_u32 s56, s54, 0xfffc0080
	s_addc_u32 s57, s55, -1
	s_cmp_eq_u32 s97, 12
	s_cselect_b32 s59, s35, s57
	s_cselect_b32 s58, s45, s56
	s_cselect_b32 s57, s19, s96
	s_cselect_b32 s56, s49, s95
	v_lshl_add_u64 v[150:151], s[54:55], 0, v[138:139]
	s_add_i32 m0, s60, 0xc000
	ds_read_b128 v[188:191], v158
	ds_read_b128 v[192:195], v158 offset:1024
	ds_read_b128 v[196:199], v158 offset:2048
	ds_read_b128 v[200:203], v158 offset:3072
	ds_read_b128 v[204:207], v158 offset:4096
	ds_read_b128 v[208:211], v158 offset:5120
	ds_read_b128 v[212:215], v158 offset:6144
	ds_read_b128 v[216:219], v158 offset:7168
	global_load_lds_dwordx4 v[150:151], off
	v_lshl_add_u64 v[150:151], s[54:55], 0, v[140:141]
	s_add_i32 m0, s60, 0xe000
	s_nop 0
	global_load_lds_dwordx4 v[150:151], off
	s_waitcnt vmcnt(8)
	s_waitcnt lgkmcnt(0)
	s_barrier
	s_setprio 1
	s_waitcnt lgkmcnt(0)
	v_mfma_f32_16x16x32_bf16 v[124:127], v[146:149], v[188:191], v[124:127]
	v_mfma_f32_16x16x32_bf16 v[120:123], v[164:167], v[188:191], v[120:123]
	v_mfma_f32_16x16x32_bf16 v[108:111], v[146:149], v[196:199], v[108:111]
	v_mfma_f32_16x16x32_bf16 v[104:107], v[164:167], v[196:199], v[104:107]
	v_mfma_f32_16x16x32_bf16 v[92:95], v[146:149], v[204:207], v[92:95]
	v_mfma_f32_16x16x32_bf16 v[88:91], v[164:167], v[204:207], v[88:91]
	v_mfma_f32_16x16x32_bf16 v[76:79], v[146:149], v[212:215], v[76:79]
	v_mfma_f32_16x16x32_bf16 v[72:75], v[164:167], v[212:215], v[72:75]
	v_mfma_f32_16x16x32_bf16 v[124:127], v[160:163], v[192:195], v[124:127]
	v_mfma_f32_16x16x32_bf16 v[120:123], v[168:171], v[192:195], v[120:123]
	v_mfma_f32_16x16x32_bf16 v[108:111], v[160:163], v[200:203], v[108:111]
	v_mfma_f32_16x16x32_bf16 v[104:107], v[168:171], v[200:203], v[104:107]
	v_mfma_f32_16x16x32_bf16 v[92:95], v[160:163], v[208:211], v[92:95]
	v_mfma_f32_16x16x32_bf16 v[88:91], v[168:171], v[208:211], v[88:91]
	v_mfma_f32_16x16x32_bf16 v[76:79], v[160:163], v[216:219], v[76:79]
	v_mfma_f32_16x16x32_bf16 v[72:75], v[168:171], v[216:219], v[72:75]
	s_setprio 0
	s_setprio 1
	v_mfma_f32_16x16x32_bf16 v[112:115], v[172:175], v[188:191], v[112:115]
	v_mfma_f32_16x16x32_bf16 v[116:119], v[180:183], v[188:191], v[116:119]
	v_mfma_f32_16x16x32_bf16 v[96:99], v[172:175], v[196:199], v[96:99]
	v_mfma_f32_16x16x32_bf16 v[100:103], v[180:183], v[196:199], v[100:103]
	v_mfma_f32_16x16x32_bf16 v[80:83], v[172:175], v[204:207], v[80:83]
	v_mfma_f32_16x16x32_bf16 v[84:87], v[180:183], v[204:207], v[84:87]
	v_mfma_f32_16x16x32_bf16 v[64:67], v[172:175], v[212:215], v[64:67]
	v_mfma_f32_16x16x32_bf16 v[68:71], v[180:183], v[212:215], v[68:71]
	v_mfma_f32_16x16x32_bf16 v[112:115], v[176:179], v[192:195], v[112:115]
	v_mfma_f32_16x16x32_bf16 v[116:119], v[184:187], v[192:195], v[116:119]
	v_mfma_f32_16x16x32_bf16 v[96:99], v[176:179], v[200:203], v[96:99]
	v_mfma_f32_16x16x32_bf16 v[100:103], v[184:187], v[200:203], v[100:103]
	v_mfma_f32_16x16x32_bf16 v[80:83], v[176:179], v[208:211], v[80:83]
	v_mfma_f32_16x16x32_bf16 v[84:87], v[184:187], v[208:211], v[84:87]
	v_mfma_f32_16x16x32_bf16 v[64:67], v[176:179], v[216:219], v[64:67]
	v_mfma_f32_16x16x32_bf16 v[68:71], v[184:187], v[216:219], v[68:71]
	s_setprio 0
	s_barrier
	s_add_i32 vcc_lo, s87, s3
	v_lshl_add_u64 v[150:151], s[56:57], 0, v[130:131]
	s_mov_b32 m0, vcc_lo
	ds_read_b128 v[188:191], v158 offset:16384
	ds_read_b128 v[192:195], v158 offset:17408
	ds_read_b128 v[196:199], v158 offset:18432
	ds_read_b128 v[200:203], v158 offset:19456
	ds_read_b128 v[204:207], v158 offset:20480
	ds_read_b128 v[208:211], v158 offset:21504
	ds_read_b128 v[212:215], v158 offset:22528
	ds_read_b128 v[216:219], v158 offset:23552
	global_load_lds_dwordx4 v[150:151], off
	s_add_i32 m0, vcc_lo, 0x2000
	s_add_u32 vcc_lo, s56, 0x40000
	v_lshl_add_u64 v[220:221], s[56:57], 0, v[134:135]
	s_addc_u32 vcc_hi, s57, 0
	s_add_i32 s91, s88, s3
	global_load_lds_dwordx4 v[220:221], off
	v_lshl_add_u64 v[222:223], vcc, 0, v[130:131]
	s_mov_b32 m0, s91
	v_lshl_add_u64 v[224:225], s[58:59], 0, v[132:133]
	global_load_lds_dwordx4 v[222:223], off
	v_lshl_add_u64 v[222:223], vcc, 0, v[134:135]
	s_add_i32 m0, s91, 0x2000
	s_nop 0
	global_load_lds_dwordx4 v[222:223], off
	v_lshl_add_u64 v[222:223], s[58:59], 0, v[128:129]
	s_mov_b32 m0, s60
	s_nop 0
	global_load_lds_dwordx4 v[222:223], off
	s_mov_b32 m0, s61
	s_nop 0
	global_load_lds_dwordx4 v[224:225], off
	s_waitcnt vmcnt(8)
	s_waitcnt lgkmcnt(0)
	s_barrier
; #define PG8_STAGE(bufoff, gbase, voff) do { _Pragma("unroll") for (int _i = 0; _i < 2; ++_i) \
;         __builtin_amdgcn_global_load_lds((const unsigned*)((const char*)(gbase) + (voff)[_i]), (LAS unsigned*)(lds + (bufoff) + ldsw + _i * 8192), 16, 0, 0); } while (0)
; #define PG8_LDA(dst, b, h) do { _Pragma("unroll") for (int m = 0; m < 4; ++m) _Pragma("unroll") for (int k = 0; k < 2; ++k) dst[m][k] = *(const LAS bf16x8*)(lds + PG8_SA(b, h) + aoff + m * 2048 + k * 1024); } while (0)
; #define PG8_LDB(dst, b, h) do { _Pragma("unroll") for (int n = 0; n < 2; ++n) _Pragma("unroll") for (int k = 0; k < 2; ++k) dst[n][k] = *(const LAS bf16x8*)(lds + PG8_SB(b, h) + boff + n * 2048 + k * 1024); } while (0)
; #define PG8_MMA(ai, bj, At, Bt) do { __builtin_amdgcn_s_setprio(1); _Pragma("unroll") for (int m = 0; m < 4; ++m) _Pragma("unroll") for (int n = 0; n < 2; ++n) _Pragma("unroll") for (int k = 0; k < 2; ++k) \
;         acc[ai][bj][m][n] = __builtin_amdgcn_mfma_f32_16x16x32_bf16(Bt[n][k], At[m][k], acc[ai][bj][m][n], 0, 0, 0); __builtin_amdgcn_s_setprio(0); } while (0)
; #define PG8_WAIT_V(n) asm volatile("s_waitcnt vmcnt(" #n ")" ::: "memory")
; #define PG8_WAIT_L(n) asm volatile("s_waitcnt lgkmcnt(" #n ")" ::: "memory")
; #define PG8_BAR __builtin_amdgcn_s_barrier()
; #define PG8_SCHED __builtin_amdgcn_sched_barrier(0)
; template <class Epi, class Sched, bool ALIGN_EPI = true, bool SP2 = true>
; DI void gemm_phase(LAS unsigned char* lds, const Gemm g, const Sched& S, const Epi& E) {
;     ...
;             PG8_WAIT_V(8); PG8_WAIT_L(0); PG8_BAR; PG8_MMA(1, 0, At, B0); PG8_MMA(1, 1, At, B1); PG8_BAR; PG8_SCHED;
;             PG8_LDB(B0, 1, 0); PG8_LDB(B1, 1, 1); PG8_SCHED; PG8_LDA(At, 1, 0); PG8_STAGE(PG8_SA(0, 1), a2 + hstepA, voffA);
;             PG8_WAIT_V(8); PG8_WAIT_L(0); PG8_BAR; PG8_MMA(0, 0, At, B0); PG8_MMA(0, 1, At, B1); PG8_BAR; PG8_SCHED;
	s_setprio 1
	s_waitcnt lgkmcnt(0)
	v_mfma_f32_16x16x32_bf16 v[60:63], v[146:149], v[188:191], v[60:63]
	v_mfma_f32_16x16x32_bf16 v[56:59], v[164:167], v[188:191], v[56:59]
	v_mfma_f32_16x16x32_bf16 v[44:47], v[146:149], v[196:199], v[44:47]
	v_mfma_f32_16x16x32_bf16 v[40:43], v[164:167], v[196:199], v[40:43]
	v_mfma_f32_16x16x32_bf16 v[28:31], v[146:149], v[204:207], v[28:31]
	v_mfma_f32_16x16x32_bf16 v[24:27], v[164:167], v[204:207], v[24:27]
	v_mfma_f32_16x16x32_bf16 v[12:15], v[146:149], v[212:215], v[12:15]
	v_mfma_f32_16x16x32_bf16 v[8:11], v[164:167], v[212:215], v[8:11]
	v_mfma_f32_16x16x32_bf16 v[60:63], v[160:163], v[192:195], v[60:63]
	v_mfma_f32_16x16x32_bf16 v[56:59], v[168:171], v[192:195], v[56:59]
	v_mfma_f32_16x16x32_bf16 v[44:47], v[160:163], v[200:203], v[44:47]
	v_mfma_f32_16x16x32_bf16 v[40:43], v[168:171], v[200:203], v[40:43]
	v_mfma_f32_16x16x32_bf16 v[28:31], v[160:163], v[208:211], v[28:31]
	v_mfma_f32_16x16x32_bf16 v[24:27], v[168:171], v[208:211], v[24:27]
	v_mfma_f32_16x16x32_bf16 v[12:15], v[160:163], v[216:219], v[12:15]
	v_mfma_f32_16x16x32_bf16 v[8:11], v[168:171], v[216:219], v[8:11]
	s_setprio 0
	s_setprio 1
	v_mfma_f32_16x16x32_bf16 v[48:51], v[172:175], v[188:191], v[48:51]
	v_mfma_f32_16x16x32_bf16 v[52:55], v[180:183], v[188:191], v[52:55]
	v_mfma_f32_16x16x32_bf16 v[32:35], v[172:175], v[196:199], v[32:35]
	v_mfma_f32_16x16x32_bf16 v[36:39], v[180:183], v[196:199], v[36:39]
	v_mfma_f32_16x16x32_bf16 v[16:19], v[172:175], v[204:207], v[16:19]
	v_mfma_f32_16x16x32_bf16 v[20:23], v[180:183], v[204:207], v[20:23]
	v_mfma_f32_16x16x32_bf16 v[4:7], v[172:175], v[212:215], v[4:7]
	v_mfma_f32_16x16x32_bf16 v[0:3], v[180:183], v[212:215], v[0:3]
	v_mfma_f32_16x16x32_bf16 v[48:51], v[176:179], v[192:195], v[48:51]
	v_mfma_f32_16x16x32_bf16 v[52:55], v[184:187], v[192:195], v[52:55]
	v_mfma_f32_16x16x32_bf16 v[32:35], v[176:179], v[200:203], v[32:35]
	v_mfma_f32_16x16x32_bf16 v[36:39], v[184:187], v[200:203], v[36:39]
	v_mfma_f32_16x16x32_bf16 v[16:19], v[176:179], v[208:211], v[16:19]
	v_mfma_f32_16x16x32_bf16 v[20:23], v[184:187], v[208:211], v[20:23]
	v_mfma_f32_16x16x32_bf16 v[4:7], v[176:179], v[216:219], v[4:7]
	v_mfma_f32_16x16x32_bf16 v[0:3], v[184:187], v[216:219], v[0:3]
	s_setprio 0
	s_barrier
	s_add_i32 s91, 0, 0x18000
	v_add_u32_e32 v136, s91, v153
	s_add_i32 vcc_lo, 0, 0x1c000
	ds_read_b128 v[146:149], v136
	ds_read_b128 v[160:163], v136 offset:1024
	ds_read_b128 v[164:167], v136 offset:2048
	ds_read_b128 v[168:171], v136 offset:3072
	v_add_u32_e32 v136, vcc_lo, v153
	ds_read_b128 v[172:175], v136
	ds_read_b128 v[176:179], v136 offset:1024
	ds_read_b128 v[180:183], v136 offset:2048
	ds_read_b128 v[184:187], v136 offset:3072
	s_add_u32 s58, s58, 0x40000
	s_addc_u32 s59, s59, 0
	s_mov_b32 m0, s66
	v_lshl_add_u64 v[228:229], s[58:59], 0, v[128:129]
	ds_read_b128 v[188:191], v158 offset:32768
	ds_read_b128 v[192:195], v158 offset:33792
	ds_read_b128 v[196:199], v158 offset:34816
	ds_read_b128 v[200:203], v158 offset:35840
	ds_read_b128 v[204:207], v158 offset:36864
	ds_read_b128 v[208:211], v158 offset:37888
	ds_read_b128 v[212:215], v158 offset:38912
	ds_read_b128 v[216:219], v158 offset:39936
	global_load_lds_dwordx4 v[228:229], off
	v_lshl_add_u64 v[228:229], s[58:59], 0, v[132:133]
	s_mov_b32 m0, s67
	s_nop 0
	global_load_lds_dwordx4 v[228:229], off
	s_waitcnt vmcnt(8)
	s_waitcnt lgkmcnt(0)
	s_barrier
	s_setprio 1
	s_waitcnt lgkmcnt(0)
	v_mfma_f32_16x16x32_bf16 v[124:127], v[146:149], v[188:191], v[124:127]
	v_mfma_f32_16x16x32_bf16 v[120:123], v[164:167], v[188:191], v[120:123]
	v_mfma_f32_16x16x32_bf16 v[108:111], v[146:149], v[196:199], v[108:111]
	v_mfma_f32_16x16x32_bf16 v[104:107], v[164:167], v[196:199], v[104:107]
	v_mfma_f32_16x16x32_bf16 v[92:95], v[146:149], v[204:207], v[92:95]
	v_mfma_f32_16x16x32_bf16 v[88:91], v[164:167], v[204:207], v[88:91]
	v_mfma_f32_16x16x32_bf16 v[76:79], v[146:149], v[212:215], v[76:79]
	v_mfma_f32_16x16x32_bf16 v[72:75], v[164:167], v[212:215], v[72:75]
	v_mfma_f32_16x16x32_bf16 v[124:127], v[160:163], v[192:195], v[124:127]
	v_mfma_f32_16x16x32_bf16 v[120:123], v[168:171], v[192:195], v[120:123]
	v_mfma_f32_16x16x32_bf16 v[108:111], v[160:163], v[200:203], v[108:111]
	v_mfma_f32_16x16x32_bf16 v[104:107], v[168:171], v[200:203], v[104:107]
	v_mfma_f32_16x16x32_bf16 v[92:95], v[160:163], v[208:211], v[92:95]
	v_mfma_f32_16x16x32_bf16 v[88:91], v[168:171], v[208:211], v[88:91]
	v_mfma_f32_16x16x32_bf16 v[76:79], v[160:163], v[216:219], v[76:79]
	v_mfma_f32_16x16x32_bf16 v[72:75], v[168:171], v[216:219], v[72:75]
	s_setprio 0
	s_setprio 1
	v_mfma_f32_16x16x32_bf16 v[112:115], v[172:175], v[188:191], v[112:115]
	v_mfma_f32_16x16x32_bf16 v[116:119], v[180:183], v[188:191], v[116:119]
	v_mfma_f32_16x16x32_bf16 v[96:99], v[172:175], v[196:199], v[96:99]
	v_mfma_f32_16x16x32_bf16 v[100:103], v[180:183], v[196:199], v[100:103]
	v_mfma_f32_16x16x32_bf16 v[80:83], v[172:175], v[204:207], v[80:83]
	v_mfma_f32_16x16x32_bf16 v[84:87], v[180:183], v[204:207], v[84:87]
	v_mfma_f32_16x16x32_bf16 v[64:67], v[172:175], v[212:215], v[64:67]
	v_mfma_f32_16x16x32_bf16 v[68:71], v[180:183], v[212:215], v[68:71]
	v_mfma_f32_16x16x32_bf16 v[112:115], v[176:179], v[192:195], v[112:115]
	v_mfma_f32_16x16x32_bf16 v[116:119], v[184:187], v[192:195], v[116:119]
	v_mfma_f32_16x16x32_bf16 v[96:99], v[176:179], v[200:203], v[96:99]
	v_mfma_f32_16x16x32_bf16 v[100:103], v[184:187], v[200:203], v[100:103]
	v_mfma_f32_16x16x32_bf16 v[80:83], v[176:179], v[208:211], v[80:83]
	v_mfma_f32_16x16x32_bf16 v[84:87], v[184:187], v[208:211], v[84:87]
	v_mfma_f32_16x16x32_bf16 v[64:67], v[176:179], v[216:219], v[64:67]
	v_mfma_f32_16x16x32_bf16 v[68:71], v[184:187], v[216:219], v[68:71]
	s_setprio 0
	s_barrier
; #define PG8_STAGE(bufoff, gbase, voff) do { _Pragma("unroll") for (int _i = 0; _i < 2; ++_i) \
;         __builtin_amdgcn_global_load_lds((const unsigned*)((const char*)(gbase) + (voff)[_i]), (LAS unsigned*)(lds + (bufoff) + ldsw + _i * 8192), 16, 0, 0); } while (0)
; #define PG8_LDA(dst, b, h) do { _Pragma("unroll") for (int m = 0; m < 4; ++m) _Pragma("unroll") for (int k = 0; k < 2; ++k) dst[m][k] = *(const LAS bf16x8*)(lds + PG8_SA(b, h) + aoff + m * 2048 + k * 1024); } while (0)
; #define PG8_MMA(ai, bj, At, Bt) do { __builtin_amdgcn_s_setprio(1); _Pragma("unroll") for (int m = 0; m < 4; ++m) _Pragma("unroll") for (int n = 0; n < 2; ++n) _Pragma("unroll") for (int k = 0; k < 2; ++k) \
;         acc[ai][bj][m][n] = __builtin_amdgcn_mfma_f32_16x16x32_bf16(Bt[n][k], At[m][k], acc[ai][bj][m][n], 0, 0, 0); __builtin_amdgcn_s_setprio(0); } while (0)
; #define PG8_WAIT_V(n) asm volatile("s_waitcnt vmcnt(" #n ")" ::: "memory")
; #define PG8_WAIT_L(n) asm volatile("s_waitcnt lgkmcnt(" #n ")" ::: "memory")
; #define PG8_BAR __builtin_amdgcn_s_barrier()
; #define PG8_SCHED __builtin_amdgcn_sched_barrier(0)
; template <class Epi, class Sched, bool ALIGN_EPI = true, bool SP2 = true>
; DI void gemm_phase(LAS unsigned char* lds, const Gemm g, const Sched& S, const Epi& E) {
;     ...
;         for (int t = 0; t < nt; t += 2) {
;             const bool last = (t == nt - 2);
;     ...
;             PG8_LDA(At, 1, 1); PG8_STAGE(PG8_SB(1, 0), b3, voffB); PG8_STAGE(PG8_SB(1, 1), b3 + hstepB, voffB); PG8_STAGE(PG8_SA(1, 0), a3, voffA);
;             PG8_WAIT_V(8); PG8_WAIT_L(0); PG8_BAR; PG8_MMA(1, 0, At, B0); PG8_MMA(1, 1, At, B1); PG8_BAR; PG8_SCHED;
;         }
	s_add_i32 s58, s91, s3
	v_lshl_add_u64 v[150:151], v[150:151], 0, s[14:15]
	s_mov_b32 m0, s58
	ds_read_b128 v[188:191], v158 offset:49152
	ds_read_b128 v[192:195], v158 offset:50176
	ds_read_b128 v[196:199], v158 offset:51200
	ds_read_b128 v[200:203], v158 offset:52224
	ds_read_b128 v[204:207], v158 offset:53248
	ds_read_b128 v[208:211], v158 offset:54272
	ds_read_b128 v[212:215], v158 offset:55296
	ds_read_b128 v[216:219], v158 offset:56320
	global_load_lds_dwordx4 v[150:151], off
	s_add_i32 m0, s58, 0x2000
	s_add_u32 s56, s56, 0x40080
	v_lshl_add_u64 v[150:151], v[220:221], 0, s[14:15]
	s_addc_u32 s57, s57, 0
	s_add_i32 s58, vcc_lo, s3
	global_load_lds_dwordx4 v[150:151], off
	v_lshl_add_u64 v[150:151], s[56:57], 0, v[130:131]
	s_mov_b32 m0, s58
	s_nop 0
	global_load_lds_dwordx4 v[150:151], off
	v_lshl_add_u64 v[150:151], s[56:57], 0, v[134:135]
	s_add_i32 m0, s58, 0x2000
	s_nop 0
	global_load_lds_dwordx4 v[150:151], off
	v_lshl_add_u64 v[150:151], v[222:223], 0, s[14:15]
	s_mov_b32 m0, s74
	s_nop 0
	global_load_lds_dwordx4 v[150:151], off
	v_lshl_add_u64 v[150:151], v[224:225], 0, s[14:15]
	s_mov_b32 m0, s75
	s_nop 0
	global_load_lds_dwordx4 v[150:151], off
	s_waitcnt vmcnt(8)
	s_waitcnt lgkmcnt(0)
	s_barrier
	s_setprio 1
	s_waitcnt lgkmcnt(0)
	v_mfma_f32_16x16x32_bf16 v[60:63], v[146:149], v[188:191], v[60:63]
	v_mfma_f32_16x16x32_bf16 v[56:59], v[164:167], v[188:191], v[56:59]
	v_mfma_f32_16x16x32_bf16 v[44:47], v[146:149], v[196:199], v[44:47]
	v_mfma_f32_16x16x32_bf16 v[40:43], v[164:167], v[196:199], v[40:43]
	v_mfma_f32_16x16x32_bf16 v[28:31], v[146:149], v[204:207], v[28:31]
	v_mfma_f32_16x16x32_bf16 v[24:27], v[164:167], v[204:207], v[24:27]
	v_mfma_f32_16x16x32_bf16 v[12:15], v[146:149], v[212:215], v[12:15]
	v_mfma_f32_16x16x32_bf16 v[8:11], v[164:167], v[212:215], v[8:11]
	v_mfma_f32_16x16x32_bf16 v[60:63], v[160:163], v[192:195], v[60:63]
	v_mfma_f32_16x16x32_bf16 v[56:59], v[168:171], v[192:195], v[56:59]
	v_mfma_f32_16x16x32_bf16 v[44:47], v[160:163], v[200:203], v[44:47]
	v_mfma_f32_16x16x32_bf16 v[40:43], v[168:171], v[200:203], v[40:43]
	v_mfma_f32_16x16x32_bf16 v[28:31], v[160:163], v[208:211], v[28:31]
	v_mfma_f32_16x16x32_bf16 v[24:27], v[168:171], v[208:211], v[24:27]
	v_mfma_f32_16x16x32_bf16 v[12:15], v[160:163], v[216:219], v[12:15]
	v_mfma_f32_16x16x32_bf16 v[8:11], v[168:171], v[216:219], v[8:11]
	s_setprio 0
	s_setprio 1
	v_mfma_f32_16x16x32_bf16 v[48:51], v[172:175], v[188:191], v[48:51]
	v_mfma_f32_16x16x32_bf16 v[52:55], v[180:183], v[188:191], v[52:55]
	v_mfma_f32_16x16x32_bf16 v[32:35], v[172:175], v[196:199], v[32:35]
	v_mfma_f32_16x16x32_bf16 v[36:39], v[180:183], v[196:199], v[36:39]
	v_mfma_f32_16x16x32_bf16 v[16:19], v[172:175], v[204:207], v[16:19]
	v_mfma_f32_16x16x32_bf16 v[20:23], v[180:183], v[204:207], v[20:23]
	v_mfma_f32_16x16x32_bf16 v[4:7], v[172:175], v[212:215], v[4:7]
	v_mfma_f32_16x16x32_bf16 v[0:3], v[180:183], v[212:215], v[0:3]
	v_mfma_f32_16x16x32_bf16 v[48:51], v[176:179], v[192:195], v[48:51]
	v_mfma_f32_16x16x32_bf16 v[52:55], v[184:187], v[192:195], v[52:55]
	v_mfma_f32_16x16x32_bf16 v[32:35], v[176:179], v[200:203], v[32:35]
	v_mfma_f32_16x16x32_bf16 v[36:39], v[184:187], v[200:203], v[36:39]
	v_mfma_f32_16x16x32_bf16 v[16:19], v[176:179], v[208:211], v[16:19]
	v_mfma_f32_16x16x32_bf16 v[20:23], v[184:187], v[208:211], v[20:23]
	v_mfma_f32_16x16x32_bf16 v[4:7], v[176:179], v[216:219], v[4:7]
	v_mfma_f32_16x16x32_bf16 v[0:3], v[184:187], v[216:219], v[0:3]
	s_setprio 0
	s_add_i32 s97, s97, 2
	s_add_u32 s54, s54, 0x100
	s_addc_u32 s55, s55, 0
	s_add_u32 s95, s95, 0x100
	s_addc_u32 s96, s96, 0
	s_cmp_gt_u32 s97, 13
	s_barrier
	s_cbranch_scc0 .LBB0_179
	s_and_b64 vcc, exec, s[16:17]
	s_cbranch_vccz .LBB0_182
	s_barrier

; #define PG8_STAGE(bufoff, gbase, voff) do { _Pragma("unroll") for (int _i = 0; _i < 2; ++_i) \
;         __builtin_amdgcn_global_load_lds((const unsigned*)((const char*)(gbase) + (voff)[_i]), (LAS unsigned*)(lds + (bufoff) + ldsw + _i * 8192), 16, 0, 0); } while (0)
; #define PG8_LDA(dst, b, h) do { _Pragma("unroll") for (int m = 0; m < 4; ++m) _Pragma("unroll") for (int k = 0; k < 2; ++k) dst[m][k] = *(const LAS bf16x8*)(lds + PG8_SA(b, h) + aoff + m * 2048 + k * 1024); } while (0)
; #define PG8_LDB(dst, b, h) do { _Pragma("unroll") for (int n = 0; n < 2; ++n) _Pragma("unroll") for (int k = 0; k < 2; ++k) dst[n][k] = *(const LAS bf16x8*)(lds + PG8_SB(b, h) + boff + n * 2048 + k * 1024); } while (0)
; #define PG8_MMA(ai, bj, At, Bt) do { __builtin_amdgcn_s_setprio(1); _Pragma("unroll") for (int m = 0; m < 4; ++m) _Pragma("unroll") for (int n = 0; n < 2; ++n) _Pragma("unroll") for (int k = 0; k < 2; ++k) \
;         acc[ai][bj][m][n] = __builtin_amdgcn_mfma_f32_16x16x32_bf16(Bt[n][k], At[m][k], acc[ai][bj][m][n], 0, 0, 0); __builtin_amdgcn_s_setprio(0); } while (0)
; #define PG8_WAIT_V(n) asm volatile("s_waitcnt vmcnt(" #n ")" ::: "memory")
; #define PG8_WAIT_L(n) asm volatile("s_waitcnt lgkmcnt(" #n ")" ::: "memory")
; #define PG8_BAR __builtin_amdgcn_s_barrier()
; #define PG8_SCHED __builtin_amdgcn_sched_barrier(0)
; template <class Epi, class Sched, bool ALIGN_EPI = true, bool SP2 = true>
; DI void gemm_phase(LAS unsigned char* lds, const Gemm g, const Sched& S, const Epi& E) {
;     ...
;         for (int t = 0; t < nt; t += 2) {
;             const bool last = (t == nt - 2);
;             const char* a1 = cA + (size_t)(t + 1) * kstep;
;             const char* a2 = last ? nA : cA + (size_t)(t + 2) * kstep; const char* b2 = last ? nB : cB + (size_t)(t + 2) * kstep;
;             const char* a3 = a2 + kstep; const char* b3 = b2 + kstep;
;             PG8_LDB(B0, 0, 0); PG8_LDB(B1, 0, 1); PG8_SCHED; PG8_LDA(At, 0, 0); PG8_STAGE(PG8_SA(1, 1), a1 + hstepA, voffA);
;             PG8_WAIT_V(8); PG8_WAIT_L(0); PG8_BAR; PG8_MMA(0, 0, At, B0); PG8_MMA(0, 1, At, B1); PG8_BAR; PG8_SCHED;
;             PG8_LDA(At, 0, 1); PG8_STAGE(PG8_SB(0, 0), b2, voffB); PG8_STAGE(PG8_SB(0, 1), b2 + hstepB, voffB); PG8_STAGE(PG8_SA(0, 0), a2, voffA);
.LBB0_619:
	ds_read_b128 v[140:143], v163
	ds_read_b128 v[144:147], v163 offset:1024
	ds_read_b128 v[148:151], v163 offset:2048
	ds_read_b128 v[152:155], v163 offset:3072
	ds_read_b128 v[156:159], v164
	ds_read_b128 v[166:169], v164 offset:1024
	ds_read_b128 v[170:173], v164 offset:2048
	ds_read_b128 v[174:177], v164 offset:3072
	s_add_u32 s60, s58, 0xfff80080
	s_addc_u32 s61, s59, -1
	s_cmp_eq_u32 s94, 28
	s_cselect_b32 s63, s45, s61
	s_cselect_b32 s62, s88, s60
	s_cselect_b32 s61, s43, s93
	s_cselect_b32 s60, s89, s92
	v_lshl_add_u64 v[210:211], s[58:59], 0, v[132:133]
	s_add_i32 m0, s73, 0xc000
	ds_read_b128 v[178:181], v165
	ds_read_b128 v[182:185], v165 offset:1024
	ds_read_b128 v[186:189], v165 offset:2048
	ds_read_b128 v[190:193], v165 offset:3072
	ds_read_b128 v[194:197], v165 offset:4096
	ds_read_b128 v[198:201], v165 offset:5120
	ds_read_b128 v[202:205], v165 offset:6144
	ds_read_b128 v[206:209], v165 offset:7168
	global_load_lds_dwordx4 v[210:211], off
	v_lshl_add_u64 v[210:211], s[58:59], 0, v[134:135]
	s_add_i32 m0, s73, 0xe000
	s_nop 0
	global_load_lds_dwordx4 v[210:211], off
	s_waitcnt vmcnt(8)
	s_waitcnt lgkmcnt(0)
	s_barrier
	s_setprio 1
	s_waitcnt lgkmcnt(0)
	v_mfma_f32_16x16x32_bf16 v[124:127], v[140:143], v[178:181], v[124:127]
	v_mfma_f32_16x16x32_bf16 v[120:123], v[148:151], v[178:181], v[120:123]
	v_mfma_f32_16x16x32_bf16 v[112:115], v[140:143], v[186:189], v[112:115]
	v_mfma_f32_16x16x32_bf16 v[104:107], v[148:151], v[186:189], v[104:107]
	v_mfma_f32_16x16x32_bf16 v[96:99], v[140:143], v[194:197], v[96:99]
	v_mfma_f32_16x16x32_bf16 v[88:91], v[148:151], v[194:197], v[88:91]
	v_mfma_f32_16x16x32_bf16 v[80:83], v[140:143], v[202:205], v[80:83]
	v_mfma_f32_16x16x32_bf16 v[72:75], v[148:151], v[202:205], v[72:75]
	v_mfma_f32_16x16x32_bf16 v[124:127], v[144:147], v[182:185], v[124:127]
	v_mfma_f32_16x16x32_bf16 v[120:123], v[152:155], v[182:185], v[120:123]
	v_mfma_f32_16x16x32_bf16 v[112:115], v[144:147], v[190:193], v[112:115]
	v_mfma_f32_16x16x32_bf16 v[104:107], v[152:155], v[190:193], v[104:107]
	v_mfma_f32_16x16x32_bf16 v[96:99], v[144:147], v[198:201], v[96:99]
	v_mfma_f32_16x16x32_bf16 v[88:91], v[152:155], v[198:201], v[88:91]
	v_mfma_f32_16x16x32_bf16 v[80:83], v[144:147], v[206:209], v[80:83]
	v_mfma_f32_16x16x32_bf16 v[72:75], v[152:155], v[206:209], v[72:75]
	s_setprio 0
	s_setprio 1
	v_mfma_f32_16x16x32_bf16 v[116:119], v[156:159], v[178:181], v[116:119]
	v_mfma_f32_16x16x32_bf16 v[108:111], v[170:173], v[178:181], v[108:111]
	v_mfma_f32_16x16x32_bf16 v[100:103], v[156:159], v[186:189], v[100:103]
	v_mfma_f32_16x16x32_bf16 v[92:95], v[170:173], v[186:189], v[92:95]
	v_mfma_f32_16x16x32_bf16 v[84:87], v[156:159], v[194:197], v[84:87]
	v_mfma_f32_16x16x32_bf16 v[76:79], v[170:173], v[194:197], v[76:79]
	v_mfma_f32_16x16x32_bf16 v[68:71], v[156:159], v[202:205], v[68:71]
	v_mfma_f32_16x16x32_bf16 v[64:67], v[170:173], v[202:205], v[64:67]
	v_mfma_f32_16x16x32_bf16 v[116:119], v[166:169], v[182:185], v[116:119]
	v_mfma_f32_16x16x32_bf16 v[108:111], v[174:177], v[182:185], v[108:111]
	v_mfma_f32_16x16x32_bf16 v[100:103], v[166:169], v[190:193], v[100:103]
	v_mfma_f32_16x16x32_bf16 v[92:95], v[174:177], v[190:193], v[92:95]
	v_mfma_f32_16x16x32_bf16 v[84:87], v[166:169], v[198:201], v[84:87]
	v_mfma_f32_16x16x32_bf16 v[76:79], v[174:177], v[198:201], v[76:79]
	v_mfma_f32_16x16x32_bf16 v[68:71], v[166:169], v[206:209], v[68:71]
	v_mfma_f32_16x16x32_bf16 v[64:67], v[174:177], v[206:209], v[64:67]
	s_setprio 0
	s_barrier
	s_add_i32 s91, s86, s72
	v_lshl_add_u64 v[210:211], s[60:61], 0, v[128:129]
	s_mov_b32 m0, s91
	ds_read_b128 v[178:181], v165 offset:16384
	ds_read_b128 v[182:185], v165 offset:17408
	ds_read_b128 v[186:189], v165 offset:18432
	ds_read_b128 v[190:193], v165 offset:19456
	ds_read_b128 v[194:197], v165 offset:20480
	ds_read_b128 v[198:201], v165 offset:21504
	ds_read_b128 v[202:205], v165 offset:22528
	ds_read_b128 v[206:209], v165 offset:23552
	global_load_lds_dwordx4 v[210:211], off
	s_add_i32 m0, s91, 0x2000
	s_add_u32 s96, s60, 0x80000
	v_lshl_add_u64 v[212:213], s[60:61], 0, v[130:131]
	s_addc_u32 s97, s61, 0
	s_add_i32 s91, s87, s72
	global_load_lds_dwordx4 v[212:213], off
	v_lshl_add_u64 v[214:215], s[96:97], 0, v[128:129]
	s_mov_b32 m0, s91
	v_lshl_add_u64 v[216:217], s[62:63], 0, v[130:131]
	global_load_lds_dwordx4 v[214:215], off
	v_lshl_add_u64 v[214:215], s[96:97], 0, v[130:131]
	s_add_i32 m0, s91, 0x2000
	s_nop 0
	global_load_lds_dwordx4 v[214:215], off
	v_lshl_add_u64 v[214:215], s[62:63], 0, v[128:129]
	s_mov_b32 m0, s73
	s_nop 0
	global_load_lds_dwordx4 v[214:215], off
	s_mov_b32 m0, s74
	s_nop 0
	global_load_lds_dwordx4 v[216:217], off
	s_waitcnt vmcnt(8)
	s_waitcnt lgkmcnt(0)
	s_barrier
; #define PG8_STAGE(bufoff, gbase, voff) do { _Pragma("unroll") for (int _i = 0; _i < 2; ++_i) \
;         __builtin_amdgcn_global_load_lds((const unsigned*)((const char*)(gbase) + (voff)[_i]), (LAS unsigned*)(lds + (bufoff) + ldsw + _i * 8192), 16, 0, 0); } while (0)
; #define PG8_LDA(dst, b, h) do { _Pragma("unroll") for (int m = 0; m < 4; ++m) _Pragma("unroll") for (int k = 0; k < 2; ++k) dst[m][k] = *(const LAS bf16x8*)(lds + PG8_SA(b, h) + aoff + m * 2048 + k * 1024); } while (0)
; #define PG8_LDB(dst, b, h) do { _Pragma("unroll") for (int n = 0; n < 2; ++n) _Pragma("unroll") for (int k = 0; k < 2; ++k) dst[n][k] = *(const LAS bf16x8*)(lds + PG8_SB(b, h) + boff + n * 2048 + k * 1024); } while (0)
; #define PG8_MMA(ai, bj, At, Bt) do { __builtin_amdgcn_s_setprio(1); _Pragma("unroll") for (int m = 0; m < 4; ++m) _Pragma("unroll") for (int n = 0; n < 2; ++n) _Pragma("unroll") for (int k = 0; k < 2; ++k) \
;         acc[ai][bj][m][n] = __builtin_amdgcn_mfma_f32_16x16x32_bf16(Bt[n][k], At[m][k], acc[ai][bj][m][n], 0, 0, 0); __builtin_amdgcn_s_setprio(0); } while (0)
; #define PG8_WAIT_V(n) asm volatile("s_waitcnt vmcnt(" #n ")" ::: "memory")
; #define PG8_WAIT_L(n) asm volatile("s_waitcnt lgkmcnt(" #n ")" ::: "memory")
; #define PG8_BAR __builtin_amdgcn_s_barrier()
; #define PG8_SCHED __builtin_amdgcn_sched_barrier(0)
; template <class Epi, class Sched, bool ALIGN_EPI = true, bool SP2 = true>
; DI void gemm_phase(LAS unsigned char* lds, const Gemm g, const Sched& S, const Epi& E) {
;     ...
;             PG8_WAIT_V(8); PG8_WAIT_L(0); PG8_BAR; PG8_MMA(1, 0, At, B0); PG8_MMA(1, 1, At, B1); PG8_BAR; PG8_SCHED;
;             PG8_LDB(B0, 1, 0); PG8_LDB(B1, 1, 1); PG8_SCHED; PG8_LDA(At, 1, 0); PG8_STAGE(PG8_SA(0, 1), a2 + hstepA, voffA);
;             PG8_WAIT_V(8); PG8_WAIT_L(0); PG8_BAR; PG8_MMA(0, 0, At, B0); PG8_MMA(0, 1, At, B1); PG8_BAR; PG8_SCHED;
	s_setprio 1
	s_waitcnt lgkmcnt(0)
	v_mfma_f32_16x16x32_bf16 v[60:63], v[140:143], v[178:181], v[60:63]
	v_mfma_f32_16x16x32_bf16 v[56:59], v[148:151], v[178:181], v[56:59]
	v_mfma_f32_16x16x32_bf16 v[48:51], v[140:143], v[186:189], v[48:51]
	v_mfma_f32_16x16x32_bf16 v[40:43], v[148:151], v[186:189], v[40:43]
	v_mfma_f32_16x16x32_bf16 v[32:35], v[140:143], v[194:197], v[32:35]
	v_mfma_f32_16x16x32_bf16 v[24:27], v[148:151], v[194:197], v[24:27]
	v_mfma_f32_16x16x32_bf16 v[16:19], v[140:143], v[202:205], v[16:19]
	v_mfma_f32_16x16x32_bf16 v[8:11], v[148:151], v[202:205], v[8:11]
	v_mfma_f32_16x16x32_bf16 v[60:63], v[144:147], v[182:185], v[60:63]
	v_mfma_f32_16x16x32_bf16 v[56:59], v[152:155], v[182:185], v[56:59]
	v_mfma_f32_16x16x32_bf16 v[48:51], v[144:147], v[190:193], v[48:51]
	v_mfma_f32_16x16x32_bf16 v[40:43], v[152:155], v[190:193], v[40:43]
	v_mfma_f32_16x16x32_bf16 v[32:35], v[144:147], v[198:201], v[32:35]
	v_mfma_f32_16x16x32_bf16 v[24:27], v[152:155], v[198:201], v[24:27]
	v_mfma_f32_16x16x32_bf16 v[16:19], v[144:147], v[206:209], v[16:19]
	v_mfma_f32_16x16x32_bf16 v[8:11], v[152:155], v[206:209], v[8:11]
	s_setprio 0
	s_setprio 1
	v_mfma_f32_16x16x32_bf16 v[52:55], v[156:159], v[178:181], v[52:55]
	v_mfma_f32_16x16x32_bf16 v[44:47], v[170:173], v[178:181], v[44:47]
	v_mfma_f32_16x16x32_bf16 v[36:39], v[156:159], v[186:189], v[36:39]
	v_mfma_f32_16x16x32_bf16 v[28:31], v[170:173], v[186:189], v[28:31]
	v_mfma_f32_16x16x32_bf16 v[20:23], v[156:159], v[194:197], v[20:23]
	v_mfma_f32_16x16x32_bf16 v[12:15], v[170:173], v[194:197], v[12:15]
	v_mfma_f32_16x16x32_bf16 v[4:7], v[156:159], v[202:205], v[4:7]
	v_mfma_f32_16x16x32_bf16 v[0:3], v[170:173], v[202:205], v[0:3]
	v_mfma_f32_16x16x32_bf16 v[52:55], v[166:169], v[182:185], v[52:55]
	v_mfma_f32_16x16x32_bf16 v[44:47], v[174:177], v[182:185], v[44:47]
	v_mfma_f32_16x16x32_bf16 v[36:39], v[166:169], v[190:193], v[36:39]
	v_mfma_f32_16x16x32_bf16 v[28:31], v[174:177], v[190:193], v[28:31]
	v_mfma_f32_16x16x32_bf16 v[20:23], v[166:169], v[198:201], v[20:23]
	v_mfma_f32_16x16x32_bf16 v[12:15], v[174:177], v[198:201], v[12:15]
	v_mfma_f32_16x16x32_bf16 v[4:7], v[166:169], v[206:209], v[4:7]
	v_mfma_f32_16x16x32_bf16 v[0:3], v[174:177], v[206:209], v[0:3]
	s_setprio 0
	s_barrier
	s_add_i32 s91, 0, 0x18000
	s_add_i32 s95, 0, 0x1c000
	v_add_u32_e32 v152, s91, v161
	v_add_u32_e32 v174, s95, v161
	ds_read_b128 v[140:143], v152
	ds_read_b128 v[144:147], v152 offset:1024
	ds_read_b128 v[148:151], v152 offset:2048
	ds_read_b128 v[152:155], v152 offset:3072
	ds_read_b128 v[156:159], v174
	ds_read_b128 v[166:169], v174 offset:1024
	ds_read_b128 v[170:173], v174 offset:2048
	ds_read_b128 v[174:177], v174 offset:3072
	s_add_u32 s62, s62, 0x80000
	s_addc_u32 s63, s63, 0
	s_mov_b32 m0, s75
	v_lshl_add_u64 v[218:219], s[62:63], 0, v[128:129]
	ds_read_b128 v[178:181], v165 offset:32768
	ds_read_b128 v[182:185], v165 offset:33792
	ds_read_b128 v[186:189], v165 offset:34816
	ds_read_b128 v[190:193], v165 offset:35840
	ds_read_b128 v[194:197], v165 offset:36864
	ds_read_b128 v[198:201], v165 offset:37888
	ds_read_b128 v[202:205], v165 offset:38912
	ds_read_b128 v[206:209], v165 offset:39936
	global_load_lds_dwordx4 v[218:219], off
	v_lshl_add_u64 v[218:219], s[62:63], 0, v[130:131]
	s_mov_b32 m0, s76
	s_nop 0
	global_load_lds_dwordx4 v[218:219], off
	s_waitcnt vmcnt(8)
	s_waitcnt lgkmcnt(0)
	s_barrier
	s_setprio 1
	s_waitcnt lgkmcnt(0)
	v_mfma_f32_16x16x32_bf16 v[124:127], v[140:143], v[178:181], v[124:127]
	v_mfma_f32_16x16x32_bf16 v[120:123], v[148:151], v[178:181], v[120:123]
	v_mfma_f32_16x16x32_bf16 v[112:115], v[140:143], v[186:189], v[112:115]
	v_mfma_f32_16x16x32_bf16 v[104:107], v[148:151], v[186:189], v[104:107]
	v_mfma_f32_16x16x32_bf16 v[96:99], v[140:143], v[194:197], v[96:99]
	v_mfma_f32_16x16x32_bf16 v[88:91], v[148:151], v[194:197], v[88:91]
	v_mfma_f32_16x16x32_bf16 v[80:83], v[140:143], v[202:205], v[80:83]
	v_mfma_f32_16x16x32_bf16 v[72:75], v[148:151], v[202:205], v[72:75]
	v_mfma_f32_16x16x32_bf16 v[124:127], v[144:147], v[182:185], v[124:127]
	v_mfma_f32_16x16x32_bf16 v[120:123], v[152:155], v[182:185], v[120:123]
	v_mfma_f32_16x16x32_bf16 v[112:115], v[144:147], v[190:193], v[112:115]
	v_mfma_f32_16x16x32_bf16 v[104:107], v[152:155], v[190:193], v[104:107]
	v_mfma_f32_16x16x32_bf16 v[96:99], v[144:147], v[198:201], v[96:99]
	v_mfma_f32_16x16x32_bf16 v[88:91], v[152:155], v[198:201], v[88:91]
	v_mfma_f32_16x16x32_bf16 v[80:83], v[144:147], v[206:209], v[80:83]
	v_mfma_f32_16x16x32_bf16 v[72:75], v[152:155], v[206:209], v[72:75]
	s_setprio 0
	s_setprio 1
	v_mfma_f32_16x16x32_bf16 v[116:119], v[156:159], v[178:181], v[116:119]
	v_mfma_f32_16x16x32_bf16 v[108:111], v[170:173], v[178:181], v[108:111]
	v_mfma_f32_16x16x32_bf16 v[100:103], v[156:159], v[186:189], v[100:103]
	v_mfma_f32_16x16x32_bf16 v[92:95], v[170:173], v[186:189], v[92:95]
	v_mfma_f32_16x16x32_bf16 v[84:87], v[156:159], v[194:197], v[84:87]
	v_mfma_f32_16x16x32_bf16 v[76:79], v[170:173], v[194:197], v[76:79]
	v_mfma_f32_16x16x32_bf16 v[68:71], v[156:159], v[202:205], v[68:71]
	v_mfma_f32_16x16x32_bf16 v[64:67], v[170:173], v[202:205], v[64:67]
	v_mfma_f32_16x16x32_bf16 v[116:119], v[166:169], v[182:185], v[116:119]
	v_mfma_f32_16x16x32_bf16 v[108:111], v[174:177], v[182:185], v[108:111]
	v_mfma_f32_16x16x32_bf16 v[100:103], v[166:169], v[190:193], v[100:103]
	v_mfma_f32_16x16x32_bf16 v[92:95], v[174:177], v[190:193], v[92:95]
	v_mfma_f32_16x16x32_bf16 v[84:87], v[166:169], v[198:201], v[84:87]
	v_mfma_f32_16x16x32_bf16 v[76:79], v[174:177], v[198:201], v[76:79]
	v_mfma_f32_16x16x32_bf16 v[68:71], v[166:169], v[206:209], v[68:71]
	v_mfma_f32_16x16x32_bf16 v[64:67], v[174:177], v[206:209], v[64:67]
	s_setprio 0
	s_barrier
; #define PG8_STAGE(bufoff, gbase, voff) do { _Pragma("unroll") for (int _i = 0; _i < 2; ++_i) \
;         __builtin_amdgcn_global_load_lds((const unsigned*)((const char*)(gbase) + (voff)[_i]), (LAS unsigned*)(lds + (bufoff) + ldsw + _i * 8192), 16, 0, 0); } while (0)
; #define PG8_LDA(dst, b, h) do { _Pragma("unroll") for (int m = 0; m < 4; ++m) _Pragma("unroll") for (int k = 0; k < 2; ++k) dst[m][k] = *(const LAS bf16x8*)(lds + PG8_SA(b, h) + aoff + m * 2048 + k * 1024); } while (0)
; #define PG8_MMA(ai, bj, At, Bt) do { __builtin_amdgcn_s_setprio(1); _Pragma("unroll") for (int m = 0; m < 4; ++m) _Pragma("unroll") for (int n = 0; n < 2; ++n) _Pragma("unroll") for (int k = 0; k < 2; ++k) \
;         acc[ai][bj][m][n] = __builtin_amdgcn_mfma_f32_16x16x32_bf16(Bt[n][k], At[m][k], acc[ai][bj][m][n], 0, 0, 0); __builtin_amdgcn_s_setprio(0); } while (0)
; #define PG8_WAIT_V(n) asm volatile("s_waitcnt vmcnt(" #n ")" ::: "memory")
; #define PG8_WAIT_L(n) asm volatile("s_waitcnt lgkmcnt(" #n ")" ::: "memory")
; #define PG8_BAR __builtin_amdgcn_s_barrier()
; #define PG8_SCHED __builtin_amdgcn_sched_barrier(0)
; template <class Epi, class Sched, bool ALIGN_EPI = true, bool SP2 = true>
; DI void gemm_phase(LAS unsigned char* lds, const Gemm g, const Sched& S, const Epi& E) {
;     ...
;         for (int t = 0; t < nt; t += 2) {
;             const bool last = (t == nt - 2);
;     ...
;             PG8_LDA(At, 1, 1); PG8_STAGE(PG8_SB(1, 0), b3, voffB); PG8_STAGE(PG8_SB(1, 1), b3 + hstepB, voffB); PG8_STAGE(PG8_SA(1, 0), a3, voffA);
;             PG8_WAIT_V(8); PG8_WAIT_L(0); PG8_BAR; PG8_MMA(1, 0, At, B0); PG8_MMA(1, 1, At, B1); PG8_BAR; PG8_SCHED;
;         }
	s_add_i32 s62, s91, s72
	v_lshl_add_u64 v[210:211], v[210:211], 0, s[10:11]
	s_mov_b32 m0, s62
	ds_read_b128 v[178:181], v165 offset:49152
	ds_read_b128 v[182:185], v165 offset:50176
	ds_read_b128 v[186:189], v165 offset:51200
	ds_read_b128 v[190:193], v165 offset:52224
	ds_read_b128 v[194:197], v165 offset:53248
	ds_read_b128 v[198:201], v165 offset:54272
	ds_read_b128 v[202:205], v165 offset:55296
	ds_read_b128 v[206:209], v165 offset:56320
	global_load_lds_dwordx4 v[210:211], off
	s_add_i32 m0, s62, 0x2000
	s_add_u32 s60, s60, 0x80080
	v_lshl_add_u64 v[210:211], v[212:213], 0, s[10:11]
	s_addc_u32 s61, s61, 0
	s_add_i32 s62, s95, s72
	global_load_lds_dwordx4 v[210:211], off
	v_lshl_add_u64 v[210:211], s[60:61], 0, v[128:129]
	s_mov_b32 m0, s62
	s_nop 0
	global_load_lds_dwordx4 v[210:211], off
	v_lshl_add_u64 v[210:211], s[60:61], 0, v[130:131]
	s_add_i32 m0, s62, 0x2000
	s_nop 0
	global_load_lds_dwordx4 v[210:211], off
	v_lshl_add_u64 v[210:211], v[214:215], 0, s[10:11]
	s_mov_b32 m0, s79
	s_nop 0
	global_load_lds_dwordx4 v[210:211], off
	v_lshl_add_u64 v[210:211], v[216:217], 0, s[10:11]
	s_mov_b32 m0, s81
	s_nop 0
	global_load_lds_dwordx4 v[210:211], off
	s_waitcnt vmcnt(8)
	s_waitcnt lgkmcnt(0)
	s_barrier
	s_setprio 1
	s_waitcnt lgkmcnt(0)
	v_mfma_f32_16x16x32_bf16 v[60:63], v[140:143], v[178:181], v[60:63]
	v_mfma_f32_16x16x32_bf16 v[56:59], v[148:151], v[178:181], v[56:59]
	v_mfma_f32_16x16x32_bf16 v[48:51], v[140:143], v[186:189], v[48:51]
	v_mfma_f32_16x16x32_bf16 v[40:43], v[148:151], v[186:189], v[40:43]
	v_mfma_f32_16x16x32_bf16 v[32:35], v[140:143], v[194:197], v[32:35]
	v_mfma_f32_16x16x32_bf16 v[24:27], v[148:151], v[194:197], v[24:27]
	v_mfma_f32_16x16x32_bf16 v[16:19], v[140:143], v[202:205], v[16:19]
	v_mfma_f32_16x16x32_bf16 v[8:11], v[148:151], v[202:205], v[8:11]
	v_mfma_f32_16x16x32_bf16 v[60:63], v[144:147], v[182:185], v[60:63]
	v_mfma_f32_16x16x32_bf16 v[56:59], v[152:155], v[182:185], v[56:59]
	v_mfma_f32_16x16x32_bf16 v[48:51], v[144:147], v[190:193], v[48:51]
	v_mfma_f32_16x16x32_bf16 v[40:43], v[152:155], v[190:193], v[40:43]
	v_mfma_f32_16x16x32_bf16 v[32:35], v[144:147], v[198:201], v[32:35]
	v_mfma_f32_16x16x32_bf16 v[24:27], v[152:155], v[198:201], v[24:27]
	v_mfma_f32_16x16x32_bf16 v[16:19], v[144:147], v[206:209], v[16:19]
	v_mfma_f32_16x16x32_bf16 v[8:11], v[152:155], v[206:209], v[8:11]
	s_setprio 0
	s_setprio 1
	v_mfma_f32_16x16x32_bf16 v[52:55], v[156:159], v[178:181], v[52:55]
	v_mfma_f32_16x16x32_bf16 v[44:47], v[170:173], v[178:181], v[44:47]
	v_mfma_f32_16x16x32_bf16 v[36:39], v[156:159], v[186:189], v[36:39]
	v_mfma_f32_16x16x32_bf16 v[28:31], v[170:173], v[186:189], v[28:31]
	v_mfma_f32_16x16x32_bf16 v[20:23], v[156:159], v[194:197], v[20:23]
	v_mfma_f32_16x16x32_bf16 v[12:15], v[170:173], v[194:197], v[12:15]
	v_mfma_f32_16x16x32_bf16 v[4:7], v[156:159], v[202:205], v[4:7]
	v_mfma_f32_16x16x32_bf16 v[0:3], v[170:173], v[202:205], v[0:3]
	v_mfma_f32_16x16x32_bf16 v[52:55], v[166:169], v[182:185], v[52:55]
	v_mfma_f32_16x16x32_bf16 v[44:47], v[174:177], v[182:185], v[44:47]
	v_mfma_f32_16x16x32_bf16 v[36:39], v[166:169], v[190:193], v[36:39]
	v_mfma_f32_16x16x32_bf16 v[28:31], v[174:177], v[190:193], v[28:31]
	v_mfma_f32_16x16x32_bf16 v[20:23], v[166:169], v[198:201], v[20:23]
	v_mfma_f32_16x16x32_bf16 v[12:15], v[174:177], v[198:201], v[12:15]
	v_mfma_f32_16x16x32_bf16 v[4:7], v[166:169], v[206:209], v[4:7]
	v_mfma_f32_16x16x32_bf16 v[0:3], v[174:177], v[206:209], v[0:3]
	s_setprio 0
	s_add_i32 s94, s94, 2
	s_add_u32 s58, s58, 0x100
	s_addc_u32 s59, s59, 0
	s_add_u32 s92, s92, 0x100
	s_addc_u32 s93, s93, 0
	s_cmp_gt_u32 s94, 29
	s_barrier
	s_cbranch_scc0 .LBB0_619
	s_and_b64 vcc, exec, s[12:13]
	s_cbranch_vccz .LBB0_622
	s_barrier

; #define PG8_STAGE(bufoff, gbase, voff) do { _Pragma("unroll") for (int _i = 0; _i < 2; ++_i) \
;         __builtin_amdgcn_global_load_lds((const unsigned*)((const char*)(gbase) + (voff)[_i]), (LAS unsigned*)(lds + (bufoff) + ldsw + _i * 8192), 16, 0, 0); } while (0)
; #define PG8_LDA(dst, b, h) do { _Pragma("unroll") for (int m = 0; m < 4; ++m) _Pragma("unroll") for (int k = 0; k < 2; ++k) dst[m][k] = *(const LAS bf16x8*)(lds + PG8_SA(b, h) + aoff + m * 2048 + k * 1024); } while (0)
; #define PG8_LDB(dst, b, h) do { _Pragma("unroll") for (int n = 0; n < 2; ++n) _Pragma("unroll") for (int k = 0; k < 2; ++k) dst[n][k] = *(const LAS bf16x8*)(lds + PG8_SB(b, h) + boff + n * 2048 + k * 1024); } while (0)
; #define PG8_MMA(ai, bj, At, Bt) do { __builtin_amdgcn_s_setprio(1); _Pragma("unroll") for (int m = 0; m < 4; ++m) _Pragma("unroll") for (int n = 0; n < 2; ++n) _Pragma("unroll") for (int k = 0; k < 2; ++k) \
;         acc[ai][bj][m][n] = __builtin_amdgcn_mfma_f32_16x16x32_bf16(Bt[n][k], At[m][k], acc[ai][bj][m][n], 0, 0, 0); __builtin_amdgcn_s_setprio(0); } while (0)
; #define PG8_WAIT_V(n) asm volatile("s_waitcnt vmcnt(" #n ")" ::: "memory")
; #define PG8_WAIT_L(n) asm volatile("s_waitcnt lgkmcnt(" #n ")" ::: "memory")
; #define PG8_BAR __builtin_amdgcn_s_barrier()
; #define PG8_SCHED __builtin_amdgcn_sched_barrier(0)
; template <class Epi, class Sched, bool ALIGN_EPI = true, bool SP2 = true>
; DI void gemm_phase(LAS unsigned char* lds, const Gemm g, const Sched& S, const Epi& E) {
;     ...
;         for (int t = 0; t < nt; t += 2) {
;             const bool last = (t == nt - 2);
;             const char* a1 = cA + (size_t)(t + 1) * kstep;
;             const char* a2 = last ? nA : cA + (size_t)(t + 2) * kstep; const char* b2 = last ? nB : cB + (size_t)(t + 2) * kstep;
;             const char* a3 = a2 + kstep; const char* b3 = b2 + kstep;
;             PG8_LDB(B0, 0, 0); PG8_LDB(B1, 0, 1); PG8_SCHED; PG8_LDA(At, 0, 0); PG8_STAGE(PG8_SA(1, 1), a1 + hstepA, voffA);
;             PG8_WAIT_V(8); PG8_WAIT_L(0); PG8_BAR; PG8_MMA(0, 0, At, B0); PG8_MMA(0, 1, At, B1); PG8_BAR; PG8_SCHED;
;             PG8_LDA(At, 0, 1); PG8_STAGE(PG8_SB(0, 0), b2, voffB); PG8_STAGE(PG8_SB(0, 1), b2 + hstepB, voffB); PG8_STAGE(PG8_SA(0, 0), a2, voffA);
.LBB0_773:
	v_add_u32_e32 v170, s92, v178
	v_add_u32_e32 v193, s93, v178
	ds_read_b128 v[158:161], v170
	ds_read_b128 v[162:165], v170 offset:1024
	ds_read_b128 v[166:169], v170 offset:2048
	ds_read_b128 v[170:173], v170 offset:3072
	ds_read_b128 v[174:177], v193
	ds_read_b128 v[194:197], v193 offset:1024
	ds_read_b128 v[198:201], v193 offset:2048
	ds_read_b128 v[202:205], v193 offset:3072
	s_add_u32 s66, s10, 0xfff80080
	s_addc_u32 s67, s11, -1
	s_cmp_eq_u32 s97, 28
	s_cselect_b32 s73, s55, s67
	s_cselect_b32 s72, s63, s66
	s_cselect_b32 s67, s57, s96
	s_cselect_b32 s66, s65, s95
	v_lshl_add_u64 v[240:241], s[10:11], 0, v[150:151]
	s_add_i32 m0, s78, 0xc000
	ds_read_b128 v[206:209], v190
	ds_read_b128 v[210:213], v190 offset:1024
	ds_read_b128 v[214:217], v190 offset:2048
	ds_read_b128 v[218:221], v190 offset:3072
	ds_read_b128 v[222:225], v190 offset:4096
	ds_read_b128 v[228:231], v190 offset:5120
	ds_read_b128 v[232:235], v190 offset:6144
	ds_read_b128 v[236:239], v190 offset:7168
	global_load_lds_dwordx4 v[240:241], off
	v_lshl_add_u64 v[240:241], s[10:11], 0, v[152:153]
	s_add_i32 m0, s78, 0xe000
	s_nop 0
	global_load_lds_dwordx4 v[240:241], off
	s_waitcnt vmcnt(8)
	s_waitcnt lgkmcnt(0)
	s_barrier
	s_setprio 1
	s_waitcnt lgkmcnt(0)
	v_mfma_f32_16x16x32_bf16 v[124:127], v[158:161], v[206:209], v[124:127]
	v_mfma_f32_16x16x32_bf16 v[120:123], v[166:169], v[206:209], v[120:123]
	v_mfma_f32_16x16x32_bf16 v[108:111], v[158:161], v[214:217], v[108:111]
	v_mfma_f32_16x16x32_bf16 v[104:107], v[166:169], v[214:217], v[104:107]
	v_mfma_f32_16x16x32_bf16 v[92:95], v[158:161], v[222:225], v[92:95]
	v_mfma_f32_16x16x32_bf16 v[88:91], v[166:169], v[222:225], v[88:91]
	v_mfma_f32_16x16x32_bf16 v[76:79], v[158:161], v[232:235], v[76:79]
	v_mfma_f32_16x16x32_bf16 v[72:75], v[166:169], v[232:235], v[72:75]
	v_mfma_f32_16x16x32_bf16 v[124:127], v[162:165], v[210:213], v[124:127]
	v_mfma_f32_16x16x32_bf16 v[120:123], v[170:173], v[210:213], v[120:123]
	v_mfma_f32_16x16x32_bf16 v[108:111], v[162:165], v[218:221], v[108:111]
	v_mfma_f32_16x16x32_bf16 v[104:107], v[170:173], v[218:221], v[104:107]
	v_mfma_f32_16x16x32_bf16 v[92:95], v[162:165], v[228:231], v[92:95]
	v_mfma_f32_16x16x32_bf16 v[88:91], v[170:173], v[228:231], v[88:91]
	v_mfma_f32_16x16x32_bf16 v[76:79], v[162:165], v[236:239], v[76:79]
	v_mfma_f32_16x16x32_bf16 v[72:75], v[170:173], v[236:239], v[72:75]
	s_setprio 0
	s_setprio 1
	v_mfma_f32_16x16x32_bf16 v[116:119], v[174:177], v[206:209], v[116:119]
	v_mfma_f32_16x16x32_bf16 v[112:115], v[198:201], v[206:209], v[112:115]
	v_mfma_f32_16x16x32_bf16 v[100:103], v[174:177], v[214:217], v[100:103]
	v_mfma_f32_16x16x32_bf16 v[96:99], v[198:201], v[214:217], v[96:99]
	v_mfma_f32_16x16x32_bf16 v[84:87], v[174:177], v[222:225], v[84:87]
	v_mfma_f32_16x16x32_bf16 v[80:83], v[198:201], v[222:225], v[80:83]
	v_mfma_f32_16x16x32_bf16 v[68:71], v[174:177], v[232:235], v[68:71]
	v_mfma_f32_16x16x32_bf16 v[64:67], v[198:201], v[232:235], v[64:67]
	v_mfma_f32_16x16x32_bf16 v[116:119], v[194:197], v[210:213], v[116:119]
	v_mfma_f32_16x16x32_bf16 v[112:115], v[202:205], v[210:213], v[112:115]
	v_mfma_f32_16x16x32_bf16 v[100:103], v[194:197], v[218:221], v[100:103]
	v_mfma_f32_16x16x32_bf16 v[96:99], v[202:205], v[218:221], v[96:99]
	v_mfma_f32_16x16x32_bf16 v[84:87], v[194:197], v[228:231], v[84:87]
	v_mfma_f32_16x16x32_bf16 v[80:83], v[202:205], v[228:231], v[80:83]
	v_mfma_f32_16x16x32_bf16 v[68:71], v[194:197], v[236:239], v[68:71]
	v_mfma_f32_16x16x32_bf16 v[64:67], v[202:205], v[236:239], v[64:67]
	s_setprio 0
	s_barrier
	s_add_i32 s91, s92, s77
	v_lshl_add_u64 v[240:241], s[66:67], 0, v[130:131]
	s_mov_b32 m0, s91
	ds_read_b128 v[206:209], v190 offset:16384
	ds_read_b128 v[210:213], v190 offset:17408
	ds_read_b128 v[214:217], v190 offset:18432
	ds_read_b128 v[218:221], v190 offset:19456
	ds_read_b128 v[222:225], v190 offset:20480
	ds_read_b128 v[228:231], v190 offset:21504
	ds_read_b128 v[232:235], v190 offset:22528
	ds_read_b128 v[236:239], v190 offset:23552
	global_load_lds_dwordx4 v[240:241], off
	s_add_i32 m0, s91, 0x2000
	s_add_u32 vcc_lo, s66, 0x80000
	v_lshl_add_u64 v[242:243], s[66:67], 0, v[132:133]
	s_addc_u32 vcc_hi, s67, 0
	s_add_i32 s91, s93, s77
	global_load_lds_dwordx4 v[242:243], off
	v_lshl_add_u64 v[244:245], vcc, 0, v[130:131]
	s_mov_b32 m0, s91
	v_lshl_add_u64 v[246:247], s[72:73], 0, v[132:133]
	global_load_lds_dwordx4 v[244:245], off
	v_lshl_add_u64 v[244:245], vcc, 0, v[132:133]
	s_add_i32 m0, s91, 0x2000
	s_nop 0
	global_load_lds_dwordx4 v[244:245], off
	v_lshl_add_u64 v[244:245], s[72:73], 0, v[130:131]
	s_mov_b32 m0, s78
	s_nop 0
	global_load_lds_dwordx4 v[244:245], off
	s_mov_b32 m0, s79
	s_nop 0
	global_load_lds_dwordx4 v[246:247], off
	s_waitcnt vmcnt(8)
	s_waitcnt lgkmcnt(0)
	s_barrier
; #define PG8_STAGE(bufoff, gbase, voff) do { _Pragma("unroll") for (int _i = 0; _i < 2; ++_i) \
;         __builtin_amdgcn_global_load_lds((const unsigned*)((const char*)(gbase) + (voff)[_i]), (LAS unsigned*)(lds + (bufoff) + ldsw + _i * 8192), 16, 0, 0); } while (0)
; #define PG8_LDA(dst, b, h) do { _Pragma("unroll") for (int m = 0; m < 4; ++m) _Pragma("unroll") for (int k = 0; k < 2; ++k) dst[m][k] = *(const LAS bf16x8*)(lds + PG8_SA(b, h) + aoff + m * 2048 + k * 1024); } while (0)
; #define PG8_LDB(dst, b, h) do { _Pragma("unroll") for (int n = 0; n < 2; ++n) _Pragma("unroll") for (int k = 0; k < 2; ++k) dst[n][k] = *(const LAS bf16x8*)(lds + PG8_SB(b, h) + boff + n * 2048 + k * 1024); } while (0)
; #define PG8_MMA(ai, bj, At, Bt) do { __builtin_amdgcn_s_setprio(1); _Pragma("unroll") for (int m = 0; m < 4; ++m) _Pragma("unroll") for (int n = 0; n < 2; ++n) _Pragma("unroll") for (int k = 0; k < 2; ++k) \
;         acc[ai][bj][m][n] = __builtin_amdgcn_mfma_f32_16x16x32_bf16(Bt[n][k], At[m][k], acc[ai][bj][m][n], 0, 0, 0); __builtin_amdgcn_s_setprio(0); } while (0)
; #define PG8_WAIT_V(n) asm volatile("s_waitcnt vmcnt(" #n ")" ::: "memory")
; #define PG8_WAIT_L(n) asm volatile("s_waitcnt lgkmcnt(" #n ")" ::: "memory")
; #define PG8_BAR __builtin_amdgcn_s_barrier()
; #define PG8_SCHED __builtin_amdgcn_sched_barrier(0)
; template <class Epi, class Sched, bool ALIGN_EPI = true, bool SP2 = true>
; DI void gemm_phase(LAS unsigned char* lds, const Gemm g, const Sched& S, const Epi& E) {
;     ...
;             PG8_WAIT_V(8); PG8_WAIT_L(0); PG8_BAR; PG8_MMA(1, 0, At, B0); PG8_MMA(1, 1, At, B1); PG8_BAR; PG8_SCHED;
;             PG8_LDB(B0, 1, 0); PG8_LDB(B1, 1, 1); PG8_SCHED; PG8_LDA(At, 1, 0); PG8_STAGE(PG8_SA(0, 1), a2 + hstepA, voffA);
;             PG8_WAIT_V(8); PG8_WAIT_L(0); PG8_BAR; PG8_MMA(0, 0, At, B0); PG8_MMA(0, 1, At, B1); PG8_BAR; PG8_SCHED;
	s_setprio 1
	s_waitcnt lgkmcnt(0)
	v_mfma_f32_16x16x32_bf16 v[60:63], v[158:161], v[206:209], v[60:63]
	v_mfma_f32_16x16x32_bf16 v[56:59], v[166:169], v[206:209], v[56:59]
	v_mfma_f32_16x16x32_bf16 v[44:47], v[158:161], v[214:217], v[44:47]
	v_mfma_f32_16x16x32_bf16 v[40:43], v[166:169], v[214:217], v[40:43]
	v_mfma_f32_16x16x32_bf16 v[28:31], v[158:161], v[222:225], v[28:31]
	v_mfma_f32_16x16x32_bf16 v[24:27], v[166:169], v[222:225], v[24:27]
	v_mfma_f32_16x16x32_bf16 v[12:15], v[158:161], v[232:235], v[12:15]
	v_mfma_f32_16x16x32_bf16 v[8:11], v[166:169], v[232:235], v[8:11]
	v_mfma_f32_16x16x32_bf16 v[60:63], v[162:165], v[210:213], v[60:63]
	v_mfma_f32_16x16x32_bf16 v[56:59], v[170:173], v[210:213], v[56:59]
	v_mfma_f32_16x16x32_bf16 v[44:47], v[162:165], v[218:221], v[44:47]
	v_mfma_f32_16x16x32_bf16 v[40:43], v[170:173], v[218:221], v[40:43]
	v_mfma_f32_16x16x32_bf16 v[28:31], v[162:165], v[228:231], v[28:31]
	v_mfma_f32_16x16x32_bf16 v[24:27], v[170:173], v[228:231], v[24:27]
	v_mfma_f32_16x16x32_bf16 v[12:15], v[162:165], v[236:239], v[12:15]
	v_mfma_f32_16x16x32_bf16 v[8:11], v[170:173], v[236:239], v[8:11]
	s_setprio 0
	s_setprio 1
	v_mfma_f32_16x16x32_bf16 v[52:55], v[174:177], v[206:209], v[52:55]
	v_mfma_f32_16x16x32_bf16 v[48:51], v[198:201], v[206:209], v[48:51]
	v_mfma_f32_16x16x32_bf16 v[36:39], v[174:177], v[214:217], v[36:39]
	v_mfma_f32_16x16x32_bf16 v[32:35], v[198:201], v[214:217], v[32:35]
	v_mfma_f32_16x16x32_bf16 v[20:23], v[174:177], v[222:225], v[20:23]
	v_mfma_f32_16x16x32_bf16 v[16:19], v[198:201], v[222:225], v[16:19]
	v_mfma_f32_16x16x32_bf16 v[4:7], v[174:177], v[232:235], v[4:7]
	v_mfma_f32_16x16x32_bf16 v[0:3], v[198:201], v[232:235], v[0:3]
	v_mfma_f32_16x16x32_bf16 v[52:55], v[194:197], v[210:213], v[52:55]
	v_mfma_f32_16x16x32_bf16 v[48:51], v[202:205], v[210:213], v[48:51]
	v_mfma_f32_16x16x32_bf16 v[36:39], v[194:197], v[218:221], v[36:39]
	v_mfma_f32_16x16x32_bf16 v[32:35], v[202:205], v[218:221], v[32:35]
	v_mfma_f32_16x16x32_bf16 v[20:23], v[194:197], v[228:231], v[20:23]
	v_mfma_f32_16x16x32_bf16 v[16:19], v[202:205], v[228:231], v[16:19]
	v_mfma_f32_16x16x32_bf16 v[4:7], v[194:197], v[236:239], v[4:7]
	v_mfma_f32_16x16x32_bf16 v[0:3], v[202:205], v[236:239], v[0:3]
	s_setprio 0
	s_barrier
	s_add_i32 s91, 0, 0x18000
	s_add_i32 vcc_lo, 0, 0x1c000
	v_add_u32_e32 v170, s91, v178
	v_add_u32_e32 v193, vcc_lo, v178
	ds_read_b128 v[158:161], v170
	ds_read_b128 v[162:165], v170 offset:1024
	ds_read_b128 v[166:169], v170 offset:2048
	ds_read_b128 v[170:173], v170 offset:3072
	ds_read_b128 v[174:177], v193
	ds_read_b128 v[194:197], v193 offset:1024
	ds_read_b128 v[198:201], v193 offset:2048
	ds_read_b128 v[202:205], v193 offset:3072
	s_add_u32 s72, s72, 0x80000
	s_addc_u32 s73, s73, 0
	s_mov_b32 m0, s81
	v_lshl_add_u64 v[248:249], s[72:73], 0, v[130:131]
	ds_read_b128 v[206:209], v190 offset:32768
	ds_read_b128 v[210:213], v190 offset:33792
	ds_read_b128 v[214:217], v190 offset:34816
	ds_read_b128 v[218:221], v190 offset:35840
	ds_read_b128 v[222:225], v190 offset:36864
	ds_read_b128 v[228:231], v190 offset:37888
	ds_read_b128 v[232:235], v190 offset:38912
	ds_read_b128 v[236:239], v190 offset:39936
	global_load_lds_dwordx4 v[248:249], off
	v_lshl_add_u64 v[248:249], s[72:73], 0, v[132:133]
	s_mov_b32 m0, s84
	s_nop 0
	global_load_lds_dwordx4 v[248:249], off
	s_waitcnt vmcnt(8)
	s_waitcnt lgkmcnt(0)
	s_barrier
	s_setprio 1
	s_waitcnt lgkmcnt(0)
	v_mfma_f32_16x16x32_bf16 v[124:127], v[158:161], v[206:209], v[124:127]
	v_mfma_f32_16x16x32_bf16 v[120:123], v[166:169], v[206:209], v[120:123]
	v_mfma_f32_16x16x32_bf16 v[108:111], v[158:161], v[214:217], v[108:111]
	v_mfma_f32_16x16x32_bf16 v[104:107], v[166:169], v[214:217], v[104:107]
	v_mfma_f32_16x16x32_bf16 v[92:95], v[158:161], v[222:225], v[92:95]
	v_mfma_f32_16x16x32_bf16 v[88:91], v[166:169], v[222:225], v[88:91]
	v_mfma_f32_16x16x32_bf16 v[76:79], v[158:161], v[232:235], v[76:79]
	v_mfma_f32_16x16x32_bf16 v[72:75], v[166:169], v[232:235], v[72:75]
	v_mfma_f32_16x16x32_bf16 v[124:127], v[162:165], v[210:213], v[124:127]
	v_mfma_f32_16x16x32_bf16 v[120:123], v[170:173], v[210:213], v[120:123]
	v_mfma_f32_16x16x32_bf16 v[108:111], v[162:165], v[218:221], v[108:111]
	v_mfma_f32_16x16x32_bf16 v[104:107], v[170:173], v[218:221], v[104:107]
	v_mfma_f32_16x16x32_bf16 v[92:95], v[162:165], v[228:231], v[92:95]
	v_mfma_f32_16x16x32_bf16 v[88:91], v[170:173], v[228:231], v[88:91]
	v_mfma_f32_16x16x32_bf16 v[76:79], v[162:165], v[236:239], v[76:79]
	v_mfma_f32_16x16x32_bf16 v[72:75], v[170:173], v[236:239], v[72:75]
	s_setprio 0
	s_setprio 1
	v_mfma_f32_16x16x32_bf16 v[116:119], v[174:177], v[206:209], v[116:119]
	v_mfma_f32_16x16x32_bf16 v[112:115], v[198:201], v[206:209], v[112:115]
	v_mfma_f32_16x16x32_bf16 v[100:103], v[174:177], v[214:217], v[100:103]
	v_mfma_f32_16x16x32_bf16 v[96:99], v[198:201], v[214:217], v[96:99]
	v_mfma_f32_16x16x32_bf16 v[84:87], v[174:177], v[222:225], v[84:87]
	v_mfma_f32_16x16x32_bf16 v[80:83], v[198:201], v[222:225], v[80:83]
	v_mfma_f32_16x16x32_bf16 v[68:71], v[174:177], v[232:235], v[68:71]
	v_mfma_f32_16x16x32_bf16 v[64:67], v[198:201], v[232:235], v[64:67]
	v_mfma_f32_16x16x32_bf16 v[116:119], v[194:197], v[210:213], v[116:119]
	v_mfma_f32_16x16x32_bf16 v[112:115], v[202:205], v[210:213], v[112:115]
	v_mfma_f32_16x16x32_bf16 v[100:103], v[194:197], v[218:221], v[100:103]
	v_mfma_f32_16x16x32_bf16 v[96:99], v[202:205], v[218:221], v[96:99]
	v_mfma_f32_16x16x32_bf16 v[84:87], v[194:197], v[228:231], v[84:87]
	v_mfma_f32_16x16x32_bf16 v[80:83], v[202:205], v[228:231], v[80:83]
	v_mfma_f32_16x16x32_bf16 v[68:71], v[194:197], v[236:239], v[68:71]
	v_mfma_f32_16x16x32_bf16 v[64:67], v[202:205], v[236:239], v[64:67]
	s_setprio 0
	s_barrier
; #define PG8_STAGE(bufoff, gbase, voff) do { _Pragma("unroll") for (int _i = 0; _i < 2; ++_i) \
;         __builtin_amdgcn_global_load_lds((const unsigned*)((const char*)(gbase) + (voff)[_i]), (LAS unsigned*)(lds + (bufoff) + ldsw + _i * 8192), 16, 0, 0); } while (0)
; #define PG8_LDA(dst, b, h) do { _Pragma("unroll") for (int m = 0; m < 4; ++m) _Pragma("unroll") for (int k = 0; k < 2; ++k) dst[m][k] = *(const LAS bf16x8*)(lds + PG8_SA(b, h) + aoff + m * 2048 + k * 1024); } while (0)
; #define PG8_MMA(ai, bj, At, Bt) do { __builtin_amdgcn_s_setprio(1); _Pragma("unroll") for (int m = 0; m < 4; ++m) _Pragma("unroll") for (int n = 0; n < 2; ++n) _Pragma("unroll") for (int k = 0; k < 2; ++k) \
;         acc[ai][bj][m][n] = __builtin_amdgcn_mfma_f32_16x16x32_bf16(Bt[n][k], At[m][k], acc[ai][bj][m][n], 0, 0, 0); __builtin_amdgcn_s_setprio(0); } while (0)
; #define PG8_WAIT_V(n) asm volatile("s_waitcnt vmcnt(" #n ")" ::: "memory")
; #define PG8_WAIT_L(n) asm volatile("s_waitcnt lgkmcnt(" #n ")" ::: "memory")
; #define PG8_BAR __builtin_amdgcn_s_barrier()
; #define PG8_SCHED __builtin_amdgcn_sched_barrier(0)
; template <class Epi, class Sched, bool ALIGN_EPI = true, bool SP2 = true>
; DI void gemm_phase(LAS unsigned char* lds, const Gemm g, const Sched& S, const Epi& E) {
;     ...
;         for (int t = 0; t < nt; t += 2) {
;             const bool last = (t == nt - 2);
;     ...
;             PG8_LDA(At, 1, 1); PG8_STAGE(PG8_SB(1, 0), b3, voffB); PG8_STAGE(PG8_SB(1, 1), b3 + hstepB, voffB); PG8_STAGE(PG8_SA(1, 0), a3, voffA);
;             PG8_WAIT_V(8); PG8_WAIT_L(0); PG8_BAR; PG8_MMA(1, 0, At, B0); PG8_MMA(1, 1, At, B1); PG8_BAR; PG8_SCHED;
;         }
	s_add_i32 s72, s91, s77
	v_lshl_add_u64 v[240:241], v[240:241], 0, s[42:43]
	s_mov_b32 m0, s72
	ds_read_b128 v[206:209], v190 offset:49152
	ds_read_b128 v[210:213], v190 offset:50176
	ds_read_b128 v[214:217], v190 offset:51200
	ds_read_b128 v[218:221], v190 offset:52224
	ds_read_b128 v[222:225], v190 offset:53248
	ds_read_b128 v[228:231], v190 offset:54272
	ds_read_b128 v[232:235], v190 offset:55296
	ds_read_b128 v[236:239], v190 offset:56320
	global_load_lds_dwordx4 v[240:241], off
	s_add_i32 m0, s72, 0x2000
	s_add_u32 s66, s66, 0x80080
	v_lshl_add_u64 v[240:241], v[242:243], 0, s[42:43]
	s_addc_u32 s67, s67, 0
	s_add_i32 s72, vcc_lo, s77
	global_load_lds_dwordx4 v[240:241], off
	v_lshl_add_u64 v[240:241], s[66:67], 0, v[130:131]
	s_mov_b32 m0, s72
	s_nop 0
	global_load_lds_dwordx4 v[240:241], off
	v_lshl_add_u64 v[240:241], s[66:67], 0, v[132:133]
	s_add_i32 m0, s72, 0x2000
	s_nop 0
	global_load_lds_dwordx4 v[240:241], off
	v_lshl_add_u64 v[240:241], v[244:245], 0, s[42:43]
	s_mov_b32 m0, s86
	s_nop 0
	global_load_lds_dwordx4 v[240:241], off
	v_lshl_add_u64 v[240:241], v[246:247], 0, s[42:43]
	s_mov_b32 m0, s87
	s_nop 0
	global_load_lds_dwordx4 v[240:241], off
	s_waitcnt vmcnt(8)
	s_waitcnt lgkmcnt(0)
	s_barrier
	s_setprio 1
	s_waitcnt lgkmcnt(0)
	v_mfma_f32_16x16x32_bf16 v[60:63], v[158:161], v[206:209], v[60:63]
	v_mfma_f32_16x16x32_bf16 v[56:59], v[166:169], v[206:209], v[56:59]
	v_mfma_f32_16x16x32_bf16 v[44:47], v[158:161], v[214:217], v[44:47]
	v_mfma_f32_16x16x32_bf16 v[40:43], v[166:169], v[214:217], v[40:43]
	v_mfma_f32_16x16x32_bf16 v[28:31], v[158:161], v[222:225], v[28:31]
	v_mfma_f32_16x16x32_bf16 v[24:27], v[166:169], v[222:225], v[24:27]
	v_mfma_f32_16x16x32_bf16 v[12:15], v[158:161], v[232:235], v[12:15]
	v_mfma_f32_16x16x32_bf16 v[8:11], v[166:169], v[232:235], v[8:11]
	v_mfma_f32_16x16x32_bf16 v[60:63], v[162:165], v[210:213], v[60:63]
	v_mfma_f32_16x16x32_bf16 v[56:59], v[170:173], v[210:213], v[56:59]
	v_mfma_f32_16x16x32_bf16 v[44:47], v[162:165], v[218:221], v[44:47]
	v_mfma_f32_16x16x32_bf16 v[40:43], v[170:173], v[218:221], v[40:43]
	v_mfma_f32_16x16x32_bf16 v[28:31], v[162:165], v[228:231], v[28:31]
	v_mfma_f32_16x16x32_bf16 v[24:27], v[170:173], v[228:231], v[24:27]
	v_mfma_f32_16x16x32_bf16 v[12:15], v[162:165], v[236:239], v[12:15]
	v_mfma_f32_16x16x32_bf16 v[8:11], v[170:173], v[236:239], v[8:11]
	s_setprio 0
	s_setprio 1
	v_mfma_f32_16x16x32_bf16 v[52:55], v[174:177], v[206:209], v[52:55]
	v_mfma_f32_16x16x32_bf16 v[48:51], v[198:201], v[206:209], v[48:51]
	v_mfma_f32_16x16x32_bf16 v[36:39], v[174:177], v[214:217], v[36:39]
	v_mfma_f32_16x16x32_bf16 v[32:35], v[198:201], v[214:217], v[32:35]
	v_mfma_f32_16x16x32_bf16 v[20:23], v[174:177], v[222:225], v[20:23]
	v_mfma_f32_16x16x32_bf16 v[16:19], v[198:201], v[222:225], v[16:19]
	v_mfma_f32_16x16x32_bf16 v[4:7], v[174:177], v[232:235], v[4:7]
	v_mfma_f32_16x16x32_bf16 v[0:3], v[198:201], v[232:235], v[0:3]
	v_mfma_f32_16x16x32_bf16 v[52:55], v[194:197], v[210:213], v[52:55]
	v_mfma_f32_16x16x32_bf16 v[48:51], v[202:205], v[210:213], v[48:51]
	v_mfma_f32_16x16x32_bf16 v[36:39], v[194:197], v[218:221], v[36:39]
	v_mfma_f32_16x16x32_bf16 v[32:35], v[202:205], v[218:221], v[32:35]
	v_mfma_f32_16x16x32_bf16 v[20:23], v[194:197], v[228:231], v[20:23]
	v_mfma_f32_16x16x32_bf16 v[16:19], v[202:205], v[228:231], v[16:19]
	v_mfma_f32_16x16x32_bf16 v[4:7], v[194:197], v[236:239], v[4:7]
	v_mfma_f32_16x16x32_bf16 v[0:3], v[202:205], v[236:239], v[0:3]
	s_setprio 0
	s_add_i32 s97, s97, 2
	s_add_u32 s10, s10, 0x100
	s_addc_u32 s11, s11, 0
	s_add_u32 s95, s95, 0x100
	s_addc_u32 s96, s96, 0
	s_cmp_gt_u32 s97, 29
	s_barrier
	s_cbranch_scc0 .LBB0_773
	s_and_b64 vcc, exec, s[44:45]
	s_cbranch_vccz .LBB0_776
	s_barrier

; #define PG8_STAGE(bufoff, gbase, voff) do { _Pragma("unroll") for (int _i = 0; _i < 2; ++_i) \
;         __builtin_amdgcn_global_load_lds((const unsigned*)((const char*)(gbase) + (voff)[_i]), (LAS unsigned*)(lds + (bufoff) + ldsw + _i * 8192), 16, 0, 0); } while (0)
; #define PG8_LDA(dst, b, h) do { _Pragma("unroll") for (int m = 0; m < 4; ++m) _Pragma("unroll") for (int k = 0; k < 2; ++k) dst[m][k] = *(const LAS bf16x8*)(lds + PG8_SA(b, h) + aoff + m * 2048 + k * 1024); } while (0)
; #define PG8_LDB(dst, b, h) do { _Pragma("unroll") for (int n = 0; n < 2; ++n) _Pragma("unroll") for (int k = 0; k < 2; ++k) dst[n][k] = *(const LAS bf16x8*)(lds + PG8_SB(b, h) + boff + n * 2048 + k * 1024); } while (0)
; #define PG8_MMA(ai, bj, At, Bt) do { __builtin_amdgcn_s_setprio(1); _Pragma("unroll") for (int m = 0; m < 4; ++m) _Pragma("unroll") for (int n = 0; n < 2; ++n) _Pragma("unroll") for (int k = 0; k < 2; ++k) \
;         acc[ai][bj][m][n] = __builtin_amdgcn_mfma_f32_16x16x32_bf16(Bt[n][k], At[m][k], acc[ai][bj][m][n], 0, 0, 0); __builtin_amdgcn_s_setprio(0); } while (0)
; #define PG8_WAIT_V(n) asm volatile("s_waitcnt vmcnt(" #n ")" ::: "memory")
; #define PG8_WAIT_L(n) asm volatile("s_waitcnt lgkmcnt(" #n ")" ::: "memory")
; #define PG8_BAR __builtin_amdgcn_s_barrier()
; #define PG8_SCHED __builtin_amdgcn_sched_barrier(0)
; template <class Epi, class Sched, bool ALIGN_EPI = true, bool SP2 = true>
; DI void gemm_phase(LAS unsigned char* lds, const Gemm g, const Sched& S, const Epi& E) {
;     ...
;         for (int t = 0; t < nt; t += 2) {
;             const bool last = (t == nt - 2);
;             const char* a1 = cA + (size_t)(t + 1) * kstep;
;             const char* a2 = last ? nA : cA + (size_t)(t + 2) * kstep; const char* b2 = last ? nB : cB + (size_t)(t + 2) * kstep;
;             const char* a3 = a2 + kstep; const char* b3 = b2 + kstep;
;             PG8_LDB(B0, 0, 0); PG8_LDB(B1, 0, 1); PG8_SCHED; PG8_LDA(At, 0, 0); PG8_STAGE(PG8_SA(1, 1), a1 + hstepA, voffA);
;             PG8_WAIT_V(8); PG8_WAIT_L(0); PG8_BAR; PG8_MMA(0, 0, At, B0); PG8_MMA(0, 1, At, B1); PG8_BAR; PG8_SCHED;
;             PG8_LDA(At, 0, 1); PG8_STAGE(PG8_SB(0, 0), b2, voffB); PG8_STAGE(PG8_SB(0, 1), b2 + hstepB, voffB); PG8_STAGE(PG8_SA(0, 0), a2, voffA);
.LBB0_909:
	ds_read_b128 v[128:131], v168
	ds_read_b128 v[132:135], v168 offset:1024
	ds_read_b128 v[154:157], v168 offset:2048
	ds_read_b128 v[158:161], v168 offset:3072
	ds_read_b128 v[176:179], v169
	ds_read_b128 v[180:183], v169 offset:1024
	ds_read_b128 v[184:187], v169 offset:2048
	ds_read_b128 v[188:191], v169 offset:3072
	s_add_u32 s18, s16, 0xfffc0080
	s_addc_u32 s19, s17, -1
	s_cmp_eq_u32 s72, 12
	s_cselect_b32 s69, s13, s19
	s_cselect_b32 s68, s15, s18
	s_cselect_b32 s19, s61, s71
	s_cselect_b32 s18, s63, s70
	v_lshl_add_u64 v[224:225], s[16:17], 0, v[146:147]
	s_add_i32 m0, s57, 0xc000
	ds_read_b128 v[192:195], v170
	ds_read_b128 v[196:199], v170 offset:1024
	ds_read_b128 v[200:203], v170 offset:2048
	ds_read_b128 v[204:207], v170 offset:3072
	ds_read_b128 v[208:211], v170 offset:4096
	ds_read_b128 v[212:215], v170 offset:5120
	ds_read_b128 v[216:219], v170 offset:6144
	ds_read_b128 v[220:223], v170 offset:7168
	global_load_lds_dwordx4 v[224:225], off
	v_lshl_add_u64 v[224:225], s[16:17], 0, v[148:149]
	s_add_i32 m0, s57, 0xe000
	s_nop 0
	global_load_lds_dwordx4 v[224:225], off
	s_waitcnt vmcnt(8)
	s_waitcnt lgkmcnt(0)
	s_barrier
	s_setprio 1
	s_waitcnt lgkmcnt(0)
	v_mfma_f32_16x16x32_bf16 v[124:127], v[128:131], v[192:195], v[124:127]
	v_mfma_f32_16x16x32_bf16 v[120:123], v[154:157], v[192:195], v[120:123]
	v_mfma_f32_16x16x32_bf16 v[108:111], v[128:131], v[200:203], v[108:111]
	v_mfma_f32_16x16x32_bf16 v[104:107], v[154:157], v[200:203], v[104:107]
	v_mfma_f32_16x16x32_bf16 v[92:95], v[128:131], v[208:211], v[92:95]
	v_mfma_f32_16x16x32_bf16 v[88:91], v[154:157], v[208:211], v[88:91]
	v_mfma_f32_16x16x32_bf16 v[76:79], v[128:131], v[216:219], v[76:79]
	v_mfma_f32_16x16x32_bf16 v[72:75], v[154:157], v[216:219], v[72:75]
	v_mfma_f32_16x16x32_bf16 v[124:127], v[132:135], v[196:199], v[124:127]
	v_mfma_f32_16x16x32_bf16 v[120:123], v[158:161], v[196:199], v[120:123]
	v_mfma_f32_16x16x32_bf16 v[108:111], v[132:135], v[204:207], v[108:111]
	v_mfma_f32_16x16x32_bf16 v[104:107], v[158:161], v[204:207], v[104:107]
	v_mfma_f32_16x16x32_bf16 v[92:95], v[132:135], v[212:215], v[92:95]
	v_mfma_f32_16x16x32_bf16 v[88:91], v[158:161], v[212:215], v[88:91]
	v_mfma_f32_16x16x32_bf16 v[76:79], v[132:135], v[220:223], v[76:79]
	v_mfma_f32_16x16x32_bf16 v[72:75], v[158:161], v[220:223], v[72:75]
	s_setprio 0
	s_setprio 1
	v_mfma_f32_16x16x32_bf16 v[116:119], v[176:179], v[192:195], v[116:119]
	v_mfma_f32_16x16x32_bf16 v[112:115], v[184:187], v[192:195], v[112:115]
	v_mfma_f32_16x16x32_bf16 v[100:103], v[176:179], v[200:203], v[100:103]
	v_mfma_f32_16x16x32_bf16 v[96:99], v[184:187], v[200:203], v[96:99]
	v_mfma_f32_16x16x32_bf16 v[84:87], v[176:179], v[208:211], v[84:87]
	v_mfma_f32_16x16x32_bf16 v[80:83], v[184:187], v[208:211], v[80:83]
	v_mfma_f32_16x16x32_bf16 v[68:71], v[176:179], v[216:219], v[68:71]
	v_mfma_f32_16x16x32_bf16 v[64:67], v[184:187], v[216:219], v[64:67]
	v_mfma_f32_16x16x32_bf16 v[116:119], v[180:183], v[196:199], v[116:119]
	v_mfma_f32_16x16x32_bf16 v[112:115], v[188:191], v[196:199], v[112:115]
	v_mfma_f32_16x16x32_bf16 v[100:103], v[180:183], v[204:207], v[100:103]
	v_mfma_f32_16x16x32_bf16 v[96:99], v[188:191], v[204:207], v[96:99]
	v_mfma_f32_16x16x32_bf16 v[84:87], v[180:183], v[212:215], v[84:87]
	v_mfma_f32_16x16x32_bf16 v[80:83], v[188:191], v[212:215], v[80:83]
	v_mfma_f32_16x16x32_bf16 v[68:71], v[180:183], v[220:223], v[68:71]
	v_mfma_f32_16x16x32_bf16 v[64:67], v[188:191], v[220:223], v[64:67]
	s_setprio 0
	s_barrier
	s_add_i32 s73, s95, s3
	v_lshl_add_u64 v[224:225], s[18:19], 0, v[138:139]
	s_mov_b32 m0, s73
	ds_read_b128 v[192:195], v170 offset:16384
	ds_read_b128 v[196:199], v170 offset:17408
	ds_read_b128 v[200:203], v170 offset:18432
	ds_read_b128 v[204:207], v170 offset:19456
	ds_read_b128 v[208:211], v170 offset:20480
	ds_read_b128 v[212:215], v170 offset:21504
	ds_read_b128 v[216:219], v170 offset:22528
	ds_read_b128 v[220:223], v170 offset:23552
	global_load_lds_dwordx4 v[224:225], off
	s_add_i32 m0, s73, 0x2000
	s_add_u32 s74, s18, 0x40000
	v_lshl_add_u64 v[228:229], s[18:19], 0, v[142:143]
	s_addc_u32 s75, s19, 0
	s_add_i32 s73, s96, s3
	global_load_lds_dwordx4 v[228:229], off
	v_lshl_add_u64 v[230:231], s[74:75], 0, v[138:139]
	s_mov_b32 m0, s73
	v_lshl_add_u64 v[232:233], s[68:69], 0, v[140:141]
	global_load_lds_dwordx4 v[230:231], off
	v_lshl_add_u64 v[230:231], s[74:75], 0, v[142:143]
	s_add_i32 m0, s73, 0x2000
	s_nop 0
	global_load_lds_dwordx4 v[230:231], off
	v_lshl_add_u64 v[230:231], s[68:69], 0, v[136:137]
	s_mov_b32 m0, s57
	s_nop 0
	global_load_lds_dwordx4 v[230:231], off
	s_mov_b32 m0, s76
	s_nop 0
	global_load_lds_dwordx4 v[232:233], off
	s_waitcnt vmcnt(8)
	s_waitcnt lgkmcnt(0)
	s_barrier
; #define PG8_STAGE(bufoff, gbase, voff) do { _Pragma("unroll") for (int _i = 0; _i < 2; ++_i) \
;         __builtin_amdgcn_global_load_lds((const unsigned*)((const char*)(gbase) + (voff)[_i]), (LAS unsigned*)(lds + (bufoff) + ldsw + _i * 8192), 16, 0, 0); } while (0)
; #define PG8_LDA(dst, b, h) do { _Pragma("unroll") for (int m = 0; m < 4; ++m) _Pragma("unroll") for (int k = 0; k < 2; ++k) dst[m][k] = *(const LAS bf16x8*)(lds + PG8_SA(b, h) + aoff + m * 2048 + k * 1024); } while (0)
; #define PG8_LDB(dst, b, h) do { _Pragma("unroll") for (int n = 0; n < 2; ++n) _Pragma("unroll") for (int k = 0; k < 2; ++k) dst[n][k] = *(const LAS bf16x8*)(lds + PG8_SB(b, h) + boff + n * 2048 + k * 1024); } while (0)
; #define PG8_MMA(ai, bj, At, Bt) do { __builtin_amdgcn_s_setprio(1); _Pragma("unroll") for (int m = 0; m < 4; ++m) _Pragma("unroll") for (int n = 0; n < 2; ++n) _Pragma("unroll") for (int k = 0; k < 2; ++k) \
;         acc[ai][bj][m][n] = __builtin_amdgcn_mfma_f32_16x16x32_bf16(Bt[n][k], At[m][k], acc[ai][bj][m][n], 0, 0, 0); __builtin_amdgcn_s_setprio(0); } while (0)
; #define PG8_WAIT_V(n) asm volatile("s_waitcnt vmcnt(" #n ")" ::: "memory")
; #define PG8_WAIT_L(n) asm volatile("s_waitcnt lgkmcnt(" #n ")" ::: "memory")
; #define PG8_BAR __builtin_amdgcn_s_barrier()
; #define PG8_SCHED __builtin_amdgcn_sched_barrier(0)
; template <class Epi, class Sched, bool ALIGN_EPI = true, bool SP2 = true>
; DI void gemm_phase(LAS unsigned char* lds, const Gemm g, const Sched& S, const Epi& E) {
;     ...
;             PG8_WAIT_V(8); PG8_WAIT_L(0); PG8_BAR; PG8_MMA(1, 0, At, B0); PG8_MMA(1, 1, At, B1); PG8_BAR; PG8_SCHED;
;             PG8_LDB(B0, 1, 0); PG8_LDB(B1, 1, 1); PG8_SCHED; PG8_LDA(At, 1, 0); PG8_STAGE(PG8_SA(0, 1), a2 + hstepA, voffA);
;             PG8_WAIT_V(8); PG8_WAIT_L(0); PG8_BAR; PG8_MMA(0, 0, At, B0); PG8_MMA(0, 1, At, B1); PG8_BAR; PG8_SCHED;
	s_setprio 1
	s_waitcnt lgkmcnt(0)
	v_mfma_f32_16x16x32_bf16 v[60:63], v[128:131], v[192:195], v[60:63]
	v_mfma_f32_16x16x32_bf16 v[56:59], v[154:157], v[192:195], v[56:59]
	v_mfma_f32_16x16x32_bf16 v[44:47], v[128:131], v[200:203], v[44:47]
	v_mfma_f32_16x16x32_bf16 v[40:43], v[154:157], v[200:203], v[40:43]
	v_mfma_f32_16x16x32_bf16 v[28:31], v[128:131], v[208:211], v[28:31]
	v_mfma_f32_16x16x32_bf16 v[24:27], v[154:157], v[208:211], v[24:27]
	v_mfma_f32_16x16x32_bf16 v[12:15], v[128:131], v[216:219], v[12:15]
	v_mfma_f32_16x16x32_bf16 v[8:11], v[154:157], v[216:219], v[8:11]
	v_mfma_f32_16x16x32_bf16 v[60:63], v[132:135], v[196:199], v[60:63]
	v_mfma_f32_16x16x32_bf16 v[56:59], v[158:161], v[196:199], v[56:59]
	v_mfma_f32_16x16x32_bf16 v[44:47], v[132:135], v[204:207], v[44:47]
	v_mfma_f32_16x16x32_bf16 v[40:43], v[158:161], v[204:207], v[40:43]
	v_mfma_f32_16x16x32_bf16 v[28:31], v[132:135], v[212:215], v[28:31]
	v_mfma_f32_16x16x32_bf16 v[24:27], v[158:161], v[212:215], v[24:27]
	v_mfma_f32_16x16x32_bf16 v[12:15], v[132:135], v[220:223], v[12:15]
	v_mfma_f32_16x16x32_bf16 v[8:11], v[158:161], v[220:223], v[8:11]
	s_setprio 0
	s_setprio 1
	v_mfma_f32_16x16x32_bf16 v[52:55], v[176:179], v[192:195], v[52:55]
	v_mfma_f32_16x16x32_bf16 v[48:51], v[184:187], v[192:195], v[48:51]
	v_mfma_f32_16x16x32_bf16 v[36:39], v[176:179], v[200:203], v[36:39]
	v_mfma_f32_16x16x32_bf16 v[32:35], v[184:187], v[200:203], v[32:35]
	v_mfma_f32_16x16x32_bf16 v[20:23], v[176:179], v[208:211], v[20:23]
	v_mfma_f32_16x16x32_bf16 v[16:19], v[184:187], v[208:211], v[16:19]
	v_mfma_f32_16x16x32_bf16 v[4:7], v[176:179], v[216:219], v[4:7]
	v_mfma_f32_16x16x32_bf16 v[0:3], v[184:187], v[216:219], v[0:3]
	v_mfma_f32_16x16x32_bf16 v[52:55], v[180:183], v[196:199], v[52:55]
	v_mfma_f32_16x16x32_bf16 v[48:51], v[188:191], v[196:199], v[48:51]
	v_mfma_f32_16x16x32_bf16 v[36:39], v[180:183], v[204:207], v[36:39]
	v_mfma_f32_16x16x32_bf16 v[32:35], v[188:191], v[204:207], v[32:35]
	v_mfma_f32_16x16x32_bf16 v[20:23], v[180:183], v[212:215], v[20:23]
	v_mfma_f32_16x16x32_bf16 v[16:19], v[188:191], v[212:215], v[16:19]
	v_mfma_f32_16x16x32_bf16 v[4:7], v[180:183], v[220:223], v[4:7]
	v_mfma_f32_16x16x32_bf16 v[0:3], v[188:191], v[220:223], v[0:3]
	s_setprio 0
	s_barrier
	s_add_i32 s73, 0, 0x18000
	v_add_u32_e32 v144, s73, v164
	s_add_i32 s74, 0, 0x1c000
	ds_read_b128 v[128:131], v144
	ds_read_b128 v[132:135], v144 offset:1024
	ds_read_b128 v[154:157], v144 offset:2048
	ds_read_b128 v[158:161], v144 offset:3072
	v_add_u32_e32 v144, s74, v164
	ds_read_b128 v[176:179], v144
	ds_read_b128 v[180:183], v144 offset:1024
	ds_read_b128 v[184:187], v144 offset:2048
	ds_read_b128 v[188:191], v144 offset:3072
	s_add_u32 s68, s68, 0x40000
	s_addc_u32 s69, s69, 0
	s_mov_b32 m0, s77
	v_lshl_add_u64 v[234:235], s[68:69], 0, v[136:137]
	ds_read_b128 v[192:195], v170 offset:32768
	ds_read_b128 v[196:199], v170 offset:33792
	ds_read_b128 v[200:203], v170 offset:34816
	ds_read_b128 v[204:207], v170 offset:35840
	ds_read_b128 v[208:211], v170 offset:36864
	ds_read_b128 v[212:215], v170 offset:37888
	ds_read_b128 v[216:219], v170 offset:38912
	ds_read_b128 v[220:223], v170 offset:39936
	global_load_lds_dwordx4 v[234:235], off
	v_lshl_add_u64 v[234:235], s[68:69], 0, v[140:141]
	s_mov_b32 m0, s78
	s_nop 0
	global_load_lds_dwordx4 v[234:235], off
	s_waitcnt vmcnt(8)
	s_waitcnt lgkmcnt(0)
	s_barrier
	s_setprio 1
	s_waitcnt lgkmcnt(0)
	v_mfma_f32_16x16x32_bf16 v[124:127], v[128:131], v[192:195], v[124:127]
	v_mfma_f32_16x16x32_bf16 v[120:123], v[154:157], v[192:195], v[120:123]
	v_mfma_f32_16x16x32_bf16 v[108:111], v[128:131], v[200:203], v[108:111]
	v_mfma_f32_16x16x32_bf16 v[104:107], v[154:157], v[200:203], v[104:107]
	v_mfma_f32_16x16x32_bf16 v[92:95], v[128:131], v[208:211], v[92:95]
	v_mfma_f32_16x16x32_bf16 v[88:91], v[154:157], v[208:211], v[88:91]
	v_mfma_f32_16x16x32_bf16 v[76:79], v[128:131], v[216:219], v[76:79]
	v_mfma_f32_16x16x32_bf16 v[72:75], v[154:157], v[216:219], v[72:75]
	v_mfma_f32_16x16x32_bf16 v[124:127], v[132:135], v[196:199], v[124:127]
	v_mfma_f32_16x16x32_bf16 v[120:123], v[158:161], v[196:199], v[120:123]
	v_mfma_f32_16x16x32_bf16 v[108:111], v[132:135], v[204:207], v[108:111]
	v_mfma_f32_16x16x32_bf16 v[104:107], v[158:161], v[204:207], v[104:107]
	v_mfma_f32_16x16x32_bf16 v[92:95], v[132:135], v[212:215], v[92:95]
	v_mfma_f32_16x16x32_bf16 v[88:91], v[158:161], v[212:215], v[88:91]
	v_mfma_f32_16x16x32_bf16 v[76:79], v[132:135], v[220:223], v[76:79]
	v_mfma_f32_16x16x32_bf16 v[72:75], v[158:161], v[220:223], v[72:75]
	s_setprio 0
	s_setprio 1
	v_mfma_f32_16x16x32_bf16 v[116:119], v[176:179], v[192:195], v[116:119]
	v_mfma_f32_16x16x32_bf16 v[112:115], v[184:187], v[192:195], v[112:115]
	v_mfma_f32_16x16x32_bf16 v[100:103], v[176:179], v[200:203], v[100:103]
	v_mfma_f32_16x16x32_bf16 v[96:99], v[184:187], v[200:203], v[96:99]
	v_mfma_f32_16x16x32_bf16 v[84:87], v[176:179], v[208:211], v[84:87]
	v_mfma_f32_16x16x32_bf16 v[80:83], v[184:187], v[208:211], v[80:83]
	v_mfma_f32_16x16x32_bf16 v[68:71], v[176:179], v[216:219], v[68:71]
	v_mfma_f32_16x16x32_bf16 v[64:67], v[184:187], v[216:219], v[64:67]
	v_mfma_f32_16x16x32_bf16 v[116:119], v[180:183], v[196:199], v[116:119]
	v_mfma_f32_16x16x32_bf16 v[112:115], v[188:191], v[196:199], v[112:115]
	v_mfma_f32_16x16x32_bf16 v[100:103], v[180:183], v[204:207], v[100:103]
	v_mfma_f32_16x16x32_bf16 v[96:99], v[188:191], v[204:207], v[96:99]
	v_mfma_f32_16x16x32_bf16 v[84:87], v[180:183], v[212:215], v[84:87]
	v_mfma_f32_16x16x32_bf16 v[80:83], v[188:191], v[212:215], v[80:83]
	v_mfma_f32_16x16x32_bf16 v[68:71], v[180:183], v[220:223], v[68:71]
	v_mfma_f32_16x16x32_bf16 v[64:67], v[188:191], v[220:223], v[64:67]
	s_setprio 0
	s_barrier
; #define PG8_STAGE(bufoff, gbase, voff) do { _Pragma("unroll") for (int _i = 0; _i < 2; ++_i) \
;         __builtin_amdgcn_global_load_lds((const unsigned*)((const char*)(gbase) + (voff)[_i]), (LAS unsigned*)(lds + (bufoff) + ldsw + _i * 8192), 16, 0, 0); } while (0)
; #define PG8_LDA(dst, b, h) do { _Pragma("unroll") for (int m = 0; m < 4; ++m) _Pragma("unroll") for (int k = 0; k < 2; ++k) dst[m][k] = *(const LAS bf16x8*)(lds + PG8_SA(b, h) + aoff + m * 2048 + k * 1024); } while (0)
; #define PG8_MMA(ai, bj, At, Bt) do { __builtin_amdgcn_s_setprio(1); _Pragma("unroll") for (int m = 0; m < 4; ++m) _Pragma("unroll") for (int n = 0; n < 2; ++n) _Pragma("unroll") for (int k = 0; k < 2; ++k) \
;         acc[ai][bj][m][n] = __builtin_amdgcn_mfma_f32_16x16x32_bf16(Bt[n][k], At[m][k], acc[ai][bj][m][n], 0, 0, 0); __builtin_amdgcn_s_setprio(0); } while (0)
; #define PG8_WAIT_V(n) asm volatile("s_waitcnt vmcnt(" #n ")" ::: "memory")
; #define PG8_WAIT_L(n) asm volatile("s_waitcnt lgkmcnt(" #n ")" ::: "memory")
; #define PG8_BAR __builtin_amdgcn_s_barrier()
; #define PG8_SCHED __builtin_amdgcn_sched_barrier(0)
; template <class Epi, class Sched, bool ALIGN_EPI = true, bool SP2 = true>
; DI void gemm_phase(LAS unsigned char* lds, const Gemm g, const Sched& S, const Epi& E) {
;     ...
;         for (int t = 0; t < nt; t += 2) {
;             const bool last = (t == nt - 2);
;     ...
;             PG8_LDA(At, 1, 1); PG8_STAGE(PG8_SB(1, 0), b3, voffB); PG8_STAGE(PG8_SB(1, 1), b3 + hstepB, voffB); PG8_STAGE(PG8_SA(1, 0), a3, voffA);
;             PG8_WAIT_V(8); PG8_WAIT_L(0); PG8_BAR; PG8_MMA(1, 0, At, B0); PG8_MMA(1, 1, At, B1); PG8_BAR; PG8_SCHED;
;         }
	s_add_i32 s68, s73, s3
	v_lshl_add_u64 v[224:225], v[224:225], 0, s[48:49]
	s_mov_b32 m0, s68
	ds_read_b128 v[192:195], v170 offset:49152
	ds_read_b128 v[196:199], v170 offset:50176
	ds_read_b128 v[200:203], v170 offset:51200
	ds_read_b128 v[204:207], v170 offset:52224
	ds_read_b128 v[208:211], v170 offset:53248
	ds_read_b128 v[212:215], v170 offset:54272
	ds_read_b128 v[216:219], v170 offset:55296
	ds_read_b128 v[220:223], v170 offset:56320
	global_load_lds_dwordx4 v[224:225], off
	s_add_i32 m0, s68, 0x2000
	s_add_u32 s18, s18, 0x40080
	v_lshl_add_u64 v[224:225], v[228:229], 0, s[48:49]
	s_addc_u32 s19, s19, 0
	s_add_i32 s68, s74, s3
	global_load_lds_dwordx4 v[224:225], off
	v_lshl_add_u64 v[224:225], s[18:19], 0, v[138:139]
	s_mov_b32 m0, s68
	s_nop 0
	global_load_lds_dwordx4 v[224:225], off
	v_lshl_add_u64 v[224:225], s[18:19], 0, v[142:143]
	s_add_i32 m0, s68, 0x2000
	s_nop 0
	global_load_lds_dwordx4 v[224:225], off
	v_lshl_add_u64 v[224:225], v[230:231], 0, s[48:49]
	s_mov_b32 m0, s86
	s_nop 0
	global_load_lds_dwordx4 v[224:225], off
	v_lshl_add_u64 v[224:225], v[232:233], 0, s[48:49]
	s_mov_b32 m0, s87
	s_nop 0
	global_load_lds_dwordx4 v[224:225], off
	s_waitcnt vmcnt(8)
	s_waitcnt lgkmcnt(0)
	s_barrier
	s_setprio 1
	s_waitcnt lgkmcnt(0)
	v_mfma_f32_16x16x32_bf16 v[60:63], v[128:131], v[192:195], v[60:63]
	v_mfma_f32_16x16x32_bf16 v[56:59], v[154:157], v[192:195], v[56:59]
	v_mfma_f32_16x16x32_bf16 v[44:47], v[128:131], v[200:203], v[44:47]
	v_mfma_f32_16x16x32_bf16 v[40:43], v[154:157], v[200:203], v[40:43]
	v_mfma_f32_16x16x32_bf16 v[28:31], v[128:131], v[208:211], v[28:31]
	v_mfma_f32_16x16x32_bf16 v[24:27], v[154:157], v[208:211], v[24:27]
	v_mfma_f32_16x16x32_bf16 v[12:15], v[128:131], v[216:219], v[12:15]
	v_mfma_f32_16x16x32_bf16 v[8:11], v[154:157], v[216:219], v[8:11]
	v_mfma_f32_16x16x32_bf16 v[60:63], v[132:135], v[196:199], v[60:63]
	v_mfma_f32_16x16x32_bf16 v[56:59], v[158:161], v[196:199], v[56:59]
	v_mfma_f32_16x16x32_bf16 v[44:47], v[132:135], v[204:207], v[44:47]
	v_mfma_f32_16x16x32_bf16 v[40:43], v[158:161], v[204:207], v[40:43]
	v_mfma_f32_16x16x32_bf16 v[28:31], v[132:135], v[212:215], v[28:31]
	v_mfma_f32_16x16x32_bf16 v[24:27], v[158:161], v[212:215], v[24:27]
	v_mfma_f32_16x16x32_bf16 v[12:15], v[132:135], v[220:223], v[12:15]
	v_mfma_f32_16x16x32_bf16 v[8:11], v[158:161], v[220:223], v[8:11]
	s_setprio 0
	s_setprio 1
	v_mfma_f32_16x16x32_bf16 v[52:55], v[176:179], v[192:195], v[52:55]
	v_mfma_f32_16x16x32_bf16 v[48:51], v[184:187], v[192:195], v[48:51]
	v_mfma_f32_16x16x32_bf16 v[36:39], v[176:179], v[200:203], v[36:39]
	v_mfma_f32_16x16x32_bf16 v[32:35], v[184:187], v[200:203], v[32:35]
	v_mfma_f32_16x16x32_bf16 v[20:23], v[176:179], v[208:211], v[20:23]
	v_mfma_f32_16x16x32_bf16 v[16:19], v[184:187], v[208:211], v[16:19]
	v_mfma_f32_16x16x32_bf16 v[4:7], v[176:179], v[216:219], v[4:7]
	v_mfma_f32_16x16x32_bf16 v[0:3], v[184:187], v[216:219], v[0:3]
	v_mfma_f32_16x16x32_bf16 v[52:55], v[180:183], v[196:199], v[52:55]
	v_mfma_f32_16x16x32_bf16 v[48:51], v[188:191], v[196:199], v[48:51]
	v_mfma_f32_16x16x32_bf16 v[36:39], v[180:183], v[204:207], v[36:39]
	v_mfma_f32_16x16x32_bf16 v[32:35], v[188:191], v[204:207], v[32:35]
	v_mfma_f32_16x16x32_bf16 v[20:23], v[180:183], v[212:215], v[20:23]
	v_mfma_f32_16x16x32_bf16 v[16:19], v[188:191], v[212:215], v[16:19]
	v_mfma_f32_16x16x32_bf16 v[4:7], v[180:183], v[220:223], v[4:7]
	v_mfma_f32_16x16x32_bf16 v[0:3], v[188:191], v[220:223], v[0:3]
	s_setprio 0
	s_add_i32 s72, s72, 2
	s_add_u32 s16, s16, 0x100
	s_addc_u32 s17, s17, 0
	s_add_u32 s70, s70, 0x100
	s_addc_u32 s71, s71, 0
	s_cmp_gt_u32 s72, 13
	s_barrier
	s_cbranch_scc0 .LBB0_909
	s_and_b64 vcc, exec, s[54:55]
	s_cbranch_vccz .LBB0_912
	s_barrier

; #define PG8_STAGE(bufoff, gbase, voff) do { _Pragma("unroll") for (int _i = 0; _i < 2; ++_i) \
;         __builtin_amdgcn_global_load_lds((const unsigned*)((const char*)(gbase) + (voff)[_i]), (LAS unsigned*)(lds + (bufoff) + ldsw + _i * 8192), 16, 0, 0); } while (0)
; #define PG8_LDA(dst, b, h) do { _Pragma("unroll") for (int m = 0; m < 4; ++m) _Pragma("unroll") for (int k = 0; k < 2; ++k) dst[m][k] = *(const LAS bf16x8*)(lds + PG8_SA(b, h) + aoff + m * 2048 + k * 1024); } while (0)
; #define PG8_LDB(dst, b, h) do { _Pragma("unroll") for (int n = 0; n < 2; ++n) _Pragma("unroll") for (int k = 0; k < 2; ++k) dst[n][k] = *(const LAS bf16x8*)(lds + PG8_SB(b, h) + boff + n * 2048 + k * 1024); } while (0)
; #define PG8_MMA(ai, bj, At, Bt) do { __builtin_amdgcn_s_setprio(1); _Pragma("unroll") for (int m = 0; m < 4; ++m) _Pragma("unroll") for (int n = 0; n < 2; ++n) _Pragma("unroll") for (int k = 0; k < 2; ++k) \
;         acc[ai][bj][m][n] = __builtin_amdgcn_mfma_f32_16x16x32_bf16(Bt[n][k], At[m][k], acc[ai][bj][m][n], 0, 0, 0); __builtin_amdgcn_s_setprio(0); } while (0)
; #define PG8_WAIT_V(n) asm volatile("s_waitcnt vmcnt(" #n ")" ::: "memory")
; #define PG8_WAIT_L(n) asm volatile("s_waitcnt lgkmcnt(" #n ")" ::: "memory")
; #define PG8_BAR __builtin_amdgcn_s_barrier()
; #define PG8_SCHED __builtin_amdgcn_sched_barrier(0)
; template <class Epi, class Sched, bool ALIGN_EPI = true, bool SP2 = true>
; DI void gemm_phase(LAS unsigned char* lds, const Gemm g, const Sched& S, const Epi& E) {
;     ...
;             const bool last = (t == nt - 2);
;             const char* a1 = cA + (size_t)(t + 1) * kstep;
;             const char* a2 = last ? nA : cA + (size_t)(t + 2) * kstep; const char* b2 = last ? nB : cB + (size_t)(t + 2) * kstep;
;             const char* a3 = a2 + kstep; const char* b3 = b2 + kstep;
;             PG8_LDB(B0, 0, 0); PG8_LDB(B1, 0, 1); PG8_SCHED; PG8_LDA(At, 0, 0); PG8_STAGE(PG8_SA(1, 1), a1 + hstepA, voffA);
;             PG8_WAIT_V(8); PG8_WAIT_L(0); PG8_BAR; PG8_MMA(0, 0, At, B0); PG8_MMA(0, 1, At, B1); PG8_BAR; PG8_SCHED;
;             PG8_LDA(At, 0, 1); PG8_STAGE(PG8_SB(0, 0), b2, voffB); PG8_STAGE(PG8_SB(0, 1), b2 + hstepB, voffB); PG8_STAGE(PG8_SA(0, 0), a2, voffA);
.LBB0_2015:
	v_add_u32_e32 v158, s59, v160
	ds_read_b128 v[174:177], v158
	ds_read_b128 v[178:181], v158 offset:1024
	ds_read_b128 v[182:185], v158 offset:2048
	ds_read_b128 v[186:189], v158 offset:3072
	v_add_u32_e32 v158, s60, v160
	ds_read_b128 v[190:193], v158
	ds_read_b128 v[194:197], v158 offset:1024
	ds_read_b128 v[198:201], v158 offset:2048
	ds_read_b128 v[202:205], v158 offset:3072
	s_add_u32 s46, s44, 0xfffe0080
	s_addc_u32 s47, s45, -1
	s_cmp_eq_u32 s80, 4
	s_cselect_b32 s49, s74, s47
	s_cselect_b32 s48, s75, s46
	s_cselect_b32 s47, s76, s79
	s_cselect_b32 s46, s77, s78
	s_mov_b32 m0, s63
	v_lshl_add_u64 v[158:159], s[44:45], 0, v[154:155]
	ds_read_b128 v[206:209], v169
	ds_read_b128 v[210:213], v169 offset:1024
	ds_read_b128 v[214:217], v169 offset:2048
	ds_read_b128 v[218:221], v169 offset:3072
	ds_read_b128 v[222:225], v169 offset:4096
	ds_read_b128 v[228:231], v169 offset:5120
	ds_read_b128 v[232:235], v169 offset:6144
	ds_read_b128 v[236:239], v169 offset:7168
	global_load_lds_dwordx4 v[158:159], off
	v_lshl_add_u64 v[158:159], s[44:45], 0, v[156:157]
	s_mov_b32 m0, s64
	s_nop 0
	global_load_lds_dwordx4 v[158:159], off
	s_waitcnt vmcnt(8)
	s_waitcnt lgkmcnt(0)
	s_barrier
	s_setprio 1
	s_waitcnt lgkmcnt(0)
	v_mfma_f32_16x16x32_bf16 v[124:127], v[174:177], v[206:209], v[124:127]
	v_mfma_f32_16x16x32_bf16 v[120:123], v[182:185], v[206:209], v[120:123]
	v_mfma_f32_16x16x32_bf16 v[108:111], v[174:177], v[214:217], v[108:111]
	v_mfma_f32_16x16x32_bf16 v[104:107], v[182:185], v[214:217], v[104:107]
	v_mfma_f32_16x16x32_bf16 v[92:95], v[174:177], v[222:225], v[92:95]
	v_mfma_f32_16x16x32_bf16 v[88:91], v[182:185], v[222:225], v[88:91]
	v_mfma_f32_16x16x32_bf16 v[76:79], v[174:177], v[232:235], v[76:79]
	v_mfma_f32_16x16x32_bf16 v[72:75], v[182:185], v[232:235], v[72:75]
	v_mfma_f32_16x16x32_bf16 v[124:127], v[178:181], v[210:213], v[124:127]
	v_mfma_f32_16x16x32_bf16 v[120:123], v[186:189], v[210:213], v[120:123]
	v_mfma_f32_16x16x32_bf16 v[108:111], v[178:181], v[218:221], v[108:111]
	v_mfma_f32_16x16x32_bf16 v[104:107], v[186:189], v[218:221], v[104:107]
	v_mfma_f32_16x16x32_bf16 v[92:95], v[178:181], v[228:231], v[92:95]
	v_mfma_f32_16x16x32_bf16 v[88:91], v[186:189], v[228:231], v[88:91]
	v_mfma_f32_16x16x32_bf16 v[76:79], v[178:181], v[236:239], v[76:79]
	v_mfma_f32_16x16x32_bf16 v[72:75], v[186:189], v[236:239], v[72:75]
	s_setprio 0
	s_setprio 1
	v_mfma_f32_16x16x32_bf16 v[116:119], v[190:193], v[206:209], v[116:119]
	v_mfma_f32_16x16x32_bf16 v[112:115], v[198:201], v[206:209], v[112:115]
	v_mfma_f32_16x16x32_bf16 v[100:103], v[190:193], v[214:217], v[100:103]
	v_mfma_f32_16x16x32_bf16 v[96:99], v[198:201], v[214:217], v[96:99]
	v_mfma_f32_16x16x32_bf16 v[84:87], v[190:193], v[222:225], v[84:87]
	v_mfma_f32_16x16x32_bf16 v[80:83], v[198:201], v[222:225], v[80:83]
	v_mfma_f32_16x16x32_bf16 v[68:71], v[190:193], v[232:235], v[68:71]
	v_mfma_f32_16x16x32_bf16 v[64:67], v[198:201], v[232:235], v[64:67]
	v_mfma_f32_16x16x32_bf16 v[116:119], v[194:197], v[210:213], v[116:119]
	v_mfma_f32_16x16x32_bf16 v[112:115], v[202:205], v[210:213], v[112:115]
	v_mfma_f32_16x16x32_bf16 v[100:103], v[194:197], v[218:221], v[100:103]
	v_mfma_f32_16x16x32_bf16 v[96:99], v[202:205], v[218:221], v[96:99]
	v_mfma_f32_16x16x32_bf16 v[84:87], v[194:197], v[228:231], v[84:87]
	v_mfma_f32_16x16x32_bf16 v[80:83], v[202:205], v[228:231], v[80:83]
	v_mfma_f32_16x16x32_bf16 v[68:71], v[194:197], v[236:239], v[68:71]
	v_mfma_f32_16x16x32_bf16 v[64:67], v[202:205], v[236:239], v[64:67]
	s_setprio 0
	s_barrier
	s_mov_b32 m0, s65
	v_lshl_add_u64 v[158:159], s[46:47], 0, v[132:133]
	s_add_u32 s82, s46, 0x20000
	ds_read_b128 v[206:209], v169 offset:16384
	ds_read_b128 v[210:213], v169 offset:17408
	ds_read_b128 v[214:217], v169 offset:18432
	ds_read_b128 v[218:221], v169 offset:19456
	ds_read_b128 v[222:225], v169 offset:20480
	ds_read_b128 v[228:231], v169 offset:21504
	ds_read_b128 v[232:235], v169 offset:22528
	ds_read_b128 v[236:239], v169 offset:23552
	global_load_lds_dwordx4 v[158:159], off
	v_lshl_add_u64 v[240:241], s[46:47], 0, v[128:129]
	s_mov_b32 m0, s66
	s_addc_u32 s83, s47, 0
	global_load_lds_dwordx4 v[240:241], off
	v_lshl_add_u64 v[242:243], s[82:83], 0, v[132:133]
	s_mov_b32 m0, s67
	v_lshl_add_u64 v[244:245], s[48:49], 0, v[130:131]
	global_load_lds_dwordx4 v[242:243], off
	v_lshl_add_u64 v[242:243], s[82:83], 0, v[128:129]
	s_mov_b32 m0, s68
	s_nop 0
	global_load_lds_dwordx4 v[242:243], off
	v_lshl_add_u64 v[242:243], s[48:49], 0, v[134:135]
	s_mov_b32 m0, s3
	s_nop 0
	global_load_lds_dwordx4 v[242:243], off
	s_mov_b32 m0, s53
	s_nop 0
	global_load_lds_dwordx4 v[244:245], off
	s_waitcnt vmcnt(8)
	s_waitcnt lgkmcnt(0)
	s_barrier
; #define PG8_STAGE(bufoff, gbase, voff) do { _Pragma("unroll") for (int _i = 0; _i < 2; ++_i) \
;         __builtin_amdgcn_global_load_lds((const unsigned*)((const char*)(gbase) + (voff)[_i]), (LAS unsigned*)(lds + (bufoff) + ldsw + _i * 8192), 16, 0, 0); } while (0)
; #define PG8_LDA(dst, b, h) do { _Pragma("unroll") for (int m = 0; m < 4; ++m) _Pragma("unroll") for (int k = 0; k < 2; ++k) dst[m][k] = *(const LAS bf16x8*)(lds + PG8_SA(b, h) + aoff + m * 2048 + k * 1024); } while (0)
; #define PG8_LDB(dst, b, h) do { _Pragma("unroll") for (int n = 0; n < 2; ++n) _Pragma("unroll") for (int k = 0; k < 2; ++k) dst[n][k] = *(const LAS bf16x8*)(lds + PG8_SB(b, h) + boff + n * 2048 + k * 1024); } while (0)
; #define PG8_MMA(ai, bj, At, Bt) do { __builtin_amdgcn_s_setprio(1); _Pragma("unroll") for (int m = 0; m < 4; ++m) _Pragma("unroll") for (int n = 0; n < 2; ++n) _Pragma("unroll") for (int k = 0; k < 2; ++k) \
;         acc[ai][bj][m][n] = __builtin_amdgcn_mfma_f32_16x16x32_bf16(Bt[n][k], At[m][k], acc[ai][bj][m][n], 0, 0, 0); __builtin_amdgcn_s_setprio(0); } while (0)
; #define PG8_WAIT_V(n) asm volatile("s_waitcnt vmcnt(" #n ")" ::: "memory")
; #define PG8_WAIT_L(n) asm volatile("s_waitcnt lgkmcnt(" #n ")" ::: "memory")
; #define PG8_BAR __builtin_amdgcn_s_barrier()
; #define PG8_SCHED __builtin_amdgcn_sched_barrier(0)
; template <class Epi, class Sched, bool ALIGN_EPI = true, bool SP2 = true>
; DI void gemm_phase(LAS unsigned char* lds, const Gemm g, const Sched& S, const Epi& E) {
;     ...
;             PG8_WAIT_V(8); PG8_WAIT_L(0); PG8_BAR; PG8_MMA(1, 0, At, B0); PG8_MMA(1, 1, At, B1); PG8_BAR; PG8_SCHED;
;             PG8_LDB(B0, 1, 0); PG8_LDB(B1, 1, 1); PG8_SCHED; PG8_LDA(At, 1, 0); PG8_STAGE(PG8_SA(0, 1), a2 + hstepA, voffA);
;             PG8_WAIT_V(8); PG8_WAIT_L(0); PG8_BAR; PG8_MMA(0, 0, At, B0); PG8_MMA(0, 1, At, B1); PG8_BAR; PG8_SCHED;
	s_setprio 1
	s_waitcnt lgkmcnt(0)
	v_mfma_f32_16x16x32_bf16 v[60:63], v[174:177], v[206:209], v[60:63]
	v_mfma_f32_16x16x32_bf16 v[56:59], v[182:185], v[206:209], v[56:59]
	v_mfma_f32_16x16x32_bf16 v[44:47], v[174:177], v[214:217], v[44:47]
	v_mfma_f32_16x16x32_bf16 v[40:43], v[182:185], v[214:217], v[40:43]
	v_mfma_f32_16x16x32_bf16 v[28:31], v[174:177], v[222:225], v[28:31]
	v_mfma_f32_16x16x32_bf16 v[24:27], v[182:185], v[222:225], v[24:27]
	v_mfma_f32_16x16x32_bf16 v[12:15], v[174:177], v[232:235], v[12:15]
	v_mfma_f32_16x16x32_bf16 v[8:11], v[182:185], v[232:235], v[8:11]
	v_mfma_f32_16x16x32_bf16 v[60:63], v[178:181], v[210:213], v[60:63]
	v_mfma_f32_16x16x32_bf16 v[56:59], v[186:189], v[210:213], v[56:59]
	v_mfma_f32_16x16x32_bf16 v[44:47], v[178:181], v[218:221], v[44:47]
	v_mfma_f32_16x16x32_bf16 v[40:43], v[186:189], v[218:221], v[40:43]
	v_mfma_f32_16x16x32_bf16 v[28:31], v[178:181], v[228:231], v[28:31]
	v_mfma_f32_16x16x32_bf16 v[24:27], v[186:189], v[228:231], v[24:27]
	v_mfma_f32_16x16x32_bf16 v[12:15], v[178:181], v[236:239], v[12:15]
	v_mfma_f32_16x16x32_bf16 v[8:11], v[186:189], v[236:239], v[8:11]
	s_setprio 0
	s_setprio 1
	v_mfma_f32_16x16x32_bf16 v[52:55], v[190:193], v[206:209], v[52:55]
	v_mfma_f32_16x16x32_bf16 v[48:51], v[198:201], v[206:209], v[48:51]
	v_mfma_f32_16x16x32_bf16 v[36:39], v[190:193], v[214:217], v[36:39]
	v_mfma_f32_16x16x32_bf16 v[32:35], v[198:201], v[214:217], v[32:35]
	v_mfma_f32_16x16x32_bf16 v[20:23], v[190:193], v[222:225], v[20:23]
	v_mfma_f32_16x16x32_bf16 v[16:19], v[198:201], v[222:225], v[16:19]
	v_mfma_f32_16x16x32_bf16 v[4:7], v[190:193], v[232:235], v[4:7]
	v_mfma_f32_16x16x32_bf16 v[0:3], v[198:201], v[232:235], v[0:3]
	v_mfma_f32_16x16x32_bf16 v[52:55], v[194:197], v[210:213], v[52:55]
	v_mfma_f32_16x16x32_bf16 v[48:51], v[202:205], v[210:213], v[48:51]
	v_mfma_f32_16x16x32_bf16 v[36:39], v[194:197], v[218:221], v[36:39]
	v_mfma_f32_16x16x32_bf16 v[32:35], v[202:205], v[218:221], v[32:35]
	v_mfma_f32_16x16x32_bf16 v[20:23], v[194:197], v[228:231], v[20:23]
	v_mfma_f32_16x16x32_bf16 v[16:19], v[202:205], v[228:231], v[16:19]
	v_mfma_f32_16x16x32_bf16 v[4:7], v[194:197], v[236:239], v[4:7]
	v_mfma_f32_16x16x32_bf16 v[0:3], v[202:205], v[236:239], v[0:3]
	s_setprio 0
	s_barrier
	v_add_u32_e32 v173, s69, v160
	ds_read_b128 v[174:177], v173
	ds_read_b128 v[178:181], v173 offset:1024
	ds_read_b128 v[182:185], v173 offset:2048
	ds_read_b128 v[186:189], v173 offset:3072
	v_add_u32_e32 v173, s70, v160
	ds_read_b128 v[190:193], v173
	ds_read_b128 v[194:197], v173 offset:1024
	ds_read_b128 v[198:201], v173 offset:2048
	ds_read_b128 v[202:205], v173 offset:3072
	s_add_u32 s48, s48, 0x20000
	s_addc_u32 s49, s49, 0
	s_mov_b32 m0, s54
	v_lshl_add_u64 v[246:247], s[48:49], 0, v[134:135]
	ds_read_b128 v[206:209], v169 offset:32768
	ds_read_b128 v[210:213], v169 offset:33792
	ds_read_b128 v[214:217], v169 offset:34816
	ds_read_b128 v[218:221], v169 offset:35840
	ds_read_b128 v[222:225], v169 offset:36864
	ds_read_b128 v[228:231], v169 offset:37888
	ds_read_b128 v[232:235], v169 offset:38912
	ds_read_b128 v[236:239], v169 offset:39936
	global_load_lds_dwordx4 v[246:247], off
	v_lshl_add_u64 v[246:247], s[48:49], 0, v[130:131]
	s_mov_b32 m0, s55
	s_nop 0
	global_load_lds_dwordx4 v[246:247], off
	s_waitcnt vmcnt(8)
	s_waitcnt lgkmcnt(0)
	s_barrier
	s_setprio 1
	s_waitcnt lgkmcnt(0)
	v_mfma_f32_16x16x32_bf16 v[124:127], v[174:177], v[206:209], v[124:127]
	v_mfma_f32_16x16x32_bf16 v[120:123], v[182:185], v[206:209], v[120:123]
	v_mfma_f32_16x16x32_bf16 v[108:111], v[174:177], v[214:217], v[108:111]
	v_mfma_f32_16x16x32_bf16 v[104:107], v[182:185], v[214:217], v[104:107]
	v_mfma_f32_16x16x32_bf16 v[92:95], v[174:177], v[222:225], v[92:95]
	v_mfma_f32_16x16x32_bf16 v[88:91], v[182:185], v[222:225], v[88:91]
	v_mfma_f32_16x16x32_bf16 v[76:79], v[174:177], v[232:235], v[76:79]
	v_mfma_f32_16x16x32_bf16 v[72:75], v[182:185], v[232:235], v[72:75]
	v_mfma_f32_16x16x32_bf16 v[124:127], v[178:181], v[210:213], v[124:127]
	v_mfma_f32_16x16x32_bf16 v[120:123], v[186:189], v[210:213], v[120:123]
	v_mfma_f32_16x16x32_bf16 v[108:111], v[178:181], v[218:221], v[108:111]
	v_mfma_f32_16x16x32_bf16 v[104:107], v[186:189], v[218:221], v[104:107]
	v_mfma_f32_16x16x32_bf16 v[92:95], v[178:181], v[228:231], v[92:95]
	v_mfma_f32_16x16x32_bf16 v[88:91], v[186:189], v[228:231], v[88:91]
	v_mfma_f32_16x16x32_bf16 v[76:79], v[178:181], v[236:239], v[76:79]
	v_mfma_f32_16x16x32_bf16 v[72:75], v[186:189], v[236:239], v[72:75]
	s_setprio 0
	s_setprio 1
	v_mfma_f32_16x16x32_bf16 v[116:119], v[190:193], v[206:209], v[116:119]
	v_mfma_f32_16x16x32_bf16 v[112:115], v[198:201], v[206:209], v[112:115]
	v_mfma_f32_16x16x32_bf16 v[100:103], v[190:193], v[214:217], v[100:103]
	v_mfma_f32_16x16x32_bf16 v[96:99], v[198:201], v[214:217], v[96:99]
	v_mfma_f32_16x16x32_bf16 v[84:87], v[190:193], v[222:225], v[84:87]
	v_mfma_f32_16x16x32_bf16 v[80:83], v[198:201], v[222:225], v[80:83]
	v_mfma_f32_16x16x32_bf16 v[68:71], v[190:193], v[232:235], v[68:71]
	v_mfma_f32_16x16x32_bf16 v[64:67], v[198:201], v[232:235], v[64:67]
	v_mfma_f32_16x16x32_bf16 v[116:119], v[194:197], v[210:213], v[116:119]
	v_mfma_f32_16x16x32_bf16 v[112:115], v[202:205], v[210:213], v[112:115]
	v_mfma_f32_16x16x32_bf16 v[100:103], v[194:197], v[218:221], v[100:103]
	v_mfma_f32_16x16x32_bf16 v[96:99], v[202:205], v[218:221], v[96:99]
	v_mfma_f32_16x16x32_bf16 v[84:87], v[194:197], v[228:231], v[84:87]
	v_mfma_f32_16x16x32_bf16 v[80:83], v[202:205], v[228:231], v[80:83]
	v_mfma_f32_16x16x32_bf16 v[68:71], v[194:197], v[236:239], v[68:71]
	v_mfma_f32_16x16x32_bf16 v[64:67], v[202:205], v[236:239], v[64:67]
	s_setprio 0
	s_barrier
; #define PG8_STAGE(bufoff, gbase, voff) do { _Pragma("unroll") for (int _i = 0; _i < 2; ++_i) \
;         __builtin_amdgcn_global_load_lds((const unsigned*)((const char*)(gbase) + (voff)[_i]), (LAS unsigned*)(lds + (bufoff) + ldsw + _i * 8192), 16, 0, 0); } while (0)
; #define PG8_LDA(dst, b, h) do { _Pragma("unroll") for (int m = 0; m < 4; ++m) _Pragma("unroll") for (int k = 0; k < 2; ++k) dst[m][k] = *(const LAS bf16x8*)(lds + PG8_SA(b, h) + aoff + m * 2048 + k * 1024); } while (0)
; #define PG8_MMA(ai, bj, At, Bt) do { __builtin_amdgcn_s_setprio(1); _Pragma("unroll") for (int m = 0; m < 4; ++m) _Pragma("unroll") for (int n = 0; n < 2; ++n) _Pragma("unroll") for (int k = 0; k < 2; ++k) \
;         acc[ai][bj][m][n] = __builtin_amdgcn_mfma_f32_16x16x32_bf16(Bt[n][k], At[m][k], acc[ai][bj][m][n], 0, 0, 0); __builtin_amdgcn_s_setprio(0); } while (0)
; #define PG8_WAIT_V(n) asm volatile("s_waitcnt vmcnt(" #n ")" ::: "memory")
; #define PG8_WAIT_L(n) asm volatile("s_waitcnt lgkmcnt(" #n ")" ::: "memory")
; #define PG8_BAR __builtin_amdgcn_s_barrier()
; #define PG8_SCHED __builtin_amdgcn_sched_barrier(0)
; template <class Epi, class Sched, bool ALIGN_EPI = true, bool SP2 = true>
; DI void gemm_phase(LAS unsigned char* lds, const Gemm g, const Sched& S, const Epi& E) {
;     ...
;         for (int t = 0; t < nt; t += 2) {
;             const bool last = (t == nt - 2);
;     ...
;             PG8_LDA(At, 1, 1); PG8_STAGE(PG8_SB(1, 0), b3, voffB); PG8_STAGE(PG8_SB(1, 1), b3 + hstepB, voffB); PG8_STAGE(PG8_SA(1, 0), a3, voffA);
;             PG8_WAIT_V(8); PG8_WAIT_L(0); PG8_BAR; PG8_MMA(1, 0, At, B0); PG8_MMA(1, 1, At, B1); PG8_BAR; PG8_SCHED;
	s_mov_b32 m0, s71
	v_lshl_add_u64 v[158:159], v[158:159], 0, s[16:17]
	ds_read_b128 v[206:209], v169 offset:49152
	ds_read_b128 v[210:213], v169 offset:50176
	ds_read_b128 v[214:217], v169 offset:51200
	ds_read_b128 v[218:221], v169 offset:52224
	ds_read_b128 v[222:225], v169 offset:53248
	ds_read_b128 v[228:231], v169 offset:54272
	ds_read_b128 v[232:235], v169 offset:55296
	ds_read_b128 v[236:239], v169 offset:56320
	global_load_lds_dwordx4 v[158:159], off
	s_add_i32 m0, s71, 0x2000
	s_add_u32 s46, s46, 0x20080
	v_lshl_add_u64 v[158:159], v[240:241], 0, s[16:17]
	s_addc_u32 s47, s47, 0
	s_add_i32 s48, s70, s52
	global_load_lds_dwordx4 v[158:159], off
	v_lshl_add_u64 v[158:159], s[46:47], 0, v[132:133]
	s_mov_b32 m0, s48
	s_nop 0
	global_load_lds_dwordx4 v[158:159], off
	v_lshl_add_u64 v[158:159], s[46:47], 0, v[128:129]
	s_add_i32 m0, s48, 0x2000
	s_nop 0
	global_load_lds_dwordx4 v[158:159], off
	v_lshl_add_u64 v[158:159], v[242:243], 0, s[16:17]
	s_mov_b32 m0, s57
	s_nop 0
	global_load_lds_dwordx4 v[158:159], off
	v_lshl_add_u64 v[158:159], v[244:245], 0, s[16:17]
	s_mov_b32 m0, s58
	s_nop 0
	global_load_lds_dwordx4 v[158:159], off
	s_waitcnt vmcnt(8)
	s_waitcnt lgkmcnt(0)
	s_barrier
	s_setprio 1
	s_waitcnt lgkmcnt(0)
	v_mfma_f32_16x16x32_bf16 v[60:63], v[174:177], v[206:209], v[60:63]
	v_mfma_f32_16x16x32_bf16 v[56:59], v[182:185], v[206:209], v[56:59]
	v_mfma_f32_16x16x32_bf16 v[44:47], v[174:177], v[214:217], v[44:47]
	v_mfma_f32_16x16x32_bf16 v[40:43], v[182:185], v[214:217], v[40:43]
	v_mfma_f32_16x16x32_bf16 v[28:31], v[174:177], v[222:225], v[28:31]
	v_mfma_f32_16x16x32_bf16 v[24:27], v[182:185], v[222:225], v[24:27]
	v_mfma_f32_16x16x32_bf16 v[12:15], v[174:177], v[232:235], v[12:15]
	v_mfma_f32_16x16x32_bf16 v[8:11], v[182:185], v[232:235], v[8:11]
	v_mfma_f32_16x16x32_bf16 v[60:63], v[178:181], v[210:213], v[60:63]
	v_mfma_f32_16x16x32_bf16 v[56:59], v[186:189], v[210:213], v[56:59]
	v_mfma_f32_16x16x32_bf16 v[44:47], v[178:181], v[218:221], v[44:47]
	v_mfma_f32_16x16x32_bf16 v[40:43], v[186:189], v[218:221], v[40:43]
	v_mfma_f32_16x16x32_bf16 v[28:31], v[178:181], v[228:231], v[28:31]
	v_mfma_f32_16x16x32_bf16 v[24:27], v[186:189], v[228:231], v[24:27]
	v_mfma_f32_16x16x32_bf16 v[12:15], v[178:181], v[236:239], v[12:15]
	v_mfma_f32_16x16x32_bf16 v[8:11], v[186:189], v[236:239], v[8:11]
	s_setprio 0
	s_setprio 1
	v_mfma_f32_16x16x32_bf16 v[52:55], v[190:193], v[206:209], v[52:55]
	v_mfma_f32_16x16x32_bf16 v[48:51], v[198:201], v[206:209], v[48:51]
	v_mfma_f32_16x16x32_bf16 v[36:39], v[190:193], v[214:217], v[36:39]
	v_mfma_f32_16x16x32_bf16 v[32:35], v[198:201], v[214:217], v[32:35]
	v_mfma_f32_16x16x32_bf16 v[20:23], v[190:193], v[222:225], v[20:23]
	v_mfma_f32_16x16x32_bf16 v[16:19], v[198:201], v[222:225], v[16:19]
	v_mfma_f32_16x16x32_bf16 v[4:7], v[190:193], v[232:235], v[4:7]
	v_mfma_f32_16x16x32_bf16 v[0:3], v[198:201], v[232:235], v[0:3]
	v_mfma_f32_16x16x32_bf16 v[52:55], v[194:197], v[210:213], v[52:55]
	v_mfma_f32_16x16x32_bf16 v[48:51], v[202:205], v[210:213], v[48:51]
	v_mfma_f32_16x16x32_bf16 v[36:39], v[194:197], v[218:221], v[36:39]
	v_mfma_f32_16x16x32_bf16 v[32:35], v[202:205], v[218:221], v[32:35]
	v_mfma_f32_16x16x32_bf16 v[20:23], v[194:197], v[228:231], v[20:23]
	v_mfma_f32_16x16x32_bf16 v[16:19], v[202:205], v[228:231], v[16:19]
	v_mfma_f32_16x16x32_bf16 v[4:7], v[194:197], v[236:239], v[4:7]
	v_mfma_f32_16x16x32_bf16 v[0:3], v[202:205], v[236:239], v[0:3]
	s_setprio 0
	s_add_i32 s80, s80, 2
	s_add_u32 s44, s44, 0x100
	s_addc_u32 s45, s45, 0
	s_add_u32 s78, s78, 0x100
	s_addc_u32 s79, s79, 0
	s_cmp_gt_u32 s80, 5
	s_barrier
	s_cbranch_scc0 .LBB0_2015
	s_and_b64 vcc, exec, s[18:19]
	s_cbranch_vccz .LBB0_2018
	s_barrier

; #define PG8_STAGE(bufoff, gbase, voff) do { _Pragma("unroll") for (int _i = 0; _i < 2; ++_i) \
;         __builtin_amdgcn_global_load_lds((const unsigned*)((const char*)(gbase) + (voff)[_i]), (LAS unsigned*)(lds + (bufoff) + ldsw + _i * 8192), 16, 0, 0); } while (0)
; #define PG8_LDA(dst, b, h) do { _Pragma("unroll") for (int m = 0; m < 4; ++m) _Pragma("unroll") for (int k = 0; k < 2; ++k) dst[m][k] = *(const LAS bf16x8*)(lds + PG8_SA(b, h) + aoff + m * 2048 + k * 1024); } while (0)
; #define PG8_LDB(dst, b, h) do { _Pragma("unroll") for (int n = 0; n < 2; ++n) _Pragma("unroll") for (int k = 0; k < 2; ++k) dst[n][k] = *(const LAS bf16x8*)(lds + PG8_SB(b, h) + boff + n * 2048 + k * 1024); } while (0)
; #define PG8_MMA(ai, bj, At, Bt) do { __builtin_amdgcn_s_setprio(1); _Pragma("unroll") for (int m = 0; m < 4; ++m) _Pragma("unroll") for (int n = 0; n < 2; ++n) _Pragma("unroll") for (int k = 0; k < 2; ++k) \
;         acc[ai][bj][m][n] = __builtin_amdgcn_mfma_f32_16x16x32_bf16(Bt[n][k], At[m][k], acc[ai][bj][m][n], 0, 0, 0); __builtin_amdgcn_s_setprio(0); } while (0)
; #define PG8_WAIT_V(n) asm volatile("s_waitcnt vmcnt(" #n ")" ::: "memory")
; #define PG8_WAIT_L(n) asm volatile("s_waitcnt lgkmcnt(" #n ")" ::: "memory")
; #define PG8_BAR __builtin_amdgcn_s_barrier()
; #define PG8_SCHED __builtin_amdgcn_sched_barrier(0)
; template <class Epi, class Sched, bool ALIGN_EPI = true, bool SP2 = true>
; DI void gemm_phase(LAS unsigned char* lds, const Gemm g, const Sched& S, const Epi& E) {
;     ...
;             const bool last = (t == nt - 2);
;             const char* a1 = cA + (size_t)(t + 1) * kstep;
;             const char* a2 = last ? nA : cA + (size_t)(t + 2) * kstep; const char* b2 = last ? nB : cB + (size_t)(t + 2) * kstep;
;             const char* a3 = a2 + kstep; const char* b3 = b2 + kstep;
;             PG8_LDB(B0, 0, 0); PG8_LDB(B1, 0, 1); PG8_SCHED; PG8_LDA(At, 0, 0); PG8_STAGE(PG8_SA(1, 1), a1 + hstepA, voffA);
;             PG8_WAIT_V(8); PG8_WAIT_L(0); PG8_BAR; PG8_MMA(0, 0, At, B0); PG8_MMA(0, 1, At, B1); PG8_BAR; PG8_SCHED;
;             PG8_LDA(At, 0, 1); PG8_STAGE(PG8_SB(0, 0), b2, voffB); PG8_STAGE(PG8_SB(0, 1), b2 + hstepB, voffB); PG8_STAGE(PG8_SA(0, 0), a2, voffA);
.LBB0_2108:
	ds_read_b128 v[140:143], v157
	ds_read_b128 v[144:147], v157 offset:1024
	ds_read_b128 v[148:151], v157 offset:2048
	ds_read_b128 v[160:163], v157 offset:3072
	ds_read_b128 v[164:167], v158
	ds_read_b128 v[168:171], v158 offset:1024
	ds_read_b128 v[172:175], v158 offset:2048
	ds_read_b128 v[176:179], v158 offset:3072
	s_add_u32 s52, s48, 0xfff80080
	s_addc_u32 s53, s49, -1
	s_cmp_eq_u32 s78, 28
	s_cselect_b32 s55, s41, s53
	s_cselect_b32 s54, s74, s52
	s_cselect_b32 s53, s39, s77
	s_cselect_b32 s52, s75, s76
	v_lshl_add_u64 v[152:153], s[48:49], 0, v[132:133]
	s_add_i32 m0, s59, 0xc000
	ds_read_b128 v[180:183], v159
	ds_read_b128 v[184:187], v159 offset:1024
	ds_read_b128 v[188:191], v159 offset:2048
	ds_read_b128 v[192:195], v159 offset:3072
	ds_read_b128 v[196:199], v159 offset:4096
	ds_read_b128 v[200:203], v159 offset:5120
	ds_read_b128 v[204:207], v159 offset:6144
	ds_read_b128 v[208:211], v159 offset:7168
	global_load_lds_dwordx4 v[152:153], off
	v_lshl_add_u64 v[152:153], s[48:49], 0, v[134:135]
	s_add_i32 m0, s59, 0xe000
	s_nop 0
	global_load_lds_dwordx4 v[152:153], off
	s_waitcnt vmcnt(8)
	s_waitcnt lgkmcnt(0)
	s_barrier
	s_setprio 1
	s_waitcnt lgkmcnt(0)
	v_mfma_f32_16x16x32_bf16 v[124:127], v[140:143], v[180:183], v[124:127]
	v_mfma_f32_16x16x32_bf16 v[120:123], v[148:151], v[180:183], v[120:123]
	v_mfma_f32_16x16x32_bf16 v[108:111], v[140:143], v[188:191], v[108:111]
	v_mfma_f32_16x16x32_bf16 v[104:107], v[148:151], v[188:191], v[104:107]
	v_mfma_f32_16x16x32_bf16 v[92:95], v[140:143], v[196:199], v[92:95]
	v_mfma_f32_16x16x32_bf16 v[88:91], v[148:151], v[196:199], v[88:91]
	v_mfma_f32_16x16x32_bf16 v[76:79], v[140:143], v[204:207], v[76:79]
	v_mfma_f32_16x16x32_bf16 v[72:75], v[148:151], v[204:207], v[72:75]
	v_mfma_f32_16x16x32_bf16 v[124:127], v[144:147], v[184:187], v[124:127]
	v_mfma_f32_16x16x32_bf16 v[120:123], v[160:163], v[184:187], v[120:123]
	v_mfma_f32_16x16x32_bf16 v[108:111], v[144:147], v[192:195], v[108:111]
	v_mfma_f32_16x16x32_bf16 v[104:107], v[160:163], v[192:195], v[104:107]
	v_mfma_f32_16x16x32_bf16 v[92:95], v[144:147], v[200:203], v[92:95]
	v_mfma_f32_16x16x32_bf16 v[88:91], v[160:163], v[200:203], v[88:91]
	v_mfma_f32_16x16x32_bf16 v[76:79], v[144:147], v[208:211], v[76:79]
	v_mfma_f32_16x16x32_bf16 v[72:75], v[160:163], v[208:211], v[72:75]
	s_setprio 0
	s_setprio 1
	v_mfma_f32_16x16x32_bf16 v[116:119], v[164:167], v[180:183], v[116:119]
	v_mfma_f32_16x16x32_bf16 v[112:115], v[172:175], v[180:183], v[112:115]
	v_mfma_f32_16x16x32_bf16 v[100:103], v[164:167], v[188:191], v[100:103]
	v_mfma_f32_16x16x32_bf16 v[96:99], v[172:175], v[188:191], v[96:99]
	v_mfma_f32_16x16x32_bf16 v[84:87], v[164:167], v[196:199], v[84:87]
	v_mfma_f32_16x16x32_bf16 v[80:83], v[172:175], v[196:199], v[80:83]
	v_mfma_f32_16x16x32_bf16 v[68:71], v[164:167], v[204:207], v[68:71]
	v_mfma_f32_16x16x32_bf16 v[64:67], v[172:175], v[204:207], v[64:67]
	v_mfma_f32_16x16x32_bf16 v[116:119], v[168:171], v[184:187], v[116:119]
	v_mfma_f32_16x16x32_bf16 v[112:115], v[176:179], v[184:187], v[112:115]
	v_mfma_f32_16x16x32_bf16 v[100:103], v[168:171], v[192:195], v[100:103]
	v_mfma_f32_16x16x32_bf16 v[96:99], v[176:179], v[192:195], v[96:99]
	v_mfma_f32_16x16x32_bf16 v[84:87], v[168:171], v[200:203], v[84:87]
	v_mfma_f32_16x16x32_bf16 v[80:83], v[176:179], v[200:203], v[80:83]
	v_mfma_f32_16x16x32_bf16 v[68:71], v[168:171], v[208:211], v[68:71]
	v_mfma_f32_16x16x32_bf16 v[64:67], v[176:179], v[208:211], v[64:67]
	s_setprio 0
	s_barrier
	s_add_i32 s79, s69, s58
	v_lshl_add_u64 v[152:153], s[52:53], 0, v[128:129]
	s_mov_b32 m0, s79
	ds_read_b128 v[180:183], v159 offset:16384
	ds_read_b128 v[184:187], v159 offset:17408
	ds_read_b128 v[188:191], v159 offset:18432
	ds_read_b128 v[192:195], v159 offset:19456
	ds_read_b128 v[196:199], v159 offset:20480
	ds_read_b128 v[200:203], v159 offset:21504
	ds_read_b128 v[204:207], v159 offset:22528
	ds_read_b128 v[208:211], v159 offset:23552
	global_load_lds_dwordx4 v[152:153], off
	s_add_i32 m0, s79, 0x2000
	s_add_u32 s80, s52, 0x80000
	v_lshl_add_u64 v[212:213], s[52:53], 0, v[130:131]
	s_addc_u32 s81, s53, 0
	s_add_i32 s79, s70, s58
	global_load_lds_dwordx4 v[212:213], off
	v_lshl_add_u64 v[214:215], s[80:81], 0, v[128:129]
	s_mov_b32 m0, s79
	v_lshl_add_u64 v[216:217], s[54:55], 0, v[130:131]
	global_load_lds_dwordx4 v[214:215], off
	v_lshl_add_u64 v[214:215], s[80:81], 0, v[130:131]
	s_add_i32 m0, s79, 0x2000
	s_nop 0
	global_load_lds_dwordx4 v[214:215], off
	v_lshl_add_u64 v[214:215], s[54:55], 0, v[128:129]
	s_mov_b32 m0, s59
	s_nop 0
	global_load_lds_dwordx4 v[214:215], off
	s_mov_b32 m0, s60
	s_nop 0
	global_load_lds_dwordx4 v[216:217], off
	s_waitcnt vmcnt(8)
	s_waitcnt lgkmcnt(0)
	s_barrier
; #define PG8_STAGE(bufoff, gbase, voff) do { _Pragma("unroll") for (int _i = 0; _i < 2; ++_i) \
;         __builtin_amdgcn_global_load_lds((const unsigned*)((const char*)(gbase) + (voff)[_i]), (LAS unsigned*)(lds + (bufoff) + ldsw + _i * 8192), 16, 0, 0); } while (0)
; #define PG8_LDA(dst, b, h) do { _Pragma("unroll") for (int m = 0; m < 4; ++m) _Pragma("unroll") for (int k = 0; k < 2; ++k) dst[m][k] = *(const LAS bf16x8*)(lds + PG8_SA(b, h) + aoff + m * 2048 + k * 1024); } while (0)
; #define PG8_LDB(dst, b, h) do { _Pragma("unroll") for (int n = 0; n < 2; ++n) _Pragma("unroll") for (int k = 0; k < 2; ++k) dst[n][k] = *(const LAS bf16x8*)(lds + PG8_SB(b, h) + boff + n * 2048 + k * 1024); } while (0)
; #define PG8_MMA(ai, bj, At, Bt) do { __builtin_amdgcn_s_setprio(1); _Pragma("unroll") for (int m = 0; m < 4; ++m) _Pragma("unroll") for (int n = 0; n < 2; ++n) _Pragma("unroll") for (int k = 0; k < 2; ++k) \
;         acc[ai][bj][m][n] = __builtin_amdgcn_mfma_f32_16x16x32_bf16(Bt[n][k], At[m][k], acc[ai][bj][m][n], 0, 0, 0); __builtin_amdgcn_s_setprio(0); } while (0)
; #define PG8_WAIT_V(n) asm volatile("s_waitcnt vmcnt(" #n ")" ::: "memory")
; #define PG8_WAIT_L(n) asm volatile("s_waitcnt lgkmcnt(" #n ")" ::: "memory")
; #define PG8_BAR __builtin_amdgcn_s_barrier()
; #define PG8_SCHED __builtin_amdgcn_sched_barrier(0)
; template <class Epi, class Sched, bool ALIGN_EPI = true, bool SP2 = true>
; DI void gemm_phase(LAS unsigned char* lds, const Gemm g, const Sched& S, const Epi& E) {
;     ...
;             PG8_WAIT_V(8); PG8_WAIT_L(0); PG8_BAR; PG8_MMA(1, 0, At, B0); PG8_MMA(1, 1, At, B1); PG8_BAR; PG8_SCHED;
;             PG8_LDB(B0, 1, 0); PG8_LDB(B1, 1, 1); PG8_SCHED; PG8_LDA(At, 1, 0); PG8_STAGE(PG8_SA(0, 1), a2 + hstepA, voffA);
;             PG8_WAIT_V(8); PG8_WAIT_L(0); PG8_BAR; PG8_MMA(0, 0, At, B0); PG8_MMA(0, 1, At, B1); PG8_BAR; PG8_SCHED;
	s_setprio 1
	s_waitcnt lgkmcnt(0)
	v_mfma_f32_16x16x32_bf16 v[60:63], v[140:143], v[180:183], v[60:63]
	v_mfma_f32_16x16x32_bf16 v[56:59], v[148:151], v[180:183], v[56:59]
	v_mfma_f32_16x16x32_bf16 v[44:47], v[140:143], v[188:191], v[44:47]
	v_mfma_f32_16x16x32_bf16 v[40:43], v[148:151], v[188:191], v[40:43]
	v_mfma_f32_16x16x32_bf16 v[28:31], v[140:143], v[196:199], v[28:31]
	v_mfma_f32_16x16x32_bf16 v[24:27], v[148:151], v[196:199], v[24:27]
	v_mfma_f32_16x16x32_bf16 v[12:15], v[140:143], v[204:207], v[12:15]
	v_mfma_f32_16x16x32_bf16 v[8:11], v[148:151], v[204:207], v[8:11]
	v_mfma_f32_16x16x32_bf16 v[60:63], v[144:147], v[184:187], v[60:63]
	v_mfma_f32_16x16x32_bf16 v[56:59], v[160:163], v[184:187], v[56:59]
	v_mfma_f32_16x16x32_bf16 v[44:47], v[144:147], v[192:195], v[44:47]
	v_mfma_f32_16x16x32_bf16 v[40:43], v[160:163], v[192:195], v[40:43]
	v_mfma_f32_16x16x32_bf16 v[28:31], v[144:147], v[200:203], v[28:31]
	v_mfma_f32_16x16x32_bf16 v[24:27], v[160:163], v[200:203], v[24:27]
	v_mfma_f32_16x16x32_bf16 v[12:15], v[144:147], v[208:211], v[12:15]
	v_mfma_f32_16x16x32_bf16 v[8:11], v[160:163], v[208:211], v[8:11]
	s_setprio 0
	s_setprio 1
	v_mfma_f32_16x16x32_bf16 v[52:55], v[164:167], v[180:183], v[52:55]
	v_mfma_f32_16x16x32_bf16 v[48:51], v[172:175], v[180:183], v[48:51]
	v_mfma_f32_16x16x32_bf16 v[36:39], v[164:167], v[188:191], v[36:39]
	v_mfma_f32_16x16x32_bf16 v[32:35], v[172:175], v[188:191], v[32:35]
	v_mfma_f32_16x16x32_bf16 v[20:23], v[164:167], v[196:199], v[20:23]
	v_mfma_f32_16x16x32_bf16 v[16:19], v[172:175], v[196:199], v[16:19]
	v_mfma_f32_16x16x32_bf16 v[4:7], v[164:167], v[204:207], v[4:7]
	v_mfma_f32_16x16x32_bf16 v[0:3], v[172:175], v[204:207], v[0:3]
	v_mfma_f32_16x16x32_bf16 v[52:55], v[168:171], v[184:187], v[52:55]
	v_mfma_f32_16x16x32_bf16 v[48:51], v[176:179], v[184:187], v[48:51]
	v_mfma_f32_16x16x32_bf16 v[36:39], v[168:171], v[192:195], v[36:39]
	v_mfma_f32_16x16x32_bf16 v[32:35], v[176:179], v[192:195], v[32:35]
	v_mfma_f32_16x16x32_bf16 v[20:23], v[168:171], v[200:203], v[20:23]
	v_mfma_f32_16x16x32_bf16 v[16:19], v[176:179], v[200:203], v[16:19]
	v_mfma_f32_16x16x32_bf16 v[4:7], v[168:171], v[208:211], v[4:7]
	v_mfma_f32_16x16x32_bf16 v[0:3], v[176:179], v[208:211], v[0:3]
	s_setprio 0
	s_barrier
	s_add_i32 s79, 0, 0x18000
	s_add_i32 s80, 0, 0x1c000
	v_add_u32_e32 v160, s79, v155
	v_add_u32_e32 v176, s80, v155
	ds_read_b128 v[140:143], v160
	ds_read_b128 v[144:147], v160 offset:1024
	ds_read_b128 v[148:151], v160 offset:2048
	ds_read_b128 v[160:163], v160 offset:3072
	ds_read_b128 v[164:167], v176
	ds_read_b128 v[168:171], v176 offset:1024
	ds_read_b128 v[172:175], v176 offset:2048
	ds_read_b128 v[176:179], v176 offset:3072
	s_add_u32 s54, s54, 0x80000
	s_addc_u32 s55, s55, 0
	s_mov_b32 m0, s61
	v_lshl_add_u64 v[218:219], s[54:55], 0, v[128:129]
	ds_read_b128 v[180:183], v159 offset:32768
	ds_read_b128 v[184:187], v159 offset:33792
	ds_read_b128 v[188:191], v159 offset:34816
	ds_read_b128 v[192:195], v159 offset:35840
	ds_read_b128 v[196:199], v159 offset:36864
	ds_read_b128 v[200:203], v159 offset:37888
	ds_read_b128 v[204:207], v159 offset:38912
	ds_read_b128 v[208:211], v159 offset:39936
	global_load_lds_dwordx4 v[218:219], off
	v_lshl_add_u64 v[218:219], s[54:55], 0, v[130:131]
	s_mov_b32 m0, s62
	s_nop 0
	global_load_lds_dwordx4 v[218:219], off
	s_waitcnt vmcnt(8)
	s_waitcnt lgkmcnt(0)
	s_barrier
	s_setprio 1
	s_waitcnt lgkmcnt(0)
	v_mfma_f32_16x16x32_bf16 v[124:127], v[140:143], v[180:183], v[124:127]
	v_mfma_f32_16x16x32_bf16 v[120:123], v[148:151], v[180:183], v[120:123]
	v_mfma_f32_16x16x32_bf16 v[108:111], v[140:143], v[188:191], v[108:111]
	v_mfma_f32_16x16x32_bf16 v[104:107], v[148:151], v[188:191], v[104:107]
	v_mfma_f32_16x16x32_bf16 v[92:95], v[140:143], v[196:199], v[92:95]
	v_mfma_f32_16x16x32_bf16 v[88:91], v[148:151], v[196:199], v[88:91]
	v_mfma_f32_16x16x32_bf16 v[76:79], v[140:143], v[204:207], v[76:79]
	v_mfma_f32_16x16x32_bf16 v[72:75], v[148:151], v[204:207], v[72:75]
	v_mfma_f32_16x16x32_bf16 v[124:127], v[144:147], v[184:187], v[124:127]
	v_mfma_f32_16x16x32_bf16 v[120:123], v[160:163], v[184:187], v[120:123]
	v_mfma_f32_16x16x32_bf16 v[108:111], v[144:147], v[192:195], v[108:111]
	v_mfma_f32_16x16x32_bf16 v[104:107], v[160:163], v[192:195], v[104:107]
	v_mfma_f32_16x16x32_bf16 v[92:95], v[144:147], v[200:203], v[92:95]
	v_mfma_f32_16x16x32_bf16 v[88:91], v[160:163], v[200:203], v[88:91]
	v_mfma_f32_16x16x32_bf16 v[76:79], v[144:147], v[208:211], v[76:79]
	v_mfma_f32_16x16x32_bf16 v[72:75], v[160:163], v[208:211], v[72:75]
	s_setprio 0
	s_setprio 1
	v_mfma_f32_16x16x32_bf16 v[116:119], v[164:167], v[180:183], v[116:119]
	v_mfma_f32_16x16x32_bf16 v[112:115], v[172:175], v[180:183], v[112:115]
	v_mfma_f32_16x16x32_bf16 v[100:103], v[164:167], v[188:191], v[100:103]
	v_mfma_f32_16x16x32_bf16 v[96:99], v[172:175], v[188:191], v[96:99]
	v_mfma_f32_16x16x32_bf16 v[84:87], v[164:167], v[196:199], v[84:87]
	v_mfma_f32_16x16x32_bf16 v[80:83], v[172:175], v[196:199], v[80:83]
	v_mfma_f32_16x16x32_bf16 v[68:71], v[164:167], v[204:207], v[68:71]
	v_mfma_f32_16x16x32_bf16 v[64:67], v[172:175], v[204:207], v[64:67]
	v_mfma_f32_16x16x32_bf16 v[116:119], v[168:171], v[184:187], v[116:119]
	v_mfma_f32_16x16x32_bf16 v[112:115], v[176:179], v[184:187], v[112:115]
	v_mfma_f32_16x16x32_bf16 v[100:103], v[168:171], v[192:195], v[100:103]
	v_mfma_f32_16x16x32_bf16 v[96:99], v[176:179], v[192:195], v[96:99]
	v_mfma_f32_16x16x32_bf16 v[84:87], v[168:171], v[200:203], v[84:87]
	v_mfma_f32_16x16x32_bf16 v[80:83], v[176:179], v[200:203], v[80:83]
	v_mfma_f32_16x16x32_bf16 v[68:71], v[168:171], v[208:211], v[68:71]
	v_mfma_f32_16x16x32_bf16 v[64:67], v[176:179], v[208:211], v[64:67]
	s_setprio 0
	s_barrier
; #define PG8_STAGE(bufoff, gbase, voff) do { _Pragma("unroll") for (int _i = 0; _i < 2; ++_i) \
;         __builtin_amdgcn_global_load_lds((const unsigned*)((const char*)(gbase) + (voff)[_i]), (LAS unsigned*)(lds + (bufoff) + ldsw + _i * 8192), 16, 0, 0); } while (0)
; #define PG8_LDA(dst, b, h) do { _Pragma("unroll") for (int m = 0; m < 4; ++m) _Pragma("unroll") for (int k = 0; k < 2; ++k) dst[m][k] = *(const LAS bf16x8*)(lds + PG8_SA(b, h) + aoff + m * 2048 + k * 1024); } while (0)
; #define PG8_MMA(ai, bj, At, Bt) do { __builtin_amdgcn_s_setprio(1); _Pragma("unroll") for (int m = 0; m < 4; ++m) _Pragma("unroll") for (int n = 0; n < 2; ++n) _Pragma("unroll") for (int k = 0; k < 2; ++k) \
;         acc[ai][bj][m][n] = __builtin_amdgcn_mfma_f32_16x16x32_bf16(Bt[n][k], At[m][k], acc[ai][bj][m][n], 0, 0, 0); __builtin_amdgcn_s_setprio(0); } while (0)
; #define PG8_WAIT_V(n) asm volatile("s_waitcnt vmcnt(" #n ")" ::: "memory")
; #define PG8_WAIT_L(n) asm volatile("s_waitcnt lgkmcnt(" #n ")" ::: "memory")
; #define PG8_BAR __builtin_amdgcn_s_barrier()
; #define PG8_SCHED __builtin_amdgcn_sched_barrier(0)
; template <class Epi, class Sched, bool ALIGN_EPI = true, bool SP2 = true>
; DI void gemm_phase(LAS unsigned char* lds, const Gemm g, const Sched& S, const Epi& E) {
;     ...
;         for (int t = 0; t < nt; t += 2) {
;             const bool last = (t == nt - 2);
;     ...
;             PG8_LDA(At, 1, 1); PG8_STAGE(PG8_SB(1, 0), b3, voffB); PG8_STAGE(PG8_SB(1, 1), b3 + hstepB, voffB); PG8_STAGE(PG8_SA(1, 0), a3, voffA);
;             PG8_WAIT_V(8); PG8_WAIT_L(0); PG8_BAR; PG8_MMA(1, 0, At, B0); PG8_MMA(1, 1, At, B1); PG8_BAR; PG8_SCHED;
	s_add_i32 s54, s79, s58
	v_lshl_add_u64 v[152:153], v[152:153], 0, s[14:15]
	s_mov_b32 m0, s54
	ds_read_b128 v[180:183], v159 offset:49152
	ds_read_b128 v[184:187], v159 offset:50176
	ds_read_b128 v[188:191], v159 offset:51200
	ds_read_b128 v[192:195], v159 offset:52224
	ds_read_b128 v[196:199], v159 offset:53248
	ds_read_b128 v[200:203], v159 offset:54272
	ds_read_b128 v[204:207], v159 offset:55296
	ds_read_b128 v[208:211], v159 offset:56320
	global_load_lds_dwordx4 v[152:153], off
	s_add_i32 m0, s54, 0x2000
	s_add_u32 s52, s52, 0x80080
	v_lshl_add_u64 v[152:153], v[212:213], 0, s[14:15]
	s_addc_u32 s53, s53, 0
	s_add_i32 s54, s80, s58
	global_load_lds_dwordx4 v[152:153], off
	v_lshl_add_u64 v[152:153], s[52:53], 0, v[128:129]
	s_mov_b32 m0, s54
	s_nop 0
	global_load_lds_dwordx4 v[152:153], off
	v_lshl_add_u64 v[152:153], s[52:53], 0, v[130:131]
	s_add_i32 m0, s54, 0x2000
	s_nop 0
	global_load_lds_dwordx4 v[152:153], off
	v_lshl_add_u64 v[152:153], v[214:215], 0, s[14:15]
	s_mov_b32 m0, s65
	s_nop 0
	global_load_lds_dwordx4 v[152:153], off
	v_lshl_add_u64 v[152:153], v[216:217], 0, s[14:15]
	s_mov_b32 m0, s66
	s_nop 0
	global_load_lds_dwordx4 v[152:153], off
	s_waitcnt vmcnt(8)
	s_waitcnt lgkmcnt(0)
	s_barrier
	s_setprio 1
	s_waitcnt lgkmcnt(0)
	v_mfma_f32_16x16x32_bf16 v[60:63], v[140:143], v[180:183], v[60:63]
	v_mfma_f32_16x16x32_bf16 v[56:59], v[148:151], v[180:183], v[56:59]
	v_mfma_f32_16x16x32_bf16 v[44:47], v[140:143], v[188:191], v[44:47]
	v_mfma_f32_16x16x32_bf16 v[40:43], v[148:151], v[188:191], v[40:43]
	v_mfma_f32_16x16x32_bf16 v[28:31], v[140:143], v[196:199], v[28:31]
	v_mfma_f32_16x16x32_bf16 v[24:27], v[148:151], v[196:199], v[24:27]
	v_mfma_f32_16x16x32_bf16 v[12:15], v[140:143], v[204:207], v[12:15]
	v_mfma_f32_16x16x32_bf16 v[8:11], v[148:151], v[204:207], v[8:11]
	v_mfma_f32_16x16x32_bf16 v[60:63], v[144:147], v[184:187], v[60:63]
	v_mfma_f32_16x16x32_bf16 v[56:59], v[160:163], v[184:187], v[56:59]
	v_mfma_f32_16x16x32_bf16 v[44:47], v[144:147], v[192:195], v[44:47]
	v_mfma_f32_16x16x32_bf16 v[40:43], v[160:163], v[192:195], v[40:43]
	v_mfma_f32_16x16x32_bf16 v[28:31], v[144:147], v[200:203], v[28:31]
	v_mfma_f32_16x16x32_bf16 v[24:27], v[160:163], v[200:203], v[24:27]
	v_mfma_f32_16x16x32_bf16 v[12:15], v[144:147], v[208:211], v[12:15]
	v_mfma_f32_16x16x32_bf16 v[8:11], v[160:163], v[208:211], v[8:11]
	s_setprio 0
	s_setprio 1
	v_mfma_f32_16x16x32_bf16 v[52:55], v[164:167], v[180:183], v[52:55]
	v_mfma_f32_16x16x32_bf16 v[48:51], v[172:175], v[180:183], v[48:51]
	v_mfma_f32_16x16x32_bf16 v[36:39], v[164:167], v[188:191], v[36:39]
	v_mfma_f32_16x16x32_bf16 v[32:35], v[172:175], v[188:191], v[32:35]
	v_mfma_f32_16x16x32_bf16 v[20:23], v[164:167], v[196:199], v[20:23]
	v_mfma_f32_16x16x32_bf16 v[16:19], v[172:175], v[196:199], v[16:19]
	v_mfma_f32_16x16x32_bf16 v[4:7], v[164:167], v[204:207], v[4:7]
	v_mfma_f32_16x16x32_bf16 v[0:3], v[172:175], v[204:207], v[0:3]
	v_mfma_f32_16x16x32_bf16 v[52:55], v[168:171], v[184:187], v[52:55]
	v_mfma_f32_16x16x32_bf16 v[48:51], v[176:179], v[184:187], v[48:51]
	v_mfma_f32_16x16x32_bf16 v[36:39], v[168:171], v[192:195], v[36:39]
	v_mfma_f32_16x16x32_bf16 v[32:35], v[176:179], v[192:195], v[32:35]
	v_mfma_f32_16x16x32_bf16 v[20:23], v[168:171], v[200:203], v[20:23]
	v_mfma_f32_16x16x32_bf16 v[16:19], v[176:179], v[200:203], v[16:19]
	v_mfma_f32_16x16x32_bf16 v[4:7], v[168:171], v[208:211], v[4:7]
	v_mfma_f32_16x16x32_bf16 v[0:3], v[176:179], v[208:211], v[0:3]
	s_setprio 0
	s_add_i32 s78, s78, 2
	s_add_u32 s48, s48, 0x100
	s_addc_u32 s49, s49, 0
	s_add_u32 s76, s76, 0x100
	s_addc_u32 s77, s77, 0
	s_cmp_gt_u32 s78, 29
	s_barrier
	s_cbranch_scc0 .LBB0_2108
	s_and_b64 vcc, exec, s[16:17]
	s_cbranch_vccz .LBB0_2111
	s_barrier

; #define PG8_STAGE(bufoff, gbase, voff) do { _Pragma("unroll") for (int _i = 0; _i < 2; ++_i) \
;         __builtin_amdgcn_global_load_lds((const unsigned*)((const char*)(gbase) + (voff)[_i]), (LAS unsigned*)(lds + (bufoff) + ldsw + _i * 8192), 16, 0, 0); } while (0)
; #define PG8_LDA(dst, b, h) do { _Pragma("unroll") for (int m = 0; m < 4; ++m) _Pragma("unroll") for (int k = 0; k < 2; ++k) dst[m][k] = *(const LAS bf16x8*)(lds + PG8_SA(b, h) + aoff + m * 2048 + k * 1024); } while (0)
; #define PG8_LDB(dst, b, h) do { _Pragma("unroll") for (int n = 0; n < 2; ++n) _Pragma("unroll") for (int k = 0; k < 2; ++k) dst[n][k] = *(const LAS bf16x8*)(lds + PG8_SB(b, h) + boff + n * 2048 + k * 1024); } while (0)
; #define PG8_MMA(ai, bj, At, Bt) do { __builtin_amdgcn_s_setprio(1); _Pragma("unroll") for (int m = 0; m < 4; ++m) _Pragma("unroll") for (int n = 0; n < 2; ++n) _Pragma("unroll") for (int k = 0; k < 2; ++k) \
;         acc[ai][bj][m][n] = __builtin_amdgcn_mfma_f32_16x16x32_bf16(Bt[n][k], At[m][k], acc[ai][bj][m][n], 0, 0, 0); __builtin_amdgcn_s_setprio(0); } while (0)
; #define PG8_WAIT_V(n) asm volatile("s_waitcnt vmcnt(" #n ")" ::: "memory")
; #define PG8_WAIT_L(n) asm volatile("s_waitcnt lgkmcnt(" #n ")" ::: "memory")
; #define PG8_BAR __builtin_amdgcn_s_barrier()
; #define PG8_SCHED __builtin_amdgcn_sched_barrier(0)
; template <class Epi, class Sched, bool ALIGN_EPI = true, bool SP2 = true>
; DI void gemm_phase(LAS unsigned char* lds, const Gemm g, const Sched& S, const Epi& E) {
;     ...
;             const bool last = (t == nt - 2);
;             const char* a1 = cA + (size_t)(t + 1) * kstep;
;             const char* a2 = last ? nA : cA + (size_t)(t + 2) * kstep; const char* b2 = last ? nB : cB + (size_t)(t + 2) * kstep;
;             const char* a3 = a2 + kstep; const char* b3 = b2 + kstep;
;             PG8_LDB(B0, 0, 0); PG8_LDB(B1, 0, 1); PG8_SCHED; PG8_LDA(At, 0, 0); PG8_STAGE(PG8_SA(1, 1), a1 + hstepA, voffA);
;             PG8_WAIT_V(8); PG8_WAIT_L(0); PG8_BAR; PG8_MMA(0, 0, At, B0); PG8_MMA(0, 1, At, B1); PG8_BAR; PG8_SCHED;
;             PG8_LDA(At, 0, 1); PG8_STAGE(PG8_SB(0, 0), b2, voffB); PG8_STAGE(PG8_SB(0, 1), b2 + hstepB, voffB); PG8_STAGE(PG8_SA(0, 0), a2, voffA);
.LBB0_2199:
	v_add_u32_e32 v168, s63, v178
	v_add_u32_e32 v193, s64, v178
	ds_read_b128 v[156:159], v168
	ds_read_b128 v[160:163], v168 offset:1024
	ds_read_b128 v[164:167], v168 offset:2048
	ds_read_b128 v[168:171], v168 offset:3072
	ds_read_b128 v[172:175], v193
	ds_read_b128 v[194:197], v193 offset:1024
	ds_read_b128 v[198:201], v193 offset:2048
	ds_read_b128 v[202:205], v193 offset:3072
	s_add_u32 s46, s6, 0xfff80080
	s_addc_u32 s47, s7, -1
	s_cmp_eq_u32 s68, 28
	s_cselect_b32 s49, s35, s47
	s_cselect_b32 s48, s43, s46
	s_cselect_b32 s47, s37, s67
	s_cselect_b32 s46, s45, s66
	v_lshl_add_u64 v[240:241], s[6:7], 0, v[148:149]
	s_add_i32 m0, s53, 0xc000
	ds_read_b128 v[206:209], v190
	ds_read_b128 v[210:213], v190 offset:1024
	ds_read_b128 v[214:217], v190 offset:2048
	ds_read_b128 v[218:221], v190 offset:3072
	ds_read_b128 v[222:225], v190 offset:4096
	ds_read_b128 v[228:231], v190 offset:5120
	ds_read_b128 v[232:235], v190 offset:6144
	ds_read_b128 v[236:239], v190 offset:7168
	global_load_lds_dwordx4 v[240:241], off
	v_lshl_add_u64 v[240:241], s[6:7], 0, v[150:151]
	s_add_i32 m0, s53, 0xe000
	s_nop 0
	global_load_lds_dwordx4 v[240:241], off
	s_waitcnt vmcnt(8)
	s_waitcnt lgkmcnt(0)
	s_barrier
	s_setprio 1
	s_waitcnt lgkmcnt(0)
	v_mfma_f32_16x16x32_bf16 v[124:127], v[156:159], v[206:209], v[124:127]
	v_mfma_f32_16x16x32_bf16 v[120:123], v[164:167], v[206:209], v[120:123]
	v_mfma_f32_16x16x32_bf16 v[108:111], v[156:159], v[214:217], v[108:111]
	v_mfma_f32_16x16x32_bf16 v[104:107], v[164:167], v[214:217], v[104:107]
	v_mfma_f32_16x16x32_bf16 v[92:95], v[156:159], v[222:225], v[92:95]
	v_mfma_f32_16x16x32_bf16 v[88:91], v[164:167], v[222:225], v[88:91]
	v_mfma_f32_16x16x32_bf16 v[76:79], v[156:159], v[232:235], v[76:79]
	v_mfma_f32_16x16x32_bf16 v[72:75], v[164:167], v[232:235], v[72:75]
	v_mfma_f32_16x16x32_bf16 v[124:127], v[160:163], v[210:213], v[124:127]
	v_mfma_f32_16x16x32_bf16 v[120:123], v[168:171], v[210:213], v[120:123]
	v_mfma_f32_16x16x32_bf16 v[108:111], v[160:163], v[218:221], v[108:111]
	v_mfma_f32_16x16x32_bf16 v[104:107], v[168:171], v[218:221], v[104:107]
	v_mfma_f32_16x16x32_bf16 v[92:95], v[160:163], v[228:231], v[92:95]
	v_mfma_f32_16x16x32_bf16 v[88:91], v[168:171], v[228:231], v[88:91]
	v_mfma_f32_16x16x32_bf16 v[76:79], v[160:163], v[236:239], v[76:79]
	v_mfma_f32_16x16x32_bf16 v[72:75], v[168:171], v[236:239], v[72:75]
	s_setprio 0
	s_setprio 1
	v_mfma_f32_16x16x32_bf16 v[116:119], v[172:175], v[206:209], v[116:119]
	v_mfma_f32_16x16x32_bf16 v[112:115], v[198:201], v[206:209], v[112:115]
	v_mfma_f32_16x16x32_bf16 v[100:103], v[172:175], v[214:217], v[100:103]
	v_mfma_f32_16x16x32_bf16 v[96:99], v[198:201], v[214:217], v[96:99]
	v_mfma_f32_16x16x32_bf16 v[84:87], v[172:175], v[222:225], v[84:87]
	v_mfma_f32_16x16x32_bf16 v[80:83], v[198:201], v[222:225], v[80:83]
	v_mfma_f32_16x16x32_bf16 v[68:71], v[172:175], v[232:235], v[68:71]
	v_mfma_f32_16x16x32_bf16 v[64:67], v[198:201], v[232:235], v[64:67]
	v_mfma_f32_16x16x32_bf16 v[116:119], v[194:197], v[210:213], v[116:119]
	v_mfma_f32_16x16x32_bf16 v[112:115], v[202:205], v[210:213], v[112:115]
	v_mfma_f32_16x16x32_bf16 v[100:103], v[194:197], v[218:221], v[100:103]
	v_mfma_f32_16x16x32_bf16 v[96:99], v[202:205], v[218:221], v[96:99]
	v_mfma_f32_16x16x32_bf16 v[84:87], v[194:197], v[228:231], v[84:87]
	v_mfma_f32_16x16x32_bf16 v[80:83], v[202:205], v[228:231], v[80:83]
	v_mfma_f32_16x16x32_bf16 v[68:71], v[194:197], v[236:239], v[68:71]
	v_mfma_f32_16x16x32_bf16 v[64:67], v[202:205], v[236:239], v[64:67]
	s_setprio 0
	s_barrier
	s_add_i32 s69, s63, s52
	v_lshl_add_u64 v[240:241], s[46:47], 0, v[128:129]
	s_mov_b32 m0, s69
	ds_read_b128 v[206:209], v190 offset:16384
	ds_read_b128 v[210:213], v190 offset:17408
	ds_read_b128 v[214:217], v190 offset:18432
	ds_read_b128 v[218:221], v190 offset:19456
	ds_read_b128 v[222:225], v190 offset:20480
	ds_read_b128 v[228:231], v190 offset:21504
	ds_read_b128 v[232:235], v190 offset:22528
	ds_read_b128 v[236:239], v190 offset:23552
	global_load_lds_dwordx4 v[240:241], off
	s_add_i32 m0, s69, 0x2000
	s_add_u32 s70, s46, 0x80000
	v_lshl_add_u64 v[242:243], s[46:47], 0, v[130:131]
	s_addc_u32 s71, s47, 0
	s_add_i32 s69, s64, s52
	global_load_lds_dwordx4 v[242:243], off
	v_lshl_add_u64 v[244:245], s[70:71], 0, v[128:129]
	s_mov_b32 m0, s69
	v_lshl_add_u64 v[246:247], s[48:49], 0, v[130:131]
	global_load_lds_dwordx4 v[244:245], off
	v_lshl_add_u64 v[244:245], s[70:71], 0, v[130:131]
	s_add_i32 m0, s69, 0x2000
	s_nop 0
	global_load_lds_dwordx4 v[244:245], off
	v_lshl_add_u64 v[244:245], s[48:49], 0, v[128:129]
	s_mov_b32 m0, s53
	s_nop 0
	global_load_lds_dwordx4 v[244:245], off
	s_mov_b32 m0, s54
	s_nop 0
	global_load_lds_dwordx4 v[246:247], off
	s_waitcnt vmcnt(8)
	s_waitcnt lgkmcnt(0)
	s_barrier
; #define PG8_STAGE(bufoff, gbase, voff) do { _Pragma("unroll") for (int _i = 0; _i < 2; ++_i) \
;         __builtin_amdgcn_global_load_lds((const unsigned*)((const char*)(gbase) + (voff)[_i]), (LAS unsigned*)(lds + (bufoff) + ldsw + _i * 8192), 16, 0, 0); } while (0)
; #define PG8_LDA(dst, b, h) do { _Pragma("unroll") for (int m = 0; m < 4; ++m) _Pragma("unroll") for (int k = 0; k < 2; ++k) dst[m][k] = *(const LAS bf16x8*)(lds + PG8_SA(b, h) + aoff + m * 2048 + k * 1024); } while (0)
; #define PG8_LDB(dst, b, h) do { _Pragma("unroll") for (int n = 0; n < 2; ++n) _Pragma("unroll") for (int k = 0; k < 2; ++k) dst[n][k] = *(const LAS bf16x8*)(lds + PG8_SB(b, h) + boff + n * 2048 + k * 1024); } while (0)
; #define PG8_MMA(ai, bj, At, Bt) do { __builtin_amdgcn_s_setprio(1); _Pragma("unroll") for (int m = 0; m < 4; ++m) _Pragma("unroll") for (int n = 0; n < 2; ++n) _Pragma("unroll") for (int k = 0; k < 2; ++k) \
;         acc[ai][bj][m][n] = __builtin_amdgcn_mfma_f32_16x16x32_bf16(Bt[n][k], At[m][k], acc[ai][bj][m][n], 0, 0, 0); __builtin_amdgcn_s_setprio(0); } while (0)
; #define PG8_WAIT_V(n) asm volatile("s_waitcnt vmcnt(" #n ")" ::: "memory")
; #define PG8_WAIT_L(n) asm volatile("s_waitcnt lgkmcnt(" #n ")" ::: "memory")
; #define PG8_BAR __builtin_amdgcn_s_barrier()
; #define PG8_SCHED __builtin_amdgcn_sched_barrier(0)
; template <class Epi, class Sched, bool ALIGN_EPI = true, bool SP2 = true>
; DI void gemm_phase(LAS unsigned char* lds, const Gemm g, const Sched& S, const Epi& E) {
;     ...
;             PG8_WAIT_V(8); PG8_WAIT_L(0); PG8_BAR; PG8_MMA(1, 0, At, B0); PG8_MMA(1, 1, At, B1); PG8_BAR; PG8_SCHED;
;             PG8_LDB(B0, 1, 0); PG8_LDB(B1, 1, 1); PG8_SCHED; PG8_LDA(At, 1, 0); PG8_STAGE(PG8_SA(0, 1), a2 + hstepA, voffA);
;             PG8_WAIT_V(8); PG8_WAIT_L(0); PG8_BAR; PG8_MMA(0, 0, At, B0); PG8_MMA(0, 1, At, B1); PG8_BAR; PG8_SCHED;
	s_setprio 1
	s_waitcnt lgkmcnt(0)
	v_mfma_f32_16x16x32_bf16 v[60:63], v[156:159], v[206:209], v[60:63]
	v_mfma_f32_16x16x32_bf16 v[56:59], v[164:167], v[206:209], v[56:59]
	v_mfma_f32_16x16x32_bf16 v[44:47], v[156:159], v[214:217], v[44:47]
	v_mfma_f32_16x16x32_bf16 v[40:43], v[164:167], v[214:217], v[40:43]
	v_mfma_f32_16x16x32_bf16 v[28:31], v[156:159], v[222:225], v[28:31]
	v_mfma_f32_16x16x32_bf16 v[24:27], v[164:167], v[222:225], v[24:27]
	v_mfma_f32_16x16x32_bf16 v[12:15], v[156:159], v[232:235], v[12:15]
	v_mfma_f32_16x16x32_bf16 v[8:11], v[164:167], v[232:235], v[8:11]
	v_mfma_f32_16x16x32_bf16 v[60:63], v[160:163], v[210:213], v[60:63]
	v_mfma_f32_16x16x32_bf16 v[56:59], v[168:171], v[210:213], v[56:59]
	v_mfma_f32_16x16x32_bf16 v[44:47], v[160:163], v[218:221], v[44:47]
	v_mfma_f32_16x16x32_bf16 v[40:43], v[168:171], v[218:221], v[40:43]
	v_mfma_f32_16x16x32_bf16 v[28:31], v[160:163], v[228:231], v[28:31]
	v_mfma_f32_16x16x32_bf16 v[24:27], v[168:171], v[228:231], v[24:27]
	v_mfma_f32_16x16x32_bf16 v[12:15], v[160:163], v[236:239], v[12:15]
	v_mfma_f32_16x16x32_bf16 v[8:11], v[168:171], v[236:239], v[8:11]
	s_setprio 0
	s_setprio 1
	v_mfma_f32_16x16x32_bf16 v[52:55], v[172:175], v[206:209], v[52:55]
	v_mfma_f32_16x16x32_bf16 v[48:51], v[198:201], v[206:209], v[48:51]
	v_mfma_f32_16x16x32_bf16 v[36:39], v[172:175], v[214:217], v[36:39]
	v_mfma_f32_16x16x32_bf16 v[32:35], v[198:201], v[214:217], v[32:35]
	v_mfma_f32_16x16x32_bf16 v[20:23], v[172:175], v[222:225], v[20:23]
	v_mfma_f32_16x16x32_bf16 v[16:19], v[198:201], v[222:225], v[16:19]
	v_mfma_f32_16x16x32_bf16 v[4:7], v[172:175], v[232:235], v[4:7]
	v_mfma_f32_16x16x32_bf16 v[0:3], v[198:201], v[232:235], v[0:3]
	v_mfma_f32_16x16x32_bf16 v[52:55], v[194:197], v[210:213], v[52:55]
	v_mfma_f32_16x16x32_bf16 v[48:51], v[202:205], v[210:213], v[48:51]
	v_mfma_f32_16x16x32_bf16 v[36:39], v[194:197], v[218:221], v[36:39]
	v_mfma_f32_16x16x32_bf16 v[32:35], v[202:205], v[218:221], v[32:35]
	v_mfma_f32_16x16x32_bf16 v[20:23], v[194:197], v[228:231], v[20:23]
	v_mfma_f32_16x16x32_bf16 v[16:19], v[202:205], v[228:231], v[16:19]
	v_mfma_f32_16x16x32_bf16 v[4:7], v[194:197], v[236:239], v[4:7]
	v_mfma_f32_16x16x32_bf16 v[0:3], v[202:205], v[236:239], v[0:3]
	s_setprio 0
	s_barrier
	s_add_i32 s69, 0, 0x18000
	s_add_i32 s70, 0, 0x1c000
	v_add_u32_e32 v168, s69, v178
	v_add_u32_e32 v193, s70, v178
	ds_read_b128 v[156:159], v168
	ds_read_b128 v[160:163], v168 offset:1024
	ds_read_b128 v[164:167], v168 offset:2048
	ds_read_b128 v[168:171], v168 offset:3072
	ds_read_b128 v[172:175], v193
	ds_read_b128 v[194:197], v193 offset:1024
	ds_read_b128 v[198:201], v193 offset:2048
	ds_read_b128 v[202:205], v193 offset:3072
	s_add_u32 s48, s48, 0x80000
	s_addc_u32 s49, s49, 0
	s_mov_b32 m0, s55
	v_lshl_add_u64 v[248:249], s[48:49], 0, v[128:129]
	ds_read_b128 v[206:209], v190 offset:32768
	ds_read_b128 v[210:213], v190 offset:33792
	ds_read_b128 v[214:217], v190 offset:34816
	ds_read_b128 v[218:221], v190 offset:35840
	ds_read_b128 v[222:225], v190 offset:36864
	ds_read_b128 v[228:231], v190 offset:37888
	ds_read_b128 v[232:235], v190 offset:38912
	ds_read_b128 v[236:239], v190 offset:39936
	global_load_lds_dwordx4 v[248:249], off
	v_lshl_add_u64 v[248:249], s[48:49], 0, v[130:131]
	s_mov_b32 m0, s56
	s_nop 0
	global_load_lds_dwordx4 v[248:249], off
	s_waitcnt vmcnt(8)
	s_waitcnt lgkmcnt(0)
	s_barrier
	s_setprio 1
	s_waitcnt lgkmcnt(0)
	v_mfma_f32_16x16x32_bf16 v[124:127], v[156:159], v[206:209], v[124:127]
	v_mfma_f32_16x16x32_bf16 v[120:123], v[164:167], v[206:209], v[120:123]
	v_mfma_f32_16x16x32_bf16 v[108:111], v[156:159], v[214:217], v[108:111]
	v_mfma_f32_16x16x32_bf16 v[104:107], v[164:167], v[214:217], v[104:107]
	v_mfma_f32_16x16x32_bf16 v[92:95], v[156:159], v[222:225], v[92:95]
	v_mfma_f32_16x16x32_bf16 v[88:91], v[164:167], v[222:225], v[88:91]
	v_mfma_f32_16x16x32_bf16 v[76:79], v[156:159], v[232:235], v[76:79]
	v_mfma_f32_16x16x32_bf16 v[72:75], v[164:167], v[232:235], v[72:75]
	v_mfma_f32_16x16x32_bf16 v[124:127], v[160:163], v[210:213], v[124:127]
	v_mfma_f32_16x16x32_bf16 v[120:123], v[168:171], v[210:213], v[120:123]
	v_mfma_f32_16x16x32_bf16 v[108:111], v[160:163], v[218:221], v[108:111]
	v_mfma_f32_16x16x32_bf16 v[104:107], v[168:171], v[218:221], v[104:107]
	v_mfma_f32_16x16x32_bf16 v[92:95], v[160:163], v[228:231], v[92:95]
	v_mfma_f32_16x16x32_bf16 v[88:91], v[168:171], v[228:231], v[88:91]
	v_mfma_f32_16x16x32_bf16 v[76:79], v[160:163], v[236:239], v[76:79]
	v_mfma_f32_16x16x32_bf16 v[72:75], v[168:171], v[236:239], v[72:75]
	s_setprio 0
	s_setprio 1
	v_mfma_f32_16x16x32_bf16 v[116:119], v[172:175], v[206:209], v[116:119]
	v_mfma_f32_16x16x32_bf16 v[112:115], v[198:201], v[206:209], v[112:115]
	v_mfma_f32_16x16x32_bf16 v[100:103], v[172:175], v[214:217], v[100:103]
	v_mfma_f32_16x16x32_bf16 v[96:99], v[198:201], v[214:217], v[96:99]
	v_mfma_f32_16x16x32_bf16 v[84:87], v[172:175], v[222:225], v[84:87]
	v_mfma_f32_16x16x32_bf16 v[80:83], v[198:201], v[222:225], v[80:83]
	v_mfma_f32_16x16x32_bf16 v[68:71], v[172:175], v[232:235], v[68:71]
	v_mfma_f32_16x16x32_bf16 v[64:67], v[198:201], v[232:235], v[64:67]
	v_mfma_f32_16x16x32_bf16 v[116:119], v[194:197], v[210:213], v[116:119]
	v_mfma_f32_16x16x32_bf16 v[112:115], v[202:205], v[210:213], v[112:115]
	v_mfma_f32_16x16x32_bf16 v[100:103], v[194:197], v[218:221], v[100:103]
	v_mfma_f32_16x16x32_bf16 v[96:99], v[202:205], v[218:221], v[96:99]
	v_mfma_f32_16x16x32_bf16 v[84:87], v[194:197], v[228:231], v[84:87]
	v_mfma_f32_16x16x32_bf16 v[80:83], v[202:205], v[228:231], v[80:83]
	v_mfma_f32_16x16x32_bf16 v[68:71], v[194:197], v[236:239], v[68:71]
	v_mfma_f32_16x16x32_bf16 v[64:67], v[202:205], v[236:239], v[64:67]
	s_setprio 0
	s_barrier
; #define PG8_STAGE(bufoff, gbase, voff) do { _Pragma("unroll") for (int _i = 0; _i < 2; ++_i) \
;         __builtin_amdgcn_global_load_lds((const unsigned*)((const char*)(gbase) + (voff)[_i]), (LAS unsigned*)(lds + (bufoff) + ldsw + _i * 8192), 16, 0, 0); } while (0)
; #define PG8_LDA(dst, b, h) do { _Pragma("unroll") for (int m = 0; m < 4; ++m) _Pragma("unroll") for (int k = 0; k < 2; ++k) dst[m][k] = *(const LAS bf16x8*)(lds + PG8_SA(b, h) + aoff + m * 2048 + k * 1024); } while (0)
; #define PG8_MMA(ai, bj, At, Bt) do { __builtin_amdgcn_s_setprio(1); _Pragma("unroll") for (int m = 0; m < 4; ++m) _Pragma("unroll") for (int n = 0; n < 2; ++n) _Pragma("unroll") for (int k = 0; k < 2; ++k) \
;         acc[ai][bj][m][n] = __builtin_amdgcn_mfma_f32_16x16x32_bf16(Bt[n][k], At[m][k], acc[ai][bj][m][n], 0, 0, 0); __builtin_amdgcn_s_setprio(0); } while (0)
; #define PG8_WAIT_V(n) asm volatile("s_waitcnt vmcnt(" #n ")" ::: "memory")
; #define PG8_WAIT_L(n) asm volatile("s_waitcnt lgkmcnt(" #n ")" ::: "memory")
; #define PG8_BAR __builtin_amdgcn_s_barrier()
; #define PG8_SCHED __builtin_amdgcn_sched_barrier(0)
; template <class Epi, class Sched, bool ALIGN_EPI = true, bool SP2 = true>
; DI void gemm_phase(LAS unsigned char* lds, const Gemm g, const Sched& S, const Epi& E) {
;     ...
;         for (int t = 0; t < nt; t += 2) {
;             const bool last = (t == nt - 2);
;     ...
;             PG8_LDA(At, 1, 1); PG8_STAGE(PG8_SB(1, 0), b3, voffB); PG8_STAGE(PG8_SB(1, 1), b3 + hstepB, voffB); PG8_STAGE(PG8_SA(1, 0), a3, voffA);
;             PG8_WAIT_V(8); PG8_WAIT_L(0); PG8_BAR; PG8_MMA(1, 0, At, B0); PG8_MMA(1, 1, At, B1); PG8_BAR; PG8_SCHED;
	s_add_i32 s48, s69, s52
	v_lshl_add_u64 v[240:241], v[240:241], 0, s[22:23]
	s_mov_b32 m0, s48
	ds_read_b128 v[206:209], v190 offset:49152
	ds_read_b128 v[210:213], v190 offset:50176
	ds_read_b128 v[214:217], v190 offset:51200
	ds_read_b128 v[218:221], v190 offset:52224
	ds_read_b128 v[222:225], v190 offset:53248
	ds_read_b128 v[228:231], v190 offset:54272
	ds_read_b128 v[232:235], v190 offset:55296
	ds_read_b128 v[236:239], v190 offset:56320
	global_load_lds_dwordx4 v[240:241], off
	s_add_i32 m0, s48, 0x2000
	s_add_u32 s46, s46, 0x80080
	v_lshl_add_u64 v[240:241], v[242:243], 0, s[22:23]
	s_addc_u32 s47, s47, 0
	s_add_i32 s48, s70, s52
	global_load_lds_dwordx4 v[240:241], off
	v_lshl_add_u64 v[240:241], s[46:47], 0, v[128:129]
	s_mov_b32 m0, s48
	s_nop 0
	global_load_lds_dwordx4 v[240:241], off
	v_lshl_add_u64 v[240:241], s[46:47], 0, v[130:131]
	s_add_i32 m0, s48, 0x2000
	s_nop 0
	global_load_lds_dwordx4 v[240:241], off
	v_lshl_add_u64 v[240:241], v[244:245], 0, s[22:23]
	s_mov_b32 m0, s58
	s_nop 0
	global_load_lds_dwordx4 v[240:241], off
	v_lshl_add_u64 v[240:241], v[246:247], 0, s[22:23]
	s_mov_b32 m0, s59
	s_nop 0
	global_load_lds_dwordx4 v[240:241], off
	s_waitcnt vmcnt(8)
	s_waitcnt lgkmcnt(0)
	s_barrier
	s_setprio 1
	s_waitcnt lgkmcnt(0)
	v_mfma_f32_16x16x32_bf16 v[60:63], v[156:159], v[206:209], v[60:63]
	v_mfma_f32_16x16x32_bf16 v[56:59], v[164:167], v[206:209], v[56:59]
	v_mfma_f32_16x16x32_bf16 v[44:47], v[156:159], v[214:217], v[44:47]
	v_mfma_f32_16x16x32_bf16 v[40:43], v[164:167], v[214:217], v[40:43]
	v_mfma_f32_16x16x32_bf16 v[28:31], v[156:159], v[222:225], v[28:31]
	v_mfma_f32_16x16x32_bf16 v[24:27], v[164:167], v[222:225], v[24:27]
	v_mfma_f32_16x16x32_bf16 v[12:15], v[156:159], v[232:235], v[12:15]
	v_mfma_f32_16x16x32_bf16 v[8:11], v[164:167], v[232:235], v[8:11]
	v_mfma_f32_16x16x32_bf16 v[60:63], v[160:163], v[210:213], v[60:63]
	v_mfma_f32_16x16x32_bf16 v[56:59], v[168:171], v[210:213], v[56:59]
	v_mfma_f32_16x16x32_bf16 v[44:47], v[160:163], v[218:221], v[44:47]
	v_mfma_f32_16x16x32_bf16 v[40:43], v[168:171], v[218:221], v[40:43]
	v_mfma_f32_16x16x32_bf16 v[28:31], v[160:163], v[228:231], v[28:31]
	v_mfma_f32_16x16x32_bf16 v[24:27], v[168:171], v[228:231], v[24:27]
	v_mfma_f32_16x16x32_bf16 v[12:15], v[160:163], v[236:239], v[12:15]
	v_mfma_f32_16x16x32_bf16 v[8:11], v[168:171], v[236:239], v[8:11]
	s_setprio 0
	s_setprio 1
	v_mfma_f32_16x16x32_bf16 v[52:55], v[172:175], v[206:209], v[52:55]
	v_mfma_f32_16x16x32_bf16 v[48:51], v[198:201], v[206:209], v[48:51]
	v_mfma_f32_16x16x32_bf16 v[36:39], v[172:175], v[214:217], v[36:39]
	v_mfma_f32_16x16x32_bf16 v[32:35], v[198:201], v[214:217], v[32:35]
	v_mfma_f32_16x16x32_bf16 v[20:23], v[172:175], v[222:225], v[20:23]
	v_mfma_f32_16x16x32_bf16 v[16:19], v[198:201], v[222:225], v[16:19]
	v_mfma_f32_16x16x32_bf16 v[4:7], v[172:175], v[232:235], v[4:7]
	v_mfma_f32_16x16x32_bf16 v[0:3], v[198:201], v[232:235], v[0:3]
	v_mfma_f32_16x16x32_bf16 v[52:55], v[194:197], v[210:213], v[52:55]
	v_mfma_f32_16x16x32_bf16 v[48:51], v[202:205], v[210:213], v[48:51]
	v_mfma_f32_16x16x32_bf16 v[36:39], v[194:197], v[218:221], v[36:39]
	v_mfma_f32_16x16x32_bf16 v[32:35], v[202:205], v[218:221], v[32:35]
	v_mfma_f32_16x16x32_bf16 v[20:23], v[194:197], v[228:231], v[20:23]
	v_mfma_f32_16x16x32_bf16 v[16:19], v[202:205], v[228:231], v[16:19]
	v_mfma_f32_16x16x32_bf16 v[4:7], v[194:197], v[236:239], v[4:7]
	v_mfma_f32_16x16x32_bf16 v[0:3], v[202:205], v[236:239], v[0:3]
	s_setprio 0
	s_add_i32 s68, s68, 2
	s_add_u32 s6, s6, 0x100
	s_addc_u32 s7, s7, 0
	s_add_u32 s66, s66, 0x100
	s_addc_u32 s67, s67, 0
	s_cmp_gt_u32 s68, 29
	s_barrier
	s_cbranch_scc0 .LBB0_2199
	s_and_b64 vcc, exec, s[28:29]
	s_cbranch_vccz .LBB0_2202
	s_barrier
